# v44 + sc1 (write-through) on the GEMM epilogue stores so the grid barrier's L2 write-back has less dirty data
# baseline (speedup 1.0000x reference)
; __device__ __forceinline__ unsigned cvt_pk_bf16(float lo, float hi) { unsigned r; asm volatile("v_cvt_pk_bf16_f32 %0, %1, %2" : "=v"(r) : "v"(lo), "v"(hi)); return r; }
;     __device__ __forceinline__ void operator()(const f32x4 (&acc)[2][2][4][2], const Unit& u, int wr, int wc, int fr, int fq) const {
;         const int row0 = u.pm * BM + wr * 64 + fr, col0 = u.pn * BM + wc * 32 + 8 * fq;
; #pragma unroll
;         for (int ai = 0; ai < 2; ++ai)
; #pragma unroll
;             for (int m = 0; m < 4; ++m) { bf16_t* rowp = O + (size_t)(row0 + ai * HALF + m * 16) * ldc + col0;
; #pragma unroll
;                 for (int bj = 0; bj < 2; ++bj) { const f32x4 v0 = acc[ai][bj][m][0], v1 = acc[ai][bj][m][1];
;                     u32x4 w; w.x = cvt_pk_bf16(v0[0], v0[1]); w.y = cvt_pk_bf16(v0[2], v0[3]); w.z = cvt_pk_bf16(v1[0], v1[1]); w.w = cvt_pk_bf16(v1[2], v1[3]);
;                     *(u32x4*)(rowp + bj * HALF) = w; } }
.LBB0_234:
	v_lshl_or_b32 v148, s28, 8, v157
	v_lshl_add_u32 v161, s62, 8, v155
	v_ashrrev_i32_e32 v149, 31, v148
	v_mov_b64_e32 v[146:147], s[38:39]
	v_mad_i64_i32 v[162:163], s[0:1], v161, s24, v[146:147]
	v_lshlrev_b64 v[148:149], 1, v[148:149]
	v_lshl_add_u64 v[162:163], v[162:163], 0, v[148:149]
	v_cvt_pk_bf16_f32 v126, v126, v127
	v_cvt_pk_bf16_f32 v127, v128, v129
	v_cvt_pk_bf16_f32 v128, v122, v123
	v_cvt_pk_bf16_f32 v129, v124, v125
	global_store_dwordx4 v[162:163], v[126:129], off sc1
	v_cvt_pk_bf16_f32 v114, v114, v115
	v_cvt_pk_bf16_f32 v115, v116, v117
	v_cvt_pk_bf16_f32 v116, v106, v107
	v_or_b32_e32 v106, 16, v161
	v_mad_i64_i32 v[106:107], s[0:1], v106, s24, v[146:147]
	v_cvt_pk_bf16_f32 v117, v108, v109
	global_store_dwordx4 v[162:163], v[114:117], off offset:256 sc1
	s_and_b64 vcc, exec, s[2:3]
	s_nop 0
	v_lshl_add_u64 v[114:115], v[106:107], 0, v[148:149]
	v_cvt_pk_bf16_f32 v106, v118, v119
	v_cvt_pk_bf16_f32 v107, v120, v121
	v_cvt_pk_bf16_f32 v108, v110, v111
	v_cvt_pk_bf16_f32 v109, v112, v113
	global_store_dwordx4 v[114:115], v[106:109], off sc1
	v_cvt_pk_bf16_f32 v98, v98, v99
	v_cvt_pk_bf16_f32 v99, v100, v101
	v_cvt_pk_bf16_f32 v100, v90, v91
	v_or_b32_e32 v90, 32, v161
	v_mad_i64_i32 v[90:91], s[0:1], v90, s24, v[146:147]
	v_cvt_pk_bf16_f32 v101, v92, v93
	global_store_dwordx4 v[114:115], v[98:101], off offset:256 sc1
	s_nop 1
	v_lshl_add_u64 v[98:99], v[90:91], 0, v[148:149]
	v_cvt_pk_bf16_f32 v90, v102, v103
	v_cvt_pk_bf16_f32 v91, v104, v105
	v_cvt_pk_bf16_f32 v92, v94, v95
	v_cvt_pk_bf16_f32 v93, v96, v97
	global_store_dwordx4 v[98:99], v[90:93], off sc1
	v_cvt_pk_bf16_f32 v82, v82, v83
	v_cvt_pk_bf16_f32 v83, v84, v85
	v_cvt_pk_bf16_f32 v84, v74, v75
	v_or_b32_e32 v74, 48, v161
	v_mad_i64_i32 v[74:75], s[0:1], v74, s24, v[146:147]
	v_cvt_pk_bf16_f32 v85, v76, v77
	global_store_dwordx4 v[98:99], v[82:85], off offset:256 sc1
	s_nop 1
	v_lshl_add_u64 v[82:83], v[74:75], 0, v[148:149]
	v_cvt_pk_bf16_f32 v74, v86, v87
	v_cvt_pk_bf16_f32 v75, v88, v89
	v_cvt_pk_bf16_f32 v76, v78, v79
	v_cvt_pk_bf16_f32 v77, v80, v81
	global_store_dwordx4 v[82:83], v[74:77], off sc1
	v_cvt_pk_bf16_f32 v70, v70, v71
	v_cvt_pk_bf16_f32 v71, v72, v73
	v_cvt_pk_bf16_f32 v72, v66, v67
	v_add_u32_e32 v66, 0x80, v161
	v_mad_i64_i32 v[66:67], s[0:1], v66, s24, v[146:147]
	v_lshl_add_u64 v[66:67], v[66:67], 0, v[148:149]
	v_cvt_pk_bf16_f32 v73, v68, v69
	global_store_dwordx4 v[82:83], v[70:73], off offset:256 sc1
	v_cvt_pk_bf16_f32 v62, v62, v63
	v_cvt_pk_bf16_f32 v63, v64, v65
	v_cvt_pk_bf16_f32 v64, v58, v59
	v_cvt_pk_bf16_f32 v65, v60, v61
	global_store_dwordx4 v[66:67], v[62:65], off sc1
	v_cvt_pk_bf16_f32 v50, v50, v51
	v_cvt_pk_bf16_f32 v51, v52, v53
	v_cvt_pk_bf16_f32 v52, v42, v43
	v_add_u32_e32 v42, 0x90, v161
	v_mad_i64_i32 v[42:43], s[0:1], v42, s24, v[146:147]
	v_cvt_pk_bf16_f32 v53, v44, v45
	global_store_dwordx4 v[66:67], v[50:53], off offset:256 sc1
	s_nop 1
	v_lshl_add_u64 v[50:51], v[42:43], 0, v[148:149]
	v_cvt_pk_bf16_f32 v42, v54, v55
	v_cvt_pk_bf16_f32 v43, v56, v57
	v_cvt_pk_bf16_f32 v44, v46, v47
	v_cvt_pk_bf16_f32 v45, v48, v49
	global_store_dwordx4 v[50:51], v[42:45], off sc1
	v_cvt_pk_bf16_f32 v34, v34, v35
	v_cvt_pk_bf16_f32 v35, v36, v37
	v_cvt_pk_bf16_f32 v36, v26, v27
	v_add_u32_e32 v26, 0xa0, v161
	v_mad_i64_i32 v[26:27], s[0:1], v26, s24, v[146:147]
	v_cvt_pk_bf16_f32 v37, v28, v29
	global_store_dwordx4 v[50:51], v[34:37], off offset:256 sc1
	s_nop 1
	v_lshl_add_u64 v[34:35], v[26:27], 0, v[148:149]
	v_cvt_pk_bf16_f32 v26, v38, v39
	v_cvt_pk_bf16_f32 v27, v40, v41
	v_cvt_pk_bf16_f32 v28, v30, v31
	v_cvt_pk_bf16_f32 v29, v32, v33
	global_store_dwordx4 v[34:35], v[26:29], off sc1
	v_cvt_pk_bf16_f32 v18, v18, v19
	v_cvt_pk_bf16_f32 v19, v20, v21
	v_cvt_pk_bf16_f32 v20, v10, v11
	v_add_u32_e32 v10, 0xb0, v161
	v_mad_i64_i32 v[10:11], s[0:1], v10, s24, v[146:147]
	v_cvt_pk_bf16_f32 v21, v12, v13
	global_store_dwordx4 v[34:35], v[18:21], off offset:256 sc1
	s_mov_b64 s[0:1], -1
	s_nop 0
	v_lshl_add_u64 v[18:19], v[10:11], 0, v[148:149]
	v_cvt_pk_bf16_f32 v10, v22, v23
	v_cvt_pk_bf16_f32 v11, v24, v25
	v_cvt_pk_bf16_f32 v12, v14, v15
	v_cvt_pk_bf16_f32 v13, v16, v17
	global_store_dwordx4 v[18:19], v[10:13], off sc1
	v_cvt_pk_bf16_f32 v6, v6, v7
	v_cvt_pk_bf16_f32 v7, v8, v9
	v_cvt_pk_bf16_f32 v8, v2, v3
	v_cvt_pk_bf16_f32 v9, v4, v5
	global_store_dwordx4 v[18:19], v[6:9], off offset:256 sc1
	s_cbranch_vccnz .LBB0_221
	s_andn2_b64 vcc, exec, s[4:5]
	s_cbranch_vccnz .LBB0_220
	s_barrier
	s_branch .LBB0_220

; #define PG8_LAS __attribute__((address_space(3)))
; __device__ __forceinline__ unsigned cvt_pk_bf16(float lo, float hi) { unsigned r; asm volatile("v_cvt_pk_bf16_f32 %0, %1, %2" : "=v"(r) : "v"(lo), "v"(hi)); return r; }
;     __device__ __forceinline__ void operator()(const i32x4 (&acc)[2][2][4][2], const Unit& u, int wr, int wc, int fr, int fq, const PG8_LAS float* sb) const {
;         const int row0 = u.pm * BM + wr * 64 + fr, col0 = u.pn * BM + wc * 32 + 8 * fq;
;         f32x4 sv[2][2];
; #pragma unroll
;         for (int bj = 0; bj < 2; ++bj)
; #pragma unroll
;             for (int n = 0; n < 2; ++n) sv[bj][n] = *(const PG8_LAS f32x4*)(sb + wc * 32 + 8 * fq + bj * HALF + 4 * n);
; #pragma unroll
;         for (int ai = 0; ai < 2; ++ai)
; #pragma unroll
;             for (int m = 0; m < 4; ++m) { const int row = row0 + ai * HALF + m * 16; const float r = sb[256 + wr * 64 + fr + ai * HALF + m * 16]; bf16_t* rowp = O + (size_t)row * ldc + col0;
; #pragma unroll
;                 for (int bj = 0; bj < 2; ++bj) { const f32x4 v0 = __builtin_convertvector(acc[ai][bj][m][0], f32x4) * sv[bj][0] * r, v1 = __builtin_convertvector(acc[ai][bj][m][1], f32x4) * sv[bj][1] * r;
;                     u32x4 w; w.x = cvt_pk_bf16(v0[0], v0[1]); w.y = cvt_pk_bf16(v0[2], v0[3]); w.z = cvt_pk_bf16(v1[0], v1[1]); w.w = cvt_pk_bf16(v1[2], v1[3]);
;                     *(u32x4*)(rowp + bj * HALF) = w; } }
.LBB0_252:
	s_lshl_b32 s0, s35, 11
	s_and_b32 s0, s0, 0x800
	s_add_i32 s0, s0, 0
	s_add_i32 s0, s0, 0x20400
	s_lshl_b32 s1, s22, 2
	s_add_i32 s1, s0, s1
	v_lshl_add_u32 v122, v168, 2, s1
	s_lshl_b32 s1, s21, 2
	s_add_i32 s0, s0, s1
	v_lshl_add_u32 v185, v1, 2, s0
	ds_read_b128 v[142:145], v122
	ds_read_b128 v[134:137], v122 offset:16
	ds_read_b128 v[126:129], v122 offset:512
	ds_read_b128 v[122:125], v122 offset:528
	ds_read_b32 v188, v185 offset:1024
	v_cvt_f32_i32_e32 v193, v139
	v_cvt_f32_i32_e32 v141, v141
	v_cvt_f32_i32_e32 v140, v140
	v_cvt_f32_i32_e32 v192, v138
	v_cvt_f32_i32_e32 v131, v131
	v_cvt_f32_i32_e32 v133, v133
	v_cvt_f32_i32_e32 v132, v132
	v_cvt_f32_i32_e32 v130, v130
	v_lshl_or_b32 v186, s33, 8, v177
	v_cvt_f32_i32_e32 v119, v119
	v_cvt_f32_i32_e32 v118, v118
	v_cvt_f32_i32_e32 v115, v115
	v_cvt_f32_i32_e32 v117, v117
	v_cvt_f32_i32_e32 v116, v116
	v_cvt_f32_i32_e32 v114, v114
	v_lshl_add_u32 v184, s92, 8, v175
	v_ashrrev_i32_e32 v187, 31, v186
	v_mov_b64_e32 v[166:167], s[44:45]
	v_cvt_f32_i32_e32 v121, v121
	v_cvt_f32_i32_e32 v120, v120
	v_mad_i64_i32 v[190:191], s[0:1], v184, s25, v[166:167]
	v_lshlrev_b64 v[138:139], 1, v[186:187]
	v_lshl_add_u64 v[186:187], v[190:191], 0, v[138:139]
	s_waitcnt lgkmcnt(0)
	v_pk_mul_f32 v[140:141], v[144:145], v[140:141]
	v_pk_mul_f32 v[190:191], v[142:143], v[192:193]
	v_pk_mul_f32 v[132:133], v[136:137], v[132:133]
	v_pk_mul_f32 v[130:131], v[134:135], v[130:131]
	v_pk_mul_f32 v[140:141], v[140:141], v[188:189] op_sel_hi:[1,0]
	v_pk_mul_f32 v[190:191], v[190:191], v[188:189] op_sel_hi:[1,0]
	v_pk_mul_f32 v[192:193], v[132:133], v[188:189] op_sel_hi:[1,0]
	v_pk_mul_f32 v[132:133], v[130:131], v[188:189] op_sel_hi:[1,0]
	v_cvt_pk_bf16_f32 v130, v190, v191
	v_cvt_pk_bf16_f32 v131, v140, v141
	v_pk_mul_f32 v[118:119], v[126:127], v[118:119]
	v_pk_mul_f32 v[116:117], v[124:125], v[116:117]
	v_pk_mul_f32 v[114:115], v[122:123], v[114:115]
	v_cvt_pk_bf16_f32 v132, v132, v133
	v_cvt_pk_bf16_f32 v133, v192, v193
	global_store_dwordx4 v[186:187], v[130:133], off sc1
	v_pk_mul_f32 v[120:121], v[128:129], v[120:121]
	v_pk_mul_f32 v[118:119], v[118:119], v[188:189] op_sel_hi:[1,0]
	v_pk_mul_f32 v[130:131], v[116:117], v[188:189] op_sel_hi:[1,0]
	v_pk_mul_f32 v[116:117], v[114:115], v[188:189] op_sel_hi:[1,0]
	v_cvt_pk_bf16_f32 v114, v118, v119
	v_pk_mul_f32 v[120:121], v[120:121], v[188:189] op_sel_hi:[1,0]
	v_cvt_f32_i32_e32 v111, v111
	v_cvt_pk_bf16_f32 v115, v120, v121
	v_cvt_pk_bf16_f32 v116, v116, v117
	v_cvt_pk_bf16_f32 v117, v130, v131
	global_store_dwordx4 v[186:187], v[114:117], off offset:256 sc1
	ds_read_b32 v114, v185 offset:1088
	v_cvt_f32_i32_e32 v110, v110
	v_cvt_f32_i32_e32 v113, v113
	v_cvt_f32_i32_e32 v112, v112
	v_cvt_f32_i32_e32 v107, v107
	v_cvt_f32_i32_e32 v109, v109
	v_cvt_f32_i32_e32 v108, v108
	v_cvt_f32_i32_e32 v106, v106
	v_cvt_f32_i32_e32 v103, v103
	v_cvt_f32_i32_e32 v102, v102
	v_cvt_f32_i32_e32 v99, v99
	v_cvt_f32_i32_e32 v101, v101
	v_cvt_f32_i32_e32 v100, v100
	v_cvt_f32_i32_e32 v98, v98
	v_cvt_f32_i32_e32 v105, v105
	v_cvt_f32_i32_e32 v104, v104
	v_or_b32_e32 v115, 16, v184
	v_mad_i64_i32 v[116:117], s[0:1], v115, s25, v[166:167]
	v_pk_mul_f32 v[112:113], v[144:145], v[112:113]
	v_pk_mul_f32 v[110:111], v[142:143], v[110:111]
	v_pk_mul_f32 v[108:109], v[136:137], v[108:109]
	v_pk_mul_f32 v[106:107], v[134:135], v[106:107]
	v_lshl_add_u64 v[116:117], v[116:117], 0, v[138:139]
	s_waitcnt lgkmcnt(0)
	v_pk_mul_f32 v[112:113], v[112:113], v[114:115] op_sel_hi:[1,0]
	v_pk_mul_f32 v[110:111], v[110:111], v[114:115] op_sel_hi:[1,0]
	v_pk_mul_f32 v[118:119], v[108:109], v[114:115] op_sel_hi:[1,0]
	v_pk_mul_f32 v[108:109], v[106:107], v[114:115] op_sel_hi:[1,0]
	v_cvt_pk_bf16_f32 v106, v110, v111
	v_cvt_pk_bf16_f32 v107, v112, v113
	v_pk_mul_f32 v[102:103], v[126:127], v[102:103]
	v_pk_mul_f32 v[100:101], v[124:125], v[100:101]
	v_pk_mul_f32 v[98:99], v[122:123], v[98:99]
	v_cvt_pk_bf16_f32 v108, v108, v109
	v_cvt_pk_bf16_f32 v109, v118, v119
	global_store_dwordx4 v[116:117], v[106:109], off sc1
	v_pk_mul_f32 v[104:105], v[128:129], v[104:105]
	v_pk_mul_f32 v[102:103], v[102:103], v[114:115] op_sel_hi:[1,0]
	v_pk_mul_f32 v[106:107], v[100:101], v[114:115] op_sel_hi:[1,0]
	v_pk_mul_f32 v[100:101], v[98:99], v[114:115] op_sel_hi:[1,0]
	v_cvt_pk_bf16_f32 v98, v102, v103
	v_pk_mul_f32 v[104:105], v[104:105], v[114:115] op_sel_hi:[1,0]
	v_cvt_f32_i32_e32 v95, v95
	v_cvt_pk_bf16_f32 v99, v104, v105
	v_cvt_pk_bf16_f32 v100, v100, v101
	v_cvt_pk_bf16_f32 v101, v106, v107
	global_store_dwordx4 v[116:117], v[98:101], off offset:256 sc1
	ds_read_b32 v98, v185 offset:1152
	v_cvt_f32_i32_e32 v94, v94
	v_cvt_f32_i32_e32 v97, v97
	v_cvt_f32_i32_e32 v96, v96
	v_cvt_f32_i32_e32 v91, v91
	v_cvt_f32_i32_e32 v93, v93
	v_cvt_f32_i32_e32 v92, v92
	v_cvt_f32_i32_e32 v90, v90
	v_cvt_f32_i32_e32 v87, v87
	v_cvt_f32_i32_e32 v86, v86
	v_cvt_f32_i32_e32 v83, v83
	v_cvt_f32_i32_e32 v85, v85
	v_cvt_f32_i32_e32 v84, v84
	v_cvt_f32_i32_e32 v82, v82
	v_cvt_f32_i32_e32 v89, v89
	v_cvt_f32_i32_e32 v88, v88
	v_or_b32_e32 v99, 32, v184
	v_mad_i64_i32 v[100:101], s[0:1], v99, s25, v[166:167]
	v_pk_mul_f32 v[96:97], v[144:145], v[96:97]
	v_pk_mul_f32 v[94:95], v[142:143], v[94:95]
	v_pk_mul_f32 v[92:93], v[136:137], v[92:93]
	v_pk_mul_f32 v[90:91], v[134:135], v[90:91]
	v_lshl_add_u64 v[100:101], v[100:101], 0, v[138:139]
	s_waitcnt lgkmcnt(0)
; __device__ __forceinline__ unsigned cvt_pk_bf16(float lo, float hi) { unsigned r; asm volatile("v_cvt_pk_bf16_f32 %0, %1, %2" : "=v"(r) : "v"(lo), "v"(hi)); return r; }
;     __device__ __forceinline__ void operator()(const i32x4 (&acc)[2][2][4][2], const Unit& u, int wr, int wc, int fr, int fq, const PG8_LAS float* sb) const {
;     ...
;         for (int ai = 0; ai < 2; ++ai)
; #pragma unroll
;             for (int m = 0; m < 4; ++m) { const int row = row0 + ai * HALF + m * 16; const float r = sb[256 + wr * 64 + fr + ai * HALF + m * 16]; bf16_t* rowp = O + (size_t)row * ldc + col0;
; #pragma unroll
;                 for (int bj = 0; bj < 2; ++bj) { const f32x4 v0 = __builtin_convertvector(acc[ai][bj][m][0], f32x4) * sv[bj][0] * r, v1 = __builtin_convertvector(acc[ai][bj][m][1], f32x4) * sv[bj][1] * r;
;                     u32x4 w; w.x = cvt_pk_bf16(v0[0], v0[1]); w.y = cvt_pk_bf16(v0[2], v0[3]); w.z = cvt_pk_bf16(v1[0], v1[1]); w.w = cvt_pk_bf16(v1[2], v1[3]);
;                     *(u32x4*)(rowp + bj * HALF) = w; } }
	v_pk_mul_f32 v[96:97], v[96:97], v[98:99] op_sel_hi:[1,0]
	v_pk_mul_f32 v[94:95], v[94:95], v[98:99] op_sel_hi:[1,0]
	v_pk_mul_f32 v[102:103], v[92:93], v[98:99] op_sel_hi:[1,0]
	v_pk_mul_f32 v[92:93], v[90:91], v[98:99] op_sel_hi:[1,0]
	v_cvt_pk_bf16_f32 v90, v94, v95
	v_cvt_pk_bf16_f32 v91, v96, v97
	v_pk_mul_f32 v[86:87], v[126:127], v[86:87]
	v_pk_mul_f32 v[84:85], v[124:125], v[84:85]
	v_pk_mul_f32 v[82:83], v[122:123], v[82:83]
	v_cvt_pk_bf16_f32 v92, v92, v93
	v_cvt_pk_bf16_f32 v93, v102, v103
	global_store_dwordx4 v[100:101], v[90:93], off sc1
	v_pk_mul_f32 v[88:89], v[128:129], v[88:89]
	v_pk_mul_f32 v[86:87], v[86:87], v[98:99] op_sel_hi:[1,0]
	v_pk_mul_f32 v[90:91], v[84:85], v[98:99] op_sel_hi:[1,0]
	v_pk_mul_f32 v[84:85], v[82:83], v[98:99] op_sel_hi:[1,0]
	v_cvt_pk_bf16_f32 v82, v86, v87
	v_pk_mul_f32 v[88:89], v[88:89], v[98:99] op_sel_hi:[1,0]
	v_cvt_f32_i32_e32 v79, v79
	v_cvt_pk_bf16_f32 v83, v88, v89
	v_cvt_pk_bf16_f32 v84, v84, v85
	v_cvt_pk_bf16_f32 v85, v90, v91
	global_store_dwordx4 v[100:101], v[82:85], off offset:256 sc1
	ds_read_b32 v82, v185 offset:1216
	v_cvt_f32_i32_e32 v78, v78
	v_cvt_f32_i32_e32 v81, v81
	v_cvt_f32_i32_e32 v80, v80
	v_cvt_f32_i32_e32 v75, v75
	v_cvt_f32_i32_e32 v77, v77
	v_cvt_f32_i32_e32 v76, v76
	v_cvt_f32_i32_e32 v74, v74
	v_cvt_f32_i32_e32 v71, v71
	v_cvt_f32_i32_e32 v70, v70
	v_cvt_f32_i32_e32 v67, v67
	v_cvt_f32_i32_e32 v69, v69
	v_cvt_f32_i32_e32 v68, v68
	v_cvt_f32_i32_e32 v66, v66
	v_cvt_f32_i32_e32 v73, v73
	v_cvt_f32_i32_e32 v72, v72
	v_or_b32_e32 v83, 48, v184
	v_mad_i64_i32 v[84:85], s[0:1], v83, s25, v[166:167]
	v_pk_mul_f32 v[80:81], v[144:145], v[80:81]
	v_pk_mul_f32 v[78:79], v[142:143], v[78:79]
	v_pk_mul_f32 v[76:77], v[136:137], v[76:77]
	v_pk_mul_f32 v[74:75], v[134:135], v[74:75]
	v_lshl_add_u64 v[84:85], v[84:85], 0, v[138:139]
	s_waitcnt lgkmcnt(0)
	v_pk_mul_f32 v[80:81], v[80:81], v[82:83] op_sel_hi:[1,0]
	v_pk_mul_f32 v[78:79], v[78:79], v[82:83] op_sel_hi:[1,0]
	v_pk_mul_f32 v[86:87], v[76:77], v[82:83] op_sel_hi:[1,0]
	v_pk_mul_f32 v[76:77], v[74:75], v[82:83] op_sel_hi:[1,0]
	v_cvt_pk_bf16_f32 v74, v78, v79
	v_cvt_pk_bf16_f32 v75, v80, v81
	v_pk_mul_f32 v[70:71], v[126:127], v[70:71]
	v_pk_mul_f32 v[68:69], v[124:125], v[68:69]
	v_pk_mul_f32 v[66:67], v[122:123], v[66:67]
	v_cvt_pk_bf16_f32 v76, v76, v77
	v_cvt_pk_bf16_f32 v77, v86, v87
	global_store_dwordx4 v[84:85], v[74:77], off sc1
	v_pk_mul_f32 v[72:73], v[128:129], v[72:73]
	v_pk_mul_f32 v[70:71], v[70:71], v[82:83] op_sel_hi:[1,0]
	v_pk_mul_f32 v[74:75], v[68:69], v[82:83] op_sel_hi:[1,0]
	v_pk_mul_f32 v[68:69], v[66:67], v[82:83] op_sel_hi:[1,0]
	v_cvt_pk_bf16_f32 v66, v70, v71
	v_pk_mul_f32 v[72:73], v[72:73], v[82:83] op_sel_hi:[1,0]
	v_cvt_f32_i32_e32 v63, v63
	v_cvt_pk_bf16_f32 v67, v72, v73
	v_cvt_pk_bf16_f32 v68, v68, v69
	v_cvt_pk_bf16_f32 v69, v74, v75
	global_store_dwordx4 v[84:85], v[66:69], off offset:256 sc1
	ds_read_b32 v66, v185 offset:1536
	v_cvt_f32_i32_e32 v62, v62
	v_cvt_f32_i32_e32 v65, v65
	v_cvt_f32_i32_e32 v64, v64
	v_cvt_f32_i32_e32 v59, v59
	v_cvt_f32_i32_e32 v61, v61
	v_cvt_f32_i32_e32 v60, v60
	v_cvt_f32_i32_e32 v58, v58
	v_cvt_f32_i32_e32 v55, v55
	v_cvt_f32_i32_e32 v54, v54
	v_cvt_f32_i32_e32 v51, v51
	v_cvt_f32_i32_e32 v53, v53
	v_cvt_f32_i32_e32 v52, v52
	v_cvt_f32_i32_e32 v50, v50
	v_cvt_f32_i32_e32 v57, v57
	v_cvt_f32_i32_e32 v56, v56
	v_add_u32_e32 v67, 0x80, v184
	v_mad_i64_i32 v[68:69], s[0:1], v67, s25, v[166:167]
	v_pk_mul_f32 v[64:65], v[144:145], v[64:65]
	v_pk_mul_f32 v[62:63], v[142:143], v[62:63]
	v_pk_mul_f32 v[60:61], v[136:137], v[60:61]
	v_pk_mul_f32 v[58:59], v[134:135], v[58:59]
	v_lshl_add_u64 v[68:69], v[68:69], 0, v[138:139]
	s_waitcnt lgkmcnt(0)
	v_pk_mul_f32 v[64:65], v[64:65], v[66:67] op_sel_hi:[1,0]
	v_pk_mul_f32 v[62:63], v[62:63], v[66:67] op_sel_hi:[1,0]
	v_pk_mul_f32 v[70:71], v[60:61], v[66:67] op_sel_hi:[1,0]
	v_pk_mul_f32 v[60:61], v[58:59], v[66:67] op_sel_hi:[1,0]
	v_cvt_pk_bf16_f32 v58, v62, v63
	v_cvt_pk_bf16_f32 v59, v64, v65
	v_pk_mul_f32 v[54:55], v[126:127], v[54:55]
	v_pk_mul_f32 v[52:53], v[124:125], v[52:53]
	v_pk_mul_f32 v[50:51], v[122:123], v[50:51]
	v_cvt_pk_bf16_f32 v60, v60, v61
	v_cvt_pk_bf16_f32 v61, v70, v71
	global_store_dwordx4 v[68:69], v[58:61], off sc1
	v_pk_mul_f32 v[56:57], v[128:129], v[56:57]
	v_pk_mul_f32 v[54:55], v[54:55], v[66:67] op_sel_hi:[1,0]
	v_pk_mul_f32 v[58:59], v[52:53], v[66:67] op_sel_hi:[1,0]
	v_pk_mul_f32 v[52:53], v[50:51], v[66:67] op_sel_hi:[1,0]
	v_cvt_pk_bf16_f32 v50, v54, v55
	v_pk_mul_f32 v[56:57], v[56:57], v[66:67] op_sel_hi:[1,0]
	v_cvt_f32_i32_e32 v47, v47
	v_cvt_pk_bf16_f32 v51, v56, v57
	v_cvt_pk_bf16_f32 v52, v52, v53
	v_cvt_pk_bf16_f32 v53, v58, v59
	global_store_dwordx4 v[68:69], v[50:53], off offset:256 sc1
	ds_read_b32 v50, v185 offset:1600
	v_cvt_f32_i32_e32 v46, v46
	v_cvt_f32_i32_e32 v49, v49
	v_cvt_f32_i32_e32 v48, v48
	v_cvt_f32_i32_e32 v43, v43
	v_cvt_f32_i32_e32 v45, v45
	v_cvt_f32_i32_e32 v44, v44
	v_cvt_f32_i32_e32 v42, v42
	v_cvt_f32_i32_e32 v39, v39
	v_cvt_f32_i32_e32 v38, v38
	v_cvt_f32_i32_e32 v35, v35
	v_cvt_f32_i32_e32 v37, v37
	v_cvt_f32_i32_e32 v36, v36
	v_cvt_f32_i32_e32 v34, v34
	v_cvt_f32_i32_e32 v41, v41
	v_cvt_f32_i32_e32 v40, v40
	v_add_u32_e32 v51, 0x90, v184
	v_mad_i64_i32 v[52:53], s[0:1], v51, s25, v[166:167]
	v_pk_mul_f32 v[48:49], v[144:145], v[48:49]
	v_pk_mul_f32 v[46:47], v[142:143], v[46:47]
	v_pk_mul_f32 v[44:45], v[136:137], v[44:45]
	v_pk_mul_f32 v[42:43], v[134:135], v[42:43]
	v_lshl_add_u64 v[52:53], v[52:53], 0, v[138:139]
	s_waitcnt lgkmcnt(0)
; #define PG8_LAS __attribute__((address_space(3)))
; __device__ __forceinline__ unsigned cvt_pk_bf16(float lo, float hi) { unsigned r; asm volatile("v_cvt_pk_bf16_f32 %0, %1, %2" : "=v"(r) : "v"(lo), "v"(hi)); return r; }
;     __device__ __forceinline__ void operator()(const i32x4 (&acc)[2][2][4][2], const Unit& u, int wr, int wc, int fr, int fq, const PG8_LAS float* sb) const {
;     ...
;         for (int ai = 0; ai < 2; ++ai)
; #pragma unroll
;             for (int m = 0; m < 4; ++m) { const int row = row0 + ai * HALF + m * 16; const float r = sb[256 + wr * 64 + fr + ai * HALF + m * 16]; bf16_t* rowp = O + (size_t)row * ldc + col0;
; #pragma unroll
;                 for (int bj = 0; bj < 2; ++bj) { const f32x4 v0 = __builtin_convertvector(acc[ai][bj][m][0], f32x4) * sv[bj][0] * r, v1 = __builtin_convertvector(acc[ai][bj][m][1], f32x4) * sv[bj][1] * r;
;                     u32x4 w; w.x = cvt_pk_bf16(v0[0], v0[1]); w.y = cvt_pk_bf16(v0[2], v0[3]); w.z = cvt_pk_bf16(v1[0], v1[1]); w.w = cvt_pk_bf16(v1[2], v1[3]);
;                     *(u32x4*)(rowp + bj * HALF) = w; } }
; __device__ __forceinline__ void stage_scales(PG8_LAS unsigned char* sb, const float* cs_tile, const float* rs_tile, int tid, int wid) {
;     const float* src = (tid < 256) ? cs_tile + tid : rs_tile + (tid - 256);
;     __builtin_amdgcn_global_load_lds((const unsigned*)src, (PG8_LAS unsigned*)(sb + wid * 256), 4, 0, 0);
; }
	v_pk_mul_f32 v[48:49], v[48:49], v[50:51] op_sel_hi:[1,0]
	v_pk_mul_f32 v[46:47], v[46:47], v[50:51] op_sel_hi:[1,0]
	v_pk_mul_f32 v[54:55], v[44:45], v[50:51] op_sel_hi:[1,0]
	v_pk_mul_f32 v[44:45], v[42:43], v[50:51] op_sel_hi:[1,0]
	v_cvt_pk_bf16_f32 v42, v46, v47
	v_cvt_pk_bf16_f32 v43, v48, v49
	v_pk_mul_f32 v[38:39], v[126:127], v[38:39]
	v_pk_mul_f32 v[36:37], v[124:125], v[36:37]
	v_pk_mul_f32 v[34:35], v[122:123], v[34:35]
	v_cvt_pk_bf16_f32 v44, v44, v45
	v_cvt_pk_bf16_f32 v45, v54, v55
	global_store_dwordx4 v[52:53], v[42:45], off sc1
	v_pk_mul_f32 v[40:41], v[128:129], v[40:41]
	v_pk_mul_f32 v[38:39], v[38:39], v[50:51] op_sel_hi:[1,0]
	v_pk_mul_f32 v[42:43], v[36:37], v[50:51] op_sel_hi:[1,0]
	v_pk_mul_f32 v[36:37], v[34:35], v[50:51] op_sel_hi:[1,0]
	v_cvt_pk_bf16_f32 v34, v38, v39
	v_pk_mul_f32 v[40:41], v[40:41], v[50:51] op_sel_hi:[1,0]
	v_cvt_f32_i32_e32 v31, v31
	v_cvt_pk_bf16_f32 v35, v40, v41
	v_cvt_pk_bf16_f32 v36, v36, v37
	v_cvt_pk_bf16_f32 v37, v42, v43
	global_store_dwordx4 v[52:53], v[34:37], off offset:256 sc1
	ds_read_b32 v34, v185 offset:1664
	v_cvt_f32_i32_e32 v30, v30
	v_cvt_f32_i32_e32 v33, v33
	v_cvt_f32_i32_e32 v32, v32
	v_cvt_f32_i32_e32 v27, v27
	v_cvt_f32_i32_e32 v29, v29
	v_cvt_f32_i32_e32 v28, v28
	v_cvt_f32_i32_e32 v26, v26
	v_cvt_f32_i32_e32 v23, v23
	v_cvt_f32_i32_e32 v22, v22
	v_cvt_f32_i32_e32 v19, v19
	v_cvt_f32_i32_e32 v21, v21
	v_cvt_f32_i32_e32 v20, v20
	v_cvt_f32_i32_e32 v18, v18
	v_cvt_f32_i32_e32 v25, v25
	v_cvt_f32_i32_e32 v24, v24
	v_add_u32_e32 v35, 0xa0, v184
	v_mad_i64_i32 v[36:37], s[0:1], v35, s25, v[166:167]
	v_pk_mul_f32 v[32:33], v[144:145], v[32:33]
	v_pk_mul_f32 v[30:31], v[142:143], v[30:31]
	v_pk_mul_f32 v[28:29], v[136:137], v[28:29]
	v_pk_mul_f32 v[26:27], v[134:135], v[26:27]
	v_lshl_add_u64 v[36:37], v[36:37], 0, v[138:139]
	s_waitcnt lgkmcnt(0)
	v_pk_mul_f32 v[32:33], v[32:33], v[34:35] op_sel_hi:[1,0]
	v_pk_mul_f32 v[30:31], v[30:31], v[34:35] op_sel_hi:[1,0]
	v_pk_mul_f32 v[38:39], v[28:29], v[34:35] op_sel_hi:[1,0]
	v_pk_mul_f32 v[28:29], v[26:27], v[34:35] op_sel_hi:[1,0]
	v_cvt_pk_bf16_f32 v26, v30, v31
	v_cvt_pk_bf16_f32 v27, v32, v33
	v_pk_mul_f32 v[22:23], v[126:127], v[22:23]
	v_pk_mul_f32 v[20:21], v[124:125], v[20:21]
	v_pk_mul_f32 v[18:19], v[122:123], v[18:19]
	v_cvt_pk_bf16_f32 v28, v28, v29
	v_cvt_pk_bf16_f32 v29, v38, v39
	global_store_dwordx4 v[36:37], v[26:29], off sc1
	v_pk_mul_f32 v[24:25], v[128:129], v[24:25]
	v_pk_mul_f32 v[22:23], v[22:23], v[34:35] op_sel_hi:[1,0]
	v_pk_mul_f32 v[26:27], v[20:21], v[34:35] op_sel_hi:[1,0]
	v_pk_mul_f32 v[20:21], v[18:19], v[34:35] op_sel_hi:[1,0]
	v_cvt_pk_bf16_f32 v18, v22, v23
	v_pk_mul_f32 v[24:25], v[24:25], v[34:35] op_sel_hi:[1,0]
	v_cvt_f32_i32_e32 v15, v15
	v_cvt_pk_bf16_f32 v19, v24, v25
	v_cvt_pk_bf16_f32 v20, v20, v21
	v_cvt_pk_bf16_f32 v21, v26, v27
	global_store_dwordx4 v[36:37], v[18:21], off offset:256 sc1
	ds_read_b32 v18, v185 offset:1728
	v_cvt_f32_i32_e32 v14, v14
	v_cvt_f32_i32_e32 v17, v17
	v_cvt_f32_i32_e32 v16, v16
	v_cvt_f32_i32_e32 v11, v11
	v_cvt_f32_i32_e32 v13, v13
	v_cvt_f32_i32_e32 v12, v12
	v_cvt_f32_i32_e32 v10, v10
	v_cvt_f32_i32_e32 v3, v3
	v_cvt_f32_i32_e32 v5, v5
	v_cvt_f32_i32_e32 v4, v4
	v_cvt_f32_i32_e32 v2, v2
	v_cvt_f32_i32_e32 v7, v7
	v_cvt_f32_i32_e32 v9, v9
	v_cvt_f32_i32_e32 v8, v8
	v_cvt_f32_i32_e32 v6, v6
	v_add_u32_e32 v19, 0xb0, v184
	v_mad_i64_i32 v[20:21], s[0:1], v19, s25, v[166:167]
	v_pk_mul_f32 v[16:17], v[144:145], v[16:17]
	v_pk_mul_f32 v[14:15], v[142:143], v[14:15]
	v_pk_mul_f32 v[12:13], v[136:137], v[12:13]
	v_pk_mul_f32 v[10:11], v[134:135], v[10:11]
	v_lshl_add_u64 v[20:21], v[20:21], 0, v[138:139]
	s_waitcnt lgkmcnt(0)
	v_pk_mul_f32 v[16:17], v[16:17], v[18:19] op_sel_hi:[1,0]
	v_pk_mul_f32 v[14:15], v[14:15], v[18:19] op_sel_hi:[1,0]
	v_pk_mul_f32 v[22:23], v[12:13], v[18:19] op_sel_hi:[1,0]
	v_pk_mul_f32 v[12:13], v[10:11], v[18:19] op_sel_hi:[1,0]
	v_cvt_pk_bf16_f32 v10, v14, v15
	v_cvt_pk_bf16_f32 v11, v16, v17
	v_pk_mul_f32 v[4:5], v[124:125], v[4:5]
	v_pk_mul_f32 v[2:3], v[122:123], v[2:3]
	v_cvt_pk_bf16_f32 v12, v12, v13
	v_cvt_pk_bf16_f32 v13, v22, v23
	global_store_dwordx4 v[20:21], v[10:13], off sc1
	v_pk_mul_f32 v[8:9], v[128:129], v[8:9]
	v_pk_mul_f32 v[6:7], v[126:127], v[6:7]
	v_pk_mul_f32 v[10:11], v[4:5], v[18:19] op_sel_hi:[1,0]
	v_pk_mul_f32 v[4:5], v[2:3], v[18:19] op_sel_hi:[1,0]
	s_and_b64 vcc, exec, s[4:5]
	s_mov_b64 s[0:1], -1
	v_pk_mul_f32 v[8:9], v[8:9], v[18:19] op_sel_hi:[1,0]
	v_pk_mul_f32 v[6:7], v[6:7], v[18:19] op_sel_hi:[1,0]
	s_nop 0
	v_cvt_pk_bf16_f32 v2, v6, v7
	v_cvt_pk_bf16_f32 v3, v8, v9
	v_cvt_pk_bf16_f32 v4, v4, v5
	v_cvt_pk_bf16_f32 v5, v10, v11
	global_store_dwordx4 v[20:21], v[2:5], off offset:256 sc1
	s_cbranch_vccnz .LBB0_243
	s_ashr_i32 s63, s62, 31
	s_lshl_b32 s0, s29, 11
	s_lshl_b64 s[4:5], s[62:63], 10
	s_and_b32 s33, s0, 0x800
	s_lshl_b64 s[0:1], s[58:59], 10
	v_lshl_add_u64 v[4:5], v[156:157], 0, s[4:5]
	v_lshl_add_u64 v[2:3], v[154:155], 0, s[0:1]
	v_lshl_add_u64 v[4:5], v[4:5], 0, s[40:41]
	v_cndmask_b32_e64 v3, v5, v3, s[2:3]
	v_cndmask_b32_e64 v2, v4, v2, s[2:3]
	s_add_i32 m0, s12, s33
	s_andn2_b64 vcc, exec, s[42:43]
	global_load_lds_dword v[2:3], off
	s_cbranch_vccnz .LBB0_242
	s_barrier
	s_branch .LBB0_242

; #define PG8_LAS __attribute__((address_space(3)))
; __device__ __forceinline__ unsigned cvt_pk_bf16(float lo, float hi) { unsigned r; asm volatile("v_cvt_pk_bf16_f32 %0, %1, %2" : "=v"(r) : "v"(lo), "v"(hi)); return r; }
;     __device__ __forceinline__ void operator()(const i32x4 (&acc)[2][2][4][2], const Unit& u, int wr, int wc, int fr, int fq, const PG8_LAS float* sb) const {
;         const int row0 = u.pm * BM + wr * 64 + fr, col0 = u.pn * BM + wc * 32 + 8 * fq;
;         f32x4 sv[2][2];
; #pragma unroll
;         for (int bj = 0; bj < 2; ++bj)
; #pragma unroll
;             for (int n = 0; n < 2; ++n) sv[bj][n] = *(const PG8_LAS f32x4*)(sb + wc * 32 + 8 * fq + bj * HALF + 4 * n);
; #pragma unroll
;         for (int ai = 0; ai < 2; ++ai)
; #pragma unroll
;             for (int m = 0; m < 4; ++m) { const int row = row0 + ai * HALF + m * 16; const float r = sb[256 + wr * 64 + fr + ai * HALF + m * 16]; bf16_t* rowp = O + (size_t)row * ldc + col0;
; #pragma unroll
;                 for (int bj = 0; bj < 2; ++bj) { const f32x4 v0 = __builtin_convertvector(acc[ai][bj][m][0], f32x4) * sv[bj][0] * r, v1 = __builtin_convertvector(acc[ai][bj][m][1], f32x4) * sv[bj][1] * r;
;                     u32x4 w; w.x = cvt_pk_bf16(v0[0], v0[1]); w.y = cvt_pk_bf16(v0[2], v0[3]); w.z = cvt_pk_bf16(v1[0], v1[1]); w.w = cvt_pk_bf16(v1[2], v1[3]);
;                     *(u32x4*)(rowp + bj * HALF) = w; } }
.LBB0_278:
	s_lshl_b32 s0, s36, 11
	s_and_b32 s0, s0, 0x800
	s_add_i32 s0, s0, 0
	s_add_i32 s0, s0, 0x20400
	s_lshl_b32 s1, s23, 2
	s_add_i32 s1, s0, s1
	v_lshl_add_u32 v122, v168, 2, s1
	s_lshl_b32 s1, s22, 2
	s_add_i32 s0, s0, s1
	v_lshl_add_u32 v176, v1, 2, s0
	ds_read_b128 v[142:145], v122
	ds_read_b128 v[134:137], v122 offset:16
	ds_read_b128 v[126:129], v122 offset:512
	ds_read_b128 v[122:125], v122 offset:528
	ds_read_b32 v184, v176 offset:1024
	v_cvt_f32_i32_e32 v189, v139
	v_cvt_f32_i32_e32 v141, v141
	v_cvt_f32_i32_e32 v140, v140
	v_cvt_f32_i32_e32 v188, v138
	v_cvt_f32_i32_e32 v131, v131
	v_cvt_f32_i32_e32 v133, v133
	v_cvt_f32_i32_e32 v132, v132
	v_cvt_f32_i32_e32 v130, v130
	v_lshl_or_b32 v182, s35, 8, v174
	v_cvt_f32_i32_e32 v119, v119
	v_cvt_f32_i32_e32 v118, v118
	v_cvt_f32_i32_e32 v115, v115
	v_cvt_f32_i32_e32 v117, v117
	v_cvt_f32_i32_e32 v116, v116
	v_cvt_f32_i32_e32 v114, v114
	v_lshl_add_u32 v172, s62, 8, v175
	v_ashrrev_i32_e32 v183, 31, v182
	v_mov_b64_e32 v[166:167], s[78:79]
	v_cvt_f32_i32_e32 v121, v121
	v_cvt_f32_i32_e32 v120, v120
	v_mad_i64_i32 v[186:187], s[0:1], v172, s26, v[166:167]
	v_lshlrev_b64 v[138:139], 1, v[182:183]
	v_lshl_add_u64 v[182:183], v[186:187], 0, v[138:139]
	s_waitcnt lgkmcnt(0)
	v_pk_mul_f32 v[140:141], v[144:145], v[140:141]
	v_pk_mul_f32 v[186:187], v[142:143], v[188:189]
	v_pk_mul_f32 v[132:133], v[136:137], v[132:133]
	v_pk_mul_f32 v[130:131], v[134:135], v[130:131]
	v_pk_mul_f32 v[140:141], v[140:141], v[184:185] op_sel_hi:[1,0]
	v_pk_mul_f32 v[186:187], v[186:187], v[184:185] op_sel_hi:[1,0]
	v_pk_mul_f32 v[188:189], v[132:133], v[184:185] op_sel_hi:[1,0]
	v_pk_mul_f32 v[132:133], v[130:131], v[184:185] op_sel_hi:[1,0]
	v_cvt_pk_bf16_f32 v130, v186, v187
	v_cvt_pk_bf16_f32 v131, v140, v141
	v_pk_mul_f32 v[118:119], v[126:127], v[118:119]
	v_pk_mul_f32 v[116:117], v[124:125], v[116:117]
	v_pk_mul_f32 v[114:115], v[122:123], v[114:115]
	v_cvt_pk_bf16_f32 v132, v132, v133
	v_cvt_pk_bf16_f32 v133, v188, v189
	global_store_dwordx4 v[182:183], v[130:133], off sc1
	v_pk_mul_f32 v[120:121], v[128:129], v[120:121]
	v_pk_mul_f32 v[118:119], v[118:119], v[184:185] op_sel_hi:[1,0]
	v_pk_mul_f32 v[130:131], v[116:117], v[184:185] op_sel_hi:[1,0]
	v_pk_mul_f32 v[116:117], v[114:115], v[184:185] op_sel_hi:[1,0]
	v_cvt_pk_bf16_f32 v114, v118, v119
	v_pk_mul_f32 v[120:121], v[120:121], v[184:185] op_sel_hi:[1,0]
	v_cvt_f32_i32_e32 v111, v111
	v_cvt_pk_bf16_f32 v115, v120, v121
	v_cvt_pk_bf16_f32 v116, v116, v117
	v_cvt_pk_bf16_f32 v117, v130, v131
	global_store_dwordx4 v[182:183], v[114:117], off offset:256 sc1
	ds_read_b32 v114, v176 offset:1088
	v_cvt_f32_i32_e32 v110, v110
	v_cvt_f32_i32_e32 v113, v113
	v_cvt_f32_i32_e32 v112, v112
	v_cvt_f32_i32_e32 v107, v107
	v_cvt_f32_i32_e32 v109, v109
	v_cvt_f32_i32_e32 v108, v108
	v_cvt_f32_i32_e32 v106, v106
	v_cvt_f32_i32_e32 v103, v103
	v_cvt_f32_i32_e32 v102, v102
	v_cvt_f32_i32_e32 v99, v99
	v_cvt_f32_i32_e32 v101, v101
	v_cvt_f32_i32_e32 v100, v100
	v_cvt_f32_i32_e32 v98, v98
	v_cvt_f32_i32_e32 v105, v105
	v_cvt_f32_i32_e32 v104, v104
	v_or_b32_e32 v115, 16, v172
	v_mad_i64_i32 v[116:117], s[0:1], v115, s26, v[166:167]
	v_pk_mul_f32 v[112:113], v[144:145], v[112:113]
	v_pk_mul_f32 v[110:111], v[142:143], v[110:111]
	v_pk_mul_f32 v[108:109], v[136:137], v[108:109]
	v_pk_mul_f32 v[106:107], v[134:135], v[106:107]
	v_lshl_add_u64 v[116:117], v[116:117], 0, v[138:139]
	s_waitcnt lgkmcnt(0)
	v_pk_mul_f32 v[112:113], v[112:113], v[114:115] op_sel_hi:[1,0]
	v_pk_mul_f32 v[110:111], v[110:111], v[114:115] op_sel_hi:[1,0]
	v_pk_mul_f32 v[118:119], v[108:109], v[114:115] op_sel_hi:[1,0]
	v_pk_mul_f32 v[108:109], v[106:107], v[114:115] op_sel_hi:[1,0]
	v_cvt_pk_bf16_f32 v106, v110, v111
	v_cvt_pk_bf16_f32 v107, v112, v113
	v_pk_mul_f32 v[102:103], v[126:127], v[102:103]
	v_pk_mul_f32 v[100:101], v[124:125], v[100:101]
	v_pk_mul_f32 v[98:99], v[122:123], v[98:99]
	v_cvt_pk_bf16_f32 v108, v108, v109
	v_cvt_pk_bf16_f32 v109, v118, v119
	global_store_dwordx4 v[116:117], v[106:109], off sc1
	v_pk_mul_f32 v[104:105], v[128:129], v[104:105]
	v_pk_mul_f32 v[102:103], v[102:103], v[114:115] op_sel_hi:[1,0]
	v_pk_mul_f32 v[106:107], v[100:101], v[114:115] op_sel_hi:[1,0]
	v_pk_mul_f32 v[100:101], v[98:99], v[114:115] op_sel_hi:[1,0]
	v_cvt_pk_bf16_f32 v98, v102, v103
	v_pk_mul_f32 v[104:105], v[104:105], v[114:115] op_sel_hi:[1,0]
	v_cvt_f32_i32_e32 v95, v95
	v_cvt_pk_bf16_f32 v99, v104, v105
	v_cvt_pk_bf16_f32 v100, v100, v101
	v_cvt_pk_bf16_f32 v101, v106, v107
	global_store_dwordx4 v[116:117], v[98:101], off offset:256 sc1
	ds_read_b32 v98, v176 offset:1152
	v_cvt_f32_i32_e32 v94, v94
	v_cvt_f32_i32_e32 v97, v97
	v_cvt_f32_i32_e32 v96, v96
	v_cvt_f32_i32_e32 v91, v91
	v_cvt_f32_i32_e32 v93, v93
	v_cvt_f32_i32_e32 v92, v92
	v_cvt_f32_i32_e32 v90, v90
	v_cvt_f32_i32_e32 v87, v87
	v_cvt_f32_i32_e32 v86, v86
	v_cvt_f32_i32_e32 v83, v83
	v_cvt_f32_i32_e32 v85, v85
	v_cvt_f32_i32_e32 v84, v84
	v_cvt_f32_i32_e32 v82, v82
	v_cvt_f32_i32_e32 v89, v89
	v_cvt_f32_i32_e32 v88, v88
	v_or_b32_e32 v99, 32, v172
	v_mad_i64_i32 v[100:101], s[0:1], v99, s26, v[166:167]
	v_pk_mul_f32 v[96:97], v[144:145], v[96:97]
	v_pk_mul_f32 v[94:95], v[142:143], v[94:95]
	v_pk_mul_f32 v[92:93], v[136:137], v[92:93]
	v_pk_mul_f32 v[90:91], v[134:135], v[90:91]
	v_lshl_add_u64 v[100:101], v[100:101], 0, v[138:139]
	s_waitcnt lgkmcnt(0)
; __device__ __forceinline__ unsigned cvt_pk_bf16(float lo, float hi) { unsigned r; asm volatile("v_cvt_pk_bf16_f32 %0, %1, %2" : "=v"(r) : "v"(lo), "v"(hi)); return r; }
;     __device__ __forceinline__ void operator()(const i32x4 (&acc)[2][2][4][2], const Unit& u, int wr, int wc, int fr, int fq, const PG8_LAS float* sb) const {
;     ...
;         for (int ai = 0; ai < 2; ++ai)
; #pragma unroll
;             for (int m = 0; m < 4; ++m) { const int row = row0 + ai * HALF + m * 16; const float r = sb[256 + wr * 64 + fr + ai * HALF + m * 16]; bf16_t* rowp = O + (size_t)row * ldc + col0;
; #pragma unroll
;                 for (int bj = 0; bj < 2; ++bj) { const f32x4 v0 = __builtin_convertvector(acc[ai][bj][m][0], f32x4) * sv[bj][0] * r, v1 = __builtin_convertvector(acc[ai][bj][m][1], f32x4) * sv[bj][1] * r;
;                     u32x4 w; w.x = cvt_pk_bf16(v0[0], v0[1]); w.y = cvt_pk_bf16(v0[2], v0[3]); w.z = cvt_pk_bf16(v1[0], v1[1]); w.w = cvt_pk_bf16(v1[2], v1[3]);
;                     *(u32x4*)(rowp + bj * HALF) = w; } }
	v_pk_mul_f32 v[96:97], v[96:97], v[98:99] op_sel_hi:[1,0]
	v_pk_mul_f32 v[94:95], v[94:95], v[98:99] op_sel_hi:[1,0]
	v_pk_mul_f32 v[102:103], v[92:93], v[98:99] op_sel_hi:[1,0]
	v_pk_mul_f32 v[92:93], v[90:91], v[98:99] op_sel_hi:[1,0]
	v_cvt_pk_bf16_f32 v90, v94, v95
	v_cvt_pk_bf16_f32 v91, v96, v97
	v_pk_mul_f32 v[86:87], v[126:127], v[86:87]
	v_pk_mul_f32 v[84:85], v[124:125], v[84:85]
	v_pk_mul_f32 v[82:83], v[122:123], v[82:83]
	v_cvt_pk_bf16_f32 v92, v92, v93
	v_cvt_pk_bf16_f32 v93, v102, v103
	global_store_dwordx4 v[100:101], v[90:93], off sc1
	v_pk_mul_f32 v[88:89], v[128:129], v[88:89]
	v_pk_mul_f32 v[86:87], v[86:87], v[98:99] op_sel_hi:[1,0]
	v_pk_mul_f32 v[90:91], v[84:85], v[98:99] op_sel_hi:[1,0]
	v_pk_mul_f32 v[84:85], v[82:83], v[98:99] op_sel_hi:[1,0]
	v_cvt_pk_bf16_f32 v82, v86, v87
	v_pk_mul_f32 v[88:89], v[88:89], v[98:99] op_sel_hi:[1,0]
	v_cvt_f32_i32_e32 v79, v79
	v_cvt_pk_bf16_f32 v83, v88, v89
	v_cvt_pk_bf16_f32 v84, v84, v85
	v_cvt_pk_bf16_f32 v85, v90, v91
	global_store_dwordx4 v[100:101], v[82:85], off offset:256 sc1
	ds_read_b32 v82, v176 offset:1216
	v_cvt_f32_i32_e32 v78, v78
	v_cvt_f32_i32_e32 v81, v81
	v_cvt_f32_i32_e32 v80, v80
	v_cvt_f32_i32_e32 v75, v75
	v_cvt_f32_i32_e32 v77, v77
	v_cvt_f32_i32_e32 v76, v76
	v_cvt_f32_i32_e32 v74, v74
	v_cvt_f32_i32_e32 v71, v71
	v_cvt_f32_i32_e32 v70, v70
	v_cvt_f32_i32_e32 v67, v67
	v_cvt_f32_i32_e32 v69, v69
	v_cvt_f32_i32_e32 v68, v68
	v_cvt_f32_i32_e32 v66, v66
	v_cvt_f32_i32_e32 v73, v73
	v_cvt_f32_i32_e32 v72, v72
	v_or_b32_e32 v83, 48, v172
	v_mad_i64_i32 v[84:85], s[0:1], v83, s26, v[166:167]
	v_pk_mul_f32 v[80:81], v[144:145], v[80:81]
	v_pk_mul_f32 v[78:79], v[142:143], v[78:79]
	v_pk_mul_f32 v[76:77], v[136:137], v[76:77]
	v_pk_mul_f32 v[74:75], v[134:135], v[74:75]
	v_lshl_add_u64 v[84:85], v[84:85], 0, v[138:139]
	s_waitcnt lgkmcnt(0)
	v_pk_mul_f32 v[80:81], v[80:81], v[82:83] op_sel_hi:[1,0]
	v_pk_mul_f32 v[78:79], v[78:79], v[82:83] op_sel_hi:[1,0]
	v_pk_mul_f32 v[86:87], v[76:77], v[82:83] op_sel_hi:[1,0]
	v_pk_mul_f32 v[76:77], v[74:75], v[82:83] op_sel_hi:[1,0]
	v_cvt_pk_bf16_f32 v74, v78, v79
	v_cvt_pk_bf16_f32 v75, v80, v81
	v_pk_mul_f32 v[70:71], v[126:127], v[70:71]
	v_pk_mul_f32 v[68:69], v[124:125], v[68:69]
	v_pk_mul_f32 v[66:67], v[122:123], v[66:67]
	v_cvt_pk_bf16_f32 v76, v76, v77
	v_cvt_pk_bf16_f32 v77, v86, v87
	global_store_dwordx4 v[84:85], v[74:77], off sc1
	v_pk_mul_f32 v[72:73], v[128:129], v[72:73]
	v_pk_mul_f32 v[70:71], v[70:71], v[82:83] op_sel_hi:[1,0]
	v_pk_mul_f32 v[74:75], v[68:69], v[82:83] op_sel_hi:[1,0]
	v_pk_mul_f32 v[68:69], v[66:67], v[82:83] op_sel_hi:[1,0]
	v_cvt_pk_bf16_f32 v66, v70, v71
	v_pk_mul_f32 v[72:73], v[72:73], v[82:83] op_sel_hi:[1,0]
	v_cvt_f32_i32_e32 v63, v63
	v_cvt_pk_bf16_f32 v67, v72, v73
	v_cvt_pk_bf16_f32 v68, v68, v69
	v_cvt_pk_bf16_f32 v69, v74, v75
	global_store_dwordx4 v[84:85], v[66:69], off offset:256 sc1
	ds_read_b32 v66, v176 offset:1536
	v_cvt_f32_i32_e32 v62, v62
	v_cvt_f32_i32_e32 v65, v65
	v_cvt_f32_i32_e32 v64, v64
	v_cvt_f32_i32_e32 v59, v59
	v_cvt_f32_i32_e32 v61, v61
	v_cvt_f32_i32_e32 v60, v60
	v_cvt_f32_i32_e32 v58, v58
	v_cvt_f32_i32_e32 v55, v55
	v_cvt_f32_i32_e32 v54, v54
	v_cvt_f32_i32_e32 v51, v51
	v_cvt_f32_i32_e32 v53, v53
	v_cvt_f32_i32_e32 v52, v52
	v_cvt_f32_i32_e32 v50, v50
	v_cvt_f32_i32_e32 v57, v57
	v_cvt_f32_i32_e32 v56, v56
	v_add_u32_e32 v67, 0x80, v172
	v_mad_i64_i32 v[68:69], s[0:1], v67, s26, v[166:167]
	v_pk_mul_f32 v[64:65], v[144:145], v[64:65]
	v_pk_mul_f32 v[62:63], v[142:143], v[62:63]
	v_pk_mul_f32 v[60:61], v[136:137], v[60:61]
	v_pk_mul_f32 v[58:59], v[134:135], v[58:59]
	v_lshl_add_u64 v[68:69], v[68:69], 0, v[138:139]
	s_waitcnt lgkmcnt(0)
	v_pk_mul_f32 v[64:65], v[64:65], v[66:67] op_sel_hi:[1,0]
	v_pk_mul_f32 v[62:63], v[62:63], v[66:67] op_sel_hi:[1,0]
	v_pk_mul_f32 v[70:71], v[60:61], v[66:67] op_sel_hi:[1,0]
	v_pk_mul_f32 v[60:61], v[58:59], v[66:67] op_sel_hi:[1,0]
	v_cvt_pk_bf16_f32 v58, v62, v63
	v_cvt_pk_bf16_f32 v59, v64, v65
	v_pk_mul_f32 v[54:55], v[126:127], v[54:55]
	v_pk_mul_f32 v[52:53], v[124:125], v[52:53]
	v_pk_mul_f32 v[50:51], v[122:123], v[50:51]
	v_cvt_pk_bf16_f32 v60, v60, v61
	v_cvt_pk_bf16_f32 v61, v70, v71
	global_store_dwordx4 v[68:69], v[58:61], off sc1
	v_pk_mul_f32 v[56:57], v[128:129], v[56:57]
	v_pk_mul_f32 v[54:55], v[54:55], v[66:67] op_sel_hi:[1,0]
	v_pk_mul_f32 v[58:59], v[52:53], v[66:67] op_sel_hi:[1,0]
	v_pk_mul_f32 v[52:53], v[50:51], v[66:67] op_sel_hi:[1,0]
	v_cvt_pk_bf16_f32 v50, v54, v55
	v_pk_mul_f32 v[56:57], v[56:57], v[66:67] op_sel_hi:[1,0]
	v_cvt_f32_i32_e32 v47, v47
	v_cvt_pk_bf16_f32 v51, v56, v57
	v_cvt_pk_bf16_f32 v52, v52, v53
	v_cvt_pk_bf16_f32 v53, v58, v59
	global_store_dwordx4 v[68:69], v[50:53], off offset:256 sc1
	ds_read_b32 v50, v176 offset:1600
	v_cvt_f32_i32_e32 v46, v46
	v_cvt_f32_i32_e32 v49, v49
	v_cvt_f32_i32_e32 v48, v48
	v_cvt_f32_i32_e32 v43, v43
	v_cvt_f32_i32_e32 v45, v45
	v_cvt_f32_i32_e32 v44, v44
	v_cvt_f32_i32_e32 v42, v42
	v_cvt_f32_i32_e32 v39, v39
	v_cvt_f32_i32_e32 v38, v38
	v_cvt_f32_i32_e32 v35, v35
	v_cvt_f32_i32_e32 v37, v37
	v_cvt_f32_i32_e32 v36, v36
	v_cvt_f32_i32_e32 v34, v34
	v_cvt_f32_i32_e32 v41, v41
	v_cvt_f32_i32_e32 v40, v40
	v_add_u32_e32 v51, 0x90, v172
	v_mad_i64_i32 v[52:53], s[0:1], v51, s26, v[166:167]
	v_pk_mul_f32 v[48:49], v[144:145], v[48:49]
	v_pk_mul_f32 v[46:47], v[142:143], v[46:47]
	v_pk_mul_f32 v[44:45], v[136:137], v[44:45]
	v_pk_mul_f32 v[42:43], v[134:135], v[42:43]
	v_lshl_add_u64 v[52:53], v[52:53], 0, v[138:139]
	s_waitcnt lgkmcnt(0)
; #define PG8_LAS __attribute__((address_space(3)))
; __device__ __forceinline__ unsigned cvt_pk_bf16(float lo, float hi) { unsigned r; asm volatile("v_cvt_pk_bf16_f32 %0, %1, %2" : "=v"(r) : "v"(lo), "v"(hi)); return r; }
;     __device__ __forceinline__ void operator()(const i32x4 (&acc)[2][2][4][2], const Unit& u, int wr, int wc, int fr, int fq, const PG8_LAS float* sb) const {
;     ...
;         for (int ai = 0; ai < 2; ++ai)
; #pragma unroll
;             for (int m = 0; m < 4; ++m) { const int row = row0 + ai * HALF + m * 16; const float r = sb[256 + wr * 64 + fr + ai * HALF + m * 16]; bf16_t* rowp = O + (size_t)row * ldc + col0;
; #pragma unroll
;                 for (int bj = 0; bj < 2; ++bj) { const f32x4 v0 = __builtin_convertvector(acc[ai][bj][m][0], f32x4) * sv[bj][0] * r, v1 = __builtin_convertvector(acc[ai][bj][m][1], f32x4) * sv[bj][1] * r;
;                     u32x4 w; w.x = cvt_pk_bf16(v0[0], v0[1]); w.y = cvt_pk_bf16(v0[2], v0[3]); w.z = cvt_pk_bf16(v1[0], v1[1]); w.w = cvt_pk_bf16(v1[2], v1[3]);
;                     *(u32x4*)(rowp + bj * HALF) = w; } }
; __device__ __forceinline__ void stage_scales(PG8_LAS unsigned char* sb, const float* cs_tile, const float* rs_tile, int tid, int wid) {
;     const float* src = (tid < 256) ? cs_tile + tid : rs_tile + (tid - 256);
;     __builtin_amdgcn_global_load_lds((const unsigned*)src, (PG8_LAS unsigned*)(sb + wid * 256), 4, 0, 0);
; }
	v_pk_mul_f32 v[48:49], v[48:49], v[50:51] op_sel_hi:[1,0]
	v_pk_mul_f32 v[46:47], v[46:47], v[50:51] op_sel_hi:[1,0]
	v_pk_mul_f32 v[54:55], v[44:45], v[50:51] op_sel_hi:[1,0]
	v_pk_mul_f32 v[44:45], v[42:43], v[50:51] op_sel_hi:[1,0]
	v_cvt_pk_bf16_f32 v42, v46, v47
	v_cvt_pk_bf16_f32 v43, v48, v49
	v_pk_mul_f32 v[38:39], v[126:127], v[38:39]
	v_pk_mul_f32 v[36:37], v[124:125], v[36:37]
	v_pk_mul_f32 v[34:35], v[122:123], v[34:35]
	v_cvt_pk_bf16_f32 v44, v44, v45
	v_cvt_pk_bf16_f32 v45, v54, v55
	global_store_dwordx4 v[52:53], v[42:45], off sc1
	v_pk_mul_f32 v[40:41], v[128:129], v[40:41]
	v_pk_mul_f32 v[38:39], v[38:39], v[50:51] op_sel_hi:[1,0]
	v_pk_mul_f32 v[42:43], v[36:37], v[50:51] op_sel_hi:[1,0]
	v_pk_mul_f32 v[36:37], v[34:35], v[50:51] op_sel_hi:[1,0]
	v_cvt_pk_bf16_f32 v34, v38, v39
	v_pk_mul_f32 v[40:41], v[40:41], v[50:51] op_sel_hi:[1,0]
	v_cvt_f32_i32_e32 v31, v31
	v_cvt_pk_bf16_f32 v35, v40, v41
	v_cvt_pk_bf16_f32 v36, v36, v37
	v_cvt_pk_bf16_f32 v37, v42, v43
	global_store_dwordx4 v[52:53], v[34:37], off offset:256 sc1
	ds_read_b32 v34, v176 offset:1664
	v_cvt_f32_i32_e32 v30, v30
	v_cvt_f32_i32_e32 v33, v33
	v_cvt_f32_i32_e32 v32, v32
	v_cvt_f32_i32_e32 v27, v27
	v_cvt_f32_i32_e32 v29, v29
	v_cvt_f32_i32_e32 v28, v28
	v_cvt_f32_i32_e32 v26, v26
	v_cvt_f32_i32_e32 v23, v23
	v_cvt_f32_i32_e32 v22, v22
	v_cvt_f32_i32_e32 v19, v19
	v_cvt_f32_i32_e32 v21, v21
	v_cvt_f32_i32_e32 v20, v20
	v_cvt_f32_i32_e32 v18, v18
	v_cvt_f32_i32_e32 v25, v25
	v_cvt_f32_i32_e32 v24, v24
	v_add_u32_e32 v35, 0xa0, v172
	v_mad_i64_i32 v[36:37], s[0:1], v35, s26, v[166:167]
	v_pk_mul_f32 v[32:33], v[144:145], v[32:33]
	v_pk_mul_f32 v[30:31], v[142:143], v[30:31]
	v_pk_mul_f32 v[28:29], v[136:137], v[28:29]
	v_pk_mul_f32 v[26:27], v[134:135], v[26:27]
	v_lshl_add_u64 v[36:37], v[36:37], 0, v[138:139]
	s_waitcnt lgkmcnt(0)
	v_pk_mul_f32 v[32:33], v[32:33], v[34:35] op_sel_hi:[1,0]
	v_pk_mul_f32 v[30:31], v[30:31], v[34:35] op_sel_hi:[1,0]
	v_pk_mul_f32 v[38:39], v[28:29], v[34:35] op_sel_hi:[1,0]
	v_pk_mul_f32 v[28:29], v[26:27], v[34:35] op_sel_hi:[1,0]
	v_cvt_pk_bf16_f32 v26, v30, v31
	v_cvt_pk_bf16_f32 v27, v32, v33
	v_pk_mul_f32 v[22:23], v[126:127], v[22:23]
	v_pk_mul_f32 v[20:21], v[124:125], v[20:21]
	v_pk_mul_f32 v[18:19], v[122:123], v[18:19]
	v_cvt_pk_bf16_f32 v28, v28, v29
	v_cvt_pk_bf16_f32 v29, v38, v39
	global_store_dwordx4 v[36:37], v[26:29], off sc1
	v_pk_mul_f32 v[24:25], v[128:129], v[24:25]
	v_pk_mul_f32 v[22:23], v[22:23], v[34:35] op_sel_hi:[1,0]
	v_pk_mul_f32 v[26:27], v[20:21], v[34:35] op_sel_hi:[1,0]
	v_pk_mul_f32 v[20:21], v[18:19], v[34:35] op_sel_hi:[1,0]
	v_cvt_pk_bf16_f32 v18, v22, v23
	v_pk_mul_f32 v[24:25], v[24:25], v[34:35] op_sel_hi:[1,0]
	v_cvt_f32_i32_e32 v15, v15
	v_cvt_pk_bf16_f32 v19, v24, v25
	v_cvt_pk_bf16_f32 v20, v20, v21
	v_cvt_pk_bf16_f32 v21, v26, v27
	global_store_dwordx4 v[36:37], v[18:21], off offset:256 sc1
	ds_read_b32 v18, v176 offset:1728
	v_cvt_f32_i32_e32 v14, v14
	v_cvt_f32_i32_e32 v17, v17
	v_cvt_f32_i32_e32 v16, v16
	v_cvt_f32_i32_e32 v11, v11
	v_cvt_f32_i32_e32 v13, v13
	v_cvt_f32_i32_e32 v12, v12
	v_cvt_f32_i32_e32 v10, v10
	v_cvt_f32_i32_e32 v3, v3
	v_cvt_f32_i32_e32 v5, v5
	v_cvt_f32_i32_e32 v4, v4
	v_cvt_f32_i32_e32 v2, v2
	v_cvt_f32_i32_e32 v7, v7
	v_cvt_f32_i32_e32 v9, v9
	v_cvt_f32_i32_e32 v8, v8
	v_cvt_f32_i32_e32 v6, v6
	v_add_u32_e32 v19, 0xb0, v172
	v_mad_i64_i32 v[20:21], s[0:1], v19, s26, v[166:167]
	v_pk_mul_f32 v[16:17], v[144:145], v[16:17]
	v_pk_mul_f32 v[14:15], v[142:143], v[14:15]
	v_pk_mul_f32 v[12:13], v[136:137], v[12:13]
	v_pk_mul_f32 v[10:11], v[134:135], v[10:11]
	v_lshl_add_u64 v[20:21], v[20:21], 0, v[138:139]
	s_waitcnt lgkmcnt(0)
	v_pk_mul_f32 v[16:17], v[16:17], v[18:19] op_sel_hi:[1,0]
	v_pk_mul_f32 v[14:15], v[14:15], v[18:19] op_sel_hi:[1,0]
	v_pk_mul_f32 v[22:23], v[12:13], v[18:19] op_sel_hi:[1,0]
	v_pk_mul_f32 v[12:13], v[10:11], v[18:19] op_sel_hi:[1,0]
	v_cvt_pk_bf16_f32 v10, v14, v15
	v_cvt_pk_bf16_f32 v11, v16, v17
	v_pk_mul_f32 v[4:5], v[124:125], v[4:5]
	v_pk_mul_f32 v[2:3], v[122:123], v[2:3]
	v_cvt_pk_bf16_f32 v12, v12, v13
	v_cvt_pk_bf16_f32 v13, v22, v23
	global_store_dwordx4 v[20:21], v[10:13], off sc1
	v_pk_mul_f32 v[8:9], v[128:129], v[8:9]
	v_pk_mul_f32 v[6:7], v[126:127], v[6:7]
	v_pk_mul_f32 v[10:11], v[4:5], v[18:19] op_sel_hi:[1,0]
	v_pk_mul_f32 v[4:5], v[2:3], v[18:19] op_sel_hi:[1,0]
	s_and_b64 vcc, exec, s[4:5]
	s_mov_b64 s[0:1], -1
	v_pk_mul_f32 v[8:9], v[8:9], v[18:19] op_sel_hi:[1,0]
	v_pk_mul_f32 v[6:7], v[6:7], v[18:19] op_sel_hi:[1,0]
	s_nop 0
	v_cvt_pk_bf16_f32 v2, v6, v7
	v_cvt_pk_bf16_f32 v3, v8, v9
	v_cvt_pk_bf16_f32 v4, v4, v5
	v_cvt_pk_bf16_f32 v5, v10, v11
	global_store_dwordx4 v[20:21], v[2:5], off offset:256 sc1
	s_cbranch_vccnz .LBB0_265
	s_ashr_i32 s49, s48, 31
	s_lshl_b32 s0, s33, 11
	s_lshl_b64 s[4:5], s[48:49], 10
	s_and_b32 s35, s0, 0x800
	s_lshl_b64 s[0:1], s[38:39], 10
	v_lshl_add_u64 v[4:5], v[156:157], 0, s[4:5]
	v_lshl_add_u64 v[2:3], v[154:155], 0, s[0:1]
	v_lshl_add_u64 v[4:5], v[4:5], 0, s[16:17]
	v_cndmask_b32_e64 v3, v5, v3, s[2:3]
	v_cndmask_b32_e64 v2, v4, v2, s[2:3]
	s_add_i32 m0, s13, s35
	s_andn2_b64 vcc, exec, s[40:41]
	global_load_lds_dword v[2:3], off
	s_cbranch_vccnz .LBB0_264
	s_barrier
	s_branch .LBB0_264

; __device__ __forceinline__ unsigned cvt_pk_bf16(float lo, float hi) { unsigned r; asm volatile("v_cvt_pk_bf16_f32 %0, %1, %2" : "=v"(r) : "v"(lo), "v"(hi)); return r; }
;     __device__ __forceinline__ void operator()(const f32x4 (&acc)[2][2][4][2], const Unit& u, int wr, int wc, int fr, int fq) const {
;         const int row0 = u.pm * BM + wr * 64 + fr, col0 = u.pn * BM + wc * 32 + 8 * fq;
; #pragma unroll
;         for (int ai = 0; ai < 2; ++ai)
; #pragma unroll
;             for (int m = 0; m < 4; ++m) { bf16_t* rowp = O + (size_t)(row0 + ai * HALF + m * 16) * ldc + col0;
; #pragma unroll
;                 for (int bj = 0; bj < 2; ++bj) { const f32x4 v0 = acc[ai][bj][m][0], v1 = acc[ai][bj][m][1];
;                     u32x4 w; w.x = cvt_pk_bf16(v0[0], v0[1]); w.y = cvt_pk_bf16(v0[2], v0[3]); w.z = cvt_pk_bf16(v1[0], v1[1]); w.w = cvt_pk_bf16(v1[2], v1[3]);
;                     *(u32x4*)(rowp + bj * HALF) = w; } }
.LBB0_392:
	v_lshl_add_u32 v154, s52, 8, v1
	v_lshl_or_b32 v146, s24, 8, v149
	v_ashrrev_i32_e32 v155, 31, v154
	v_ashrrev_i32_e32 v147, 31, v146
	v_lshlrev_b64 v[156:157], 13, v[154:155]
	v_lshl_add_u64 v[156:157], s[96:97], 0, v[156:157]
	v_lshlrev_b64 v[158:159], 1, v[146:147]
	v_lshl_add_u64 v[146:147], v[156:157], 0, v[158:159]
	v_cvt_pk_bf16_f32 v126, v126, v127
	v_cvt_pk_bf16_f32 v127, v128, v129
	v_cvt_pk_bf16_f32 v128, v122, v123
	v_cvt_pk_bf16_f32 v129, v124, v125
	global_store_dwordx4 v[146:147], v[126:129], off sc1
	v_cvt_pk_bf16_f32 v114, v114, v115
	v_cvt_pk_bf16_f32 v115, v116, v117
	v_cvt_pk_bf16_f32 v116, v106, v107
	v_or_b32_e32 v106, 16, v154
	v_ashrrev_i32_e32 v107, 31, v106
	v_lshlrev_b64 v[106:107], 13, v[106:107]
	v_lshl_add_u64 v[106:107], s[96:97], 0, v[106:107]
	v_cvt_pk_bf16_f32 v117, v108, v109
	global_store_dwordx4 v[146:147], v[114:117], off offset:256 sc1
	s_mov_b64 s[0:1], 0x100000
	s_nop 0
	v_lshl_add_u64 v[114:115], v[106:107], 0, v[158:159]
	v_cvt_pk_bf16_f32 v106, v118, v119
	v_cvt_pk_bf16_f32 v107, v120, v121
	v_cvt_pk_bf16_f32 v108, v110, v111
	v_cvt_pk_bf16_f32 v109, v112, v113
	global_store_dwordx4 v[114:115], v[106:109], off sc1
	v_cvt_pk_bf16_f32 v98, v98, v99
	v_cvt_pk_bf16_f32 v99, v100, v101
	v_cvt_pk_bf16_f32 v100, v90, v91
	v_or_b32_e32 v90, 32, v154
	v_ashrrev_i32_e32 v91, 31, v90
	v_lshlrev_b64 v[90:91], 13, v[90:91]
	v_lshl_add_u64 v[90:91], s[96:97], 0, v[90:91]
	v_cvt_pk_bf16_f32 v101, v92, v93
	global_store_dwordx4 v[114:115], v[98:101], off offset:256 sc1
	s_nop 1
	v_lshl_add_u64 v[98:99], v[90:91], 0, v[158:159]
	v_cvt_pk_bf16_f32 v90, v102, v103
	v_cvt_pk_bf16_f32 v91, v104, v105
	v_cvt_pk_bf16_f32 v92, v94, v95
	v_cvt_pk_bf16_f32 v93, v96, v97
	global_store_dwordx4 v[98:99], v[90:93], off sc1
	v_cvt_pk_bf16_f32 v82, v82, v83
	v_cvt_pk_bf16_f32 v83, v84, v85
	v_cvt_pk_bf16_f32 v84, v74, v75
	v_or_b32_e32 v74, 48, v154
	v_ashrrev_i32_e32 v75, 31, v74
	v_lshlrev_b64 v[74:75], 13, v[74:75]
	v_lshl_add_u64 v[74:75], s[96:97], 0, v[74:75]
	v_cvt_pk_bf16_f32 v85, v76, v77
	global_store_dwordx4 v[98:99], v[82:85], off offset:256 sc1
	s_nop 1
	v_lshl_add_u64 v[82:83], v[74:75], 0, v[158:159]
	v_cvt_pk_bf16_f32 v74, v86, v87
	v_cvt_pk_bf16_f32 v75, v88, v89
	v_cvt_pk_bf16_f32 v76, v78, v79
	v_cvt_pk_bf16_f32 v77, v80, v81
	global_store_dwordx4 v[82:83], v[74:77], off sc1
	v_cvt_pk_bf16_f32 v70, v70, v71
	v_cvt_pk_bf16_f32 v71, v72, v73
	v_cvt_pk_bf16_f32 v72, v66, v67
	v_lshl_add_u64 v[66:67], v[146:147], 0, s[0:1]
	s_mov_b32 s0, 0x100000
	v_cvt_pk_bf16_f32 v73, v68, v69
	global_store_dwordx4 v[82:83], v[70:73], off offset:256 sc1
	v_cvt_pk_bf16_f32 v62, v62, v63
	v_cvt_pk_bf16_f32 v63, v64, v65
	v_cvt_pk_bf16_f32 v64, v58, v59
	v_add_co_u32_e32 v58, vcc, s0, v146
	v_cvt_pk_bf16_f32 v65, v60, v61
	s_mov_b64 s[0:1], 0x120000
	s_nop 0
	v_addc_co_u32_e32 v59, vcc, 0, v147, vcc
	global_store_dwordx4 v[58:59], v[62:65], off sc1
	v_cvt_pk_bf16_f32 v50, v50, v51
	v_cvt_pk_bf16_f32 v51, v52, v53
	v_cvt_pk_bf16_f32 v52, v42, v43
	v_cvt_pk_bf16_f32 v53, v44, v45
	global_store_dwordx4 v[66:67], v[50:53], off offset:256 sc1
	v_cvt_pk_bf16_f32 v42, v54, v55
	v_cvt_pk_bf16_f32 v43, v56, v57
	v_cvt_pk_bf16_f32 v44, v46, v47
	v_cvt_pk_bf16_f32 v45, v48, v49
	s_nop 1
	v_lshl_add_u64 v[50:51], v[146:147], 0, s[0:1]
	s_mov_b32 s0, 0x120000
	v_add_co_u32_e32 v46, vcc, s0, v146
	s_mov_b64 s[0:1], 0x140000
	s_nop 0
	v_addc_co_u32_e32 v47, vcc, 0, v147, vcc
	global_store_dwordx4 v[46:47], v[42:45], off sc1
	v_cvt_pk_bf16_f32 v34, v34, v35
	v_cvt_pk_bf16_f32 v35, v36, v37
	v_cvt_pk_bf16_f32 v36, v26, v27
	v_cvt_pk_bf16_f32 v37, v28, v29
	global_store_dwordx4 v[50:51], v[34:37], off offset:256 sc1
	v_cvt_pk_bf16_f32 v26, v38, v39
	v_cvt_pk_bf16_f32 v27, v40, v41
	v_cvt_pk_bf16_f32 v28, v30, v31
	v_cvt_pk_bf16_f32 v29, v32, v33
	s_nop 1
	v_lshl_add_u64 v[34:35], v[146:147], 0, s[0:1]
	s_mov_b32 s0, 0x140000
	v_add_co_u32_e32 v30, vcc, s0, v146
	s_mov_b64 s[0:1], 0x160000
	s_nop 0
	v_addc_co_u32_e32 v31, vcc, 0, v147, vcc
	global_store_dwordx4 v[30:31], v[26:29], off sc1
	v_cvt_pk_bf16_f32 v18, v18, v19
	v_cvt_pk_bf16_f32 v19, v20, v21
	v_cvt_pk_bf16_f32 v20, v10, v11
	v_cvt_pk_bf16_f32 v21, v12, v13
	global_store_dwordx4 v[34:35], v[18:21], off offset:256 sc1
	v_cvt_pk_bf16_f32 v10, v22, v23
	v_cvt_pk_bf16_f32 v11, v24, v25
	v_cvt_pk_bf16_f32 v12, v14, v15
	v_cvt_pk_bf16_f32 v13, v16, v17
	s_nop 1
	v_lshl_add_u64 v[18:19], v[146:147], 0, s[0:1]
	s_mov_b32 s0, 0x160000
	v_add_co_u32_e32 v14, vcc, s0, v146
	s_mov_b64 s[0:1], -1
	s_nop 0
	v_addc_co_u32_e32 v15, vcc, 0, v147, vcc
	s_and_b64 vcc, exec, s[2:3]
	global_store_dwordx4 v[14:15], v[10:13], off sc1
	v_cvt_pk_bf16_f32 v6, v6, v7
	v_cvt_pk_bf16_f32 v7, v8, v9
	v_cvt_pk_bf16_f32 v8, v2, v3
	v_cvt_pk_bf16_f32 v9, v4, v5
	global_store_dwordx4 v[18:19], v[6:9], off offset:256 sc1
	s_cbranch_vccnz .LBB0_379
	s_andn2_b64 vcc, exec, s[4:5]
	s_cbranch_vccnz .LBB0_378
	s_barrier
	s_branch .LBB0_378

; #define PG8_LAS __attribute__((address_space(3)))
; __device__ __forceinline__ unsigned cvt_pk_bf16(float lo, float hi) { unsigned r; asm volatile("v_cvt_pk_bf16_f32 %0, %1, %2" : "=v"(r) : "v"(lo), "v"(hi)); return r; }
; __device__ __forceinline__ float bf_lo(unsigned w) { return __uint_as_float(w << 16); }
; __device__ __forceinline__ float bf_hi(unsigned w) { return __uint_as_float(w & 0xffff0000u); }
;     __device__ __forceinline__ void operator()(const i32x4 (&acc)[2][2][4][2], const Unit& u, int wr, int wc, int fr, int fq, const PG8_LAS float* sb) const {
;         const int row0 = u.pm * BM + wr * 64 + fr, col0 = u.pn * BM + wc * 32 + 8 * fq;
;         f32x4 sv[2][2];
; #pragma unroll
;         for (int bj = 0; bj < 2; ++bj)
; #pragma unroll
;             for (int n = 0; n < 2; ++n) sv[bj][n] = *(const PG8_LAS f32x4*)(sb + wc * 32 + 8 * fq + bj * HALF + 4 * n);
; #pragma unroll
;         for (int ai = 0; ai < 2; ++ai) {
;             u32x4 g[4][2];
; #pragma unroll
;             for (int m = 0; m < 4; ++m) { const size_t row = (size_t)(row0 + ai * HALF + m * 16);
; #pragma unroll
;                 for (int bj = 0; bj < 2; ++bj) g[m][bj] = *(const u32x4*)(Gt + row * ldg + col0 + bj * HALF); }
;             asm volatile("" ::: "memory");
; #pragma unroll
;             for (int m = 0; m < 4; ++m) { const size_t row = (size_t)(row0 + ai * HALF + m * 16); bf16_t* rowp = O + row * ldc + col0; const float r = sb[256 + wr * 64 + fr + ai * HALF + m * 16];
; #pragma unroll
;                 for (int bj = 0; bj < 2; ++bj) { const u32x4 gg = g[m][bj];
;                     const f32x4 v0 = __builtin_convertvector(acc[ai][bj][m][0], f32x4) * sv[bj][0] * r, v1 = __builtin_convertvector(acc[ai][bj][m][1], f32x4) * sv[bj][1] * r;
;                     float o[8];
;                     o[0] = sigmoidf_(bf_lo(gg.x)) * v0[0]; o[1] = sigmoidf_(bf_hi(gg.x)) * v0[1]; o[2] = sigmoidf_(bf_lo(gg.y)) * v0[2]; o[3] = sigmoidf_(bf_hi(gg.y)) * v0[3];
;                     o[4] = sigmoidf_(bf_lo(gg.z)) * v1[0]; o[5] = sigmoidf_(bf_hi(gg.z)) * v1[1]; o[6] = sigmoidf_(bf_lo(gg.w)) * v1[2]; o[7] = sigmoidf_(bf_hi(gg.w)) * v1[3];
;                     u32x4 w; w.x = cvt_pk_bf16(o[0], o[1]); w.y = cvt_pk_bf16(o[2], o[3]); w.z = cvt_pk_bf16(o[4], o[5]); w.w = cvt_pk_bf16(o[6], o[7]);
;                     *(u32x4*)(rowp + bj * HALF) = w; } }
.LBB0_558:
	v_lshl_or_b32 v82, s27, 8, v212
	v_ashrrev_i32_e32 v83, 31, v82
	v_lshlrev_b64 v[186:187], 1, v[82:83]
	v_lshl_add_u32 v188, s60, 8, v208
	v_lshl_add_u64 v[190:191], s[48:49], 0, v[186:187]
	v_mad_i64_i32 v[82:83], s[28:29], v188, s21, v[190:191]
	global_load_dwordx4 v[216:219], v[82:83], off
	s_lshl_b32 s26, s26, 11
	s_and_b32 s26, s26, 0x800
	s_add_i32 s26, s26, 0
	s_lshl_b32 s27, s18, 2
	s_lshl_b32 s28, s17, 2
	v_or_b32_e32 v232, 16, v188
	v_or_b32_e32 v194, 32, v188
	v_or_b32_e32 v192, 48, v188
	s_add_i32 s26, s26, 0x20400
	v_cvt_f32_i32_e32 v225, v71
	v_cvt_f32_i32_e32 v224, v70
	v_cvt_f32_i32_e32 v227, v73
	v_cvt_f32_i32_e32 v226, v72
	v_cvt_f32_i32_e32 v231, v69
	v_cvt_f32_i32_e32 v230, v68
	s_add_i32 s29, s26, s27
	s_add_i32 s28, s26, s28
	v_mad_i64_i32 v[68:69], s[26:27], v232, s21, v[190:191]
	v_mad_i64_i32 v[70:71], s[26:27], v194, s21, v[190:191]
	v_mad_i64_i32 v[72:73], s[26:27], v192, s21, v[190:191]
	global_load_dwordx4 v[220:223], v[82:83], off offset:256
	global_load_dwordx4 v[158:161], v[68:69], off
	global_load_dwordx4 v[154:157], v[68:69], off offset:256
	global_load_dwordx4 v[150:153], v[70:71], off
	global_load_dwordx4 v[146:149], v[70:71], off offset:256
	global_load_dwordx4 v[142:145], v[72:73], off
	global_load_dwordx4 v[138:141], v[72:73], off offset:256
	v_ashrrev_i32_e32 v189, 31, v188
	v_readlane_b32 s36, v249, 35
	v_cvt_f32_i32_e32 v229, v67
	v_cvt_f32_i32_e32 v228, v66
	v_lshlrev_b64 v[66:67], 13, v[188:189]
	v_readlane_b32 s37, v249, 36
	v_lshl_add_u32 v189, v200, 2, s28
	v_cvt_f32_i32_e32 v135, v135
	v_lshl_add_u64 v[66:67], s[36:37], 0, v[66:67]
	v_lshl_add_u64 v[234:235], v[66:67], 0, v[186:187]
	v_lshl_add_u32 v66, v199, 2, s29
	ds_read_b128 v[86:89], v66
	ds_read_b128 v[82:85], v66 offset:16
	ds_read_b128 v[70:73], v66 offset:512
	ds_read_b128 v[66:69], v66 offset:528
	ds_read_b32 v236, v189 offset:1024
	s_waitcnt lgkmcnt(0)
	v_pk_mul_f32 v[226:227], v[88:89], v[226:227]
	v_pk_mul_f32 v[224:225], v[86:87], v[224:225]
	v_pk_mul_f32 v[230:231], v[84:85], v[230:231]
	v_pk_mul_f32 v[228:229], v[82:83], v[228:229]
	v_pk_mul_f32 v[226:227], v[226:227], v[236:237] op_sel_hi:[1,0]
	v_pk_mul_f32 v[224:225], v[224:225], v[236:237] op_sel_hi:[1,0]
	v_pk_mul_f32 v[230:231], v[230:231], v[236:237] op_sel_hi:[1,0]
	v_pk_mul_f32 v[228:229], v[228:229], v[236:237] op_sel_hi:[1,0]
	v_cvt_f32_i32_e32 v137, v137
	v_cvt_f32_i32_e32 v136, v136
	v_cvt_f32_i32_e32 v134, v134
	v_cvt_f32_i32_e32 v133, v133
	v_cvt_f32_i32_e32 v132, v132
	v_pk_mul_f32 v[136:137], v[72:73], v[136:137]
	v_pk_mul_f32 v[134:135], v[70:71], v[134:135]
	v_cvt_f32_i32_e32 v131, v131
	v_cvt_f32_i32_e32 v130, v130
	v_pk_mul_f32 v[132:133], v[68:69], v[132:133]
	v_cvt_f32_i32_e32 v127, v127
	v_cvt_f32_i32_e32 v129, v129
	v_pk_mul_f32 v[130:131], v[66:67], v[130:131]
	v_cvt_f32_i32_e32 v128, v128
	v_cvt_f32_i32_e32 v126, v126
	v_cvt_f32_i32_e32 v125, v125
	v_cvt_f32_i32_e32 v124, v124
	v_pk_mul_f32 v[128:129], v[88:89], v[128:129]
	v_pk_mul_f32 v[126:127], v[86:87], v[126:127]
	v_cvt_f32_i32_e32 v123, v123
	v_cvt_f32_i32_e32 v122, v122
	v_pk_mul_f32 v[124:125], v[84:85], v[124:125]
	v_ashrrev_i32_e32 v233, 31, v232
	v_cvt_f32_i32_e32 v119, v119
	v_pk_mul_f32 v[122:123], v[82:83], v[122:123]
	v_cvt_f32_i32_e32 v121, v121
	v_cvt_f32_i32_e32 v120, v120
	v_cvt_f32_i32_e32 v118, v118
	v_cvt_f32_i32_e32 v117, v117
	v_cvt_f32_i32_e32 v116, v116
	v_pk_mul_f32 v[120:121], v[72:73], v[120:121]
	v_pk_mul_f32 v[118:119], v[70:71], v[118:119]
	v_cvt_f32_i32_e32 v115, v115
	s_waitcnt vmcnt(0)
	v_lshlrev_b32_e32 v215, 16, v216
	v_and_b32_e32 v216, 0xffff0000, v216
	v_mul_f32_e32 v216, 0xbfb8aa3b, v216
	v_exp_f32_e32 v216, v216
	v_lshlrev_b32_e32 v237, 16, v217
	v_and_b32_e32 v217, 0xffff0000, v217
	v_lshlrev_b32_e32 v238, 16, v218
	v_add_f32_e32 v216, 1.0, v216
	v_rcp_f32_e32 v216, v216
	v_and_b32_e32 v218, 0xffff0000, v218
	v_lshlrev_b32_e32 v239, 16, v219
	v_mul_f32_e32 v217, 0xbfb8aa3b, v217
	v_and_b32_e32 v219, 0xffff0000, v219
	v_mul_f32_e32 v215, 0xbfb8aa3b, v215
	v_mul_f32_e32 v237, 0xbfb8aa3b, v237
	v_mul_f32_e32 v218, 0xbfb8aa3b, v218
	v_exp_f32_e32 v217, v217
	v_mul_f32_e32 v219, 0xbfb8aa3b, v219
	v_mul_f32_e32 v238, 0xbfb8aa3b, v238
	v_exp_f32_e32 v215, v215
	v_exp_f32_e32 v237, v237
	v_exp_f32_e32 v218, v218
	v_mul_f32_e32 v216, v216, v225
	v_mul_f32_e32 v225, 0xbfb8aa3b, v239
	v_exp_f32_e32 v219, v219
	v_exp_f32_e32 v238, v238
	v_exp_f32_e32 v225, v225
	v_add_f32_e32 v217, 1.0, v217
	v_add_f32_e32 v215, 1.0, v215
	v_add_f32_e32 v237, 1.0, v237
	v_add_f32_e32 v218, 1.0, v218
	v_rcp_f32_e32 v217, v217
	v_add_f32_e32 v219, 1.0, v219
	v_add_f32_e32 v238, 1.0, v238
	v_rcp_f32_e32 v215, v215
	v_rcp_f32_e32 v237, v237
	v_rcp_f32_e32 v218, v218
	v_add_f32_e32 v225, 1.0, v225
	v_rcp_f32_e32 v219, v219
	v_rcp_f32_e32 v238, v238
	v_rcp_f32_e32 v225, v225
	v_mul_f32_e32 v217, v217, v227
	v_mul_f32_e32 v215, v215, v224
	v_mul_f32_e32 v224, v237, v226
	v_mul_f32_e32 v218, v218, v229
	v_mul_f32_e32 v219, v219, v231
	v_cvt_pk_bf16_f32 v216, v215, v216
	v_cvt_pk_bf16_f32 v217, v224, v217
	v_mul_f32_e32 v226, v238, v228
	v_mul_f32_e32 v225, v225, v230
	v_cvt_pk_bf16_f32 v218, v226, v218
	v_cvt_pk_bf16_f32 v219, v225, v219
	global_store_dwordx4 v[234:235], v[216:219], off sc1
	v_lshlrev_b32_e32 v215, 16, v220
	v_mul_f32_e32 v215, 0xbfb8aa3b, v215
	v_and_b32_e32 v216, 0xffff0000, v220
	v_lshlrev_b32_e32 v217, 16, v221
	v_mul_f32_e32 v216, 0xbfb8aa3b, v216
	v_mul_f32_e32 v217, 0xbfb8aa3b, v217
	v_exp_f32_e32 v216, v216
	v_exp_f32_e32 v217, v217
	v_exp_f32_e32 v215, v215
	v_and_b32_e32 v218, 0xffff0000, v221
	v_add_f32_e32 v216, 1.0, v216
	v_add_f32_e32 v217, 1.0, v217
; __device__ __forceinline__ unsigned cvt_pk_bf16(float lo, float hi) { unsigned r; asm volatile("v_cvt_pk_bf16_f32 %0, %1, %2" : "=v"(r) : "v"(lo), "v"(hi)); return r; }
; __device__ __forceinline__ float bf_lo(unsigned w) { return __uint_as_float(w << 16); }
; __device__ __forceinline__ float bf_hi(unsigned w) { return __uint_as_float(w & 0xffff0000u); }
; __device__ __forceinline__ float sigmoidf_(float x) { return fast_rcp(1.0f + fast_exp(-x)); }
;     __device__ __forceinline__ void operator()(const i32x4 (&acc)[2][2][4][2], const Unit& u, int wr, int wc, int fr, int fq, const PG8_LAS float* sb) const {
;     ...
;             for (int m = 0; m < 4; ++m) { const size_t row = (size_t)(row0 + ai * HALF + m * 16); bf16_t* rowp = O + row * ldc + col0; const float r = sb[256 + wr * 64 + fr + ai * HALF + m * 16];
; #pragma unroll
;                 for (int bj = 0; bj < 2; ++bj) { const u32x4 gg = g[m][bj];
;                     const f32x4 v0 = __builtin_convertvector(acc[ai][bj][m][0], f32x4) * sv[bj][0] * r, v1 = __builtin_convertvector(acc[ai][bj][m][1], f32x4) * sv[bj][1] * r;
;                     float o[8];
;                     o[0] = sigmoidf_(bf_lo(gg.x)) * v0[0]; o[1] = sigmoidf_(bf_hi(gg.x)) * v0[1]; o[2] = sigmoidf_(bf_lo(gg.y)) * v0[2]; o[3] = sigmoidf_(bf_hi(gg.y)) * v0[3];
;                     o[4] = sigmoidf_(bf_lo(gg.z)) * v1[0]; o[5] = sigmoidf_(bf_hi(gg.z)) * v1[1]; o[6] = sigmoidf_(bf_lo(gg.w)) * v1[2]; o[7] = sigmoidf_(bf_hi(gg.w)) * v1[3];
;                     u32x4 w; w.x = cvt_pk_bf16(o[0], o[1]); w.y = cvt_pk_bf16(o[2], o[3]); w.z = cvt_pk_bf16(o[4], o[5]); w.w = cvt_pk_bf16(o[6], o[7]);
;                     *(u32x4*)(rowp + bj * HALF) = w; } }
	v_add_f32_e32 v215, 1.0, v215
	v_rcp_f32_e32 v216, v216
	v_rcp_f32_e32 v217, v217
	v_mul_f32_e32 v218, 0xbfb8aa3b, v218
	v_rcp_f32_e32 v215, v215
	v_exp_f32_e32 v218, v218
	v_pk_mul_f32 v[136:137], v[136:137], v[236:237] op_sel_hi:[1,0]
	v_pk_mul_f32 v[134:135], v[134:135], v[236:237] op_sel_hi:[1,0]
	v_mul_f32_e32 v136, v217, v136
	v_mul_f32_e32 v135, v216, v135
	v_lshlrev_b32_e32 v216, 16, v222
	v_and_b32_e32 v217, 0xffff0000, v222
	v_mul_f32_e32 v134, v215, v134
	v_add_f32_e32 v215, 1.0, v218
	v_mul_f32_e32 v216, 0xbfb8aa3b, v216
	v_mul_f32_e32 v217, 0xbfb8aa3b, v217
	v_rcp_f32_e32 v215, v215
	v_exp_f32_e32 v216, v216
	v_exp_f32_e32 v217, v217
	v_and_b32_e32 v218, 0xffff0000, v223
	v_mul_f32_e32 v137, v215, v137
	v_add_f32_e32 v215, 1.0, v216
	v_add_f32_e32 v216, 1.0, v217
	v_lshlrev_b32_e32 v217, 16, v223
	v_mul_f32_e32 v217, 0xbfb8aa3b, v217
	v_mul_f32_e32 v218, 0xbfb8aa3b, v218
	v_exp_f32_e32 v217, v217
	v_exp_f32_e32 v218, v218
	v_rcp_f32_e32 v215, v215
	v_rcp_f32_e32 v216, v216
	v_add_f32_e32 v217, 1.0, v217
	v_add_f32_e32 v218, 1.0, v218
	v_rcp_f32_e32 v217, v217
	v_rcp_f32_e32 v218, v218
	v_pk_mul_f32 v[132:133], v[132:133], v[236:237] op_sel_hi:[1,0]
	v_pk_mul_f32 v[130:131], v[130:131], v[236:237] op_sel_hi:[1,0]
	v_mul_f32_e32 v217, v217, v132
	v_mul_f32_e32 v215, v215, v130
	v_mul_f32_e32 v216, v216, v131
	v_mul_f32_e32 v133, v218, v133
	v_cvt_pk_bf16_f32 v130, v134, v135
	v_cvt_pk_bf16_f32 v131, v136, v137
	v_cvt_pk_bf16_f32 v132, v215, v216
	v_cvt_pk_bf16_f32 v133, v217, v133
	global_store_dwordx4 v[234:235], v[130:133], off offset:256 sc1
	ds_read_b32 v132, v189 offset:1088
	v_and_b32_e32 v134, 0xffff0000, v158
	v_lshlrev_b32_e32 v135, 16, v159
	v_mul_f32_e32 v134, 0xbfb8aa3b, v134
	v_mul_f32_e32 v135, 0xbfb8aa3b, v135
	s_waitcnt lgkmcnt(0)
	v_pk_mul_f32 v[128:129], v[128:129], v[132:133] op_sel_hi:[1,0]
	v_pk_mul_f32 v[126:127], v[126:127], v[132:133] op_sel_hi:[1,0]
	v_lshlrev_b32_e32 v133, 16, v158
	v_mul_f32_e32 v133, 0xbfb8aa3b, v133
	v_exp_f32_e32 v134, v134
	v_exp_f32_e32 v135, v135
	v_exp_f32_e32 v133, v133
	v_and_b32_e32 v136, 0xffff0000, v159
	v_add_f32_e32 v134, 1.0, v134
	v_add_f32_e32 v135, 1.0, v135
	v_pk_mul_f32 v[124:125], v[124:125], v[132:133] op_sel_hi:[1,0]
	v_pk_mul_f32 v[122:123], v[122:123], v[132:133] op_sel_hi:[1,0]
	v_add_f32_e32 v133, 1.0, v133
	v_rcp_f32_e32 v134, v134
	v_rcp_f32_e32 v135, v135
	v_mul_f32_e32 v136, 0xbfb8aa3b, v136
	v_rcp_f32_e32 v133, v133
	v_exp_f32_e32 v136, v136
	v_mul_f32_e32 v127, v134, v127
	v_mul_f32_e32 v128, v135, v128
	v_lshlrev_b32_e32 v134, 16, v160
	v_and_b32_e32 v135, 0xffff0000, v160
	v_mul_f32_e32 v126, v133, v126
	v_add_f32_e32 v133, 1.0, v136
	v_mul_f32_e32 v134, 0xbfb8aa3b, v134
	v_mul_f32_e32 v135, 0xbfb8aa3b, v135
	v_rcp_f32_e32 v133, v133
	v_exp_f32_e32 v134, v134
	v_exp_f32_e32 v135, v135
	v_and_b32_e32 v136, 0xffff0000, v161
	v_mul_f32_e32 v129, v133, v129
	v_add_f32_e32 v133, 1.0, v134
	v_add_f32_e32 v134, 1.0, v135
	v_lshlrev_b32_e32 v135, 16, v161
	v_mul_f32_e32 v135, 0xbfb8aa3b, v135
	v_mul_f32_e32 v136, 0xbfb8aa3b, v136
	v_exp_f32_e32 v135, v135
	v_exp_f32_e32 v136, v136
	v_rcp_f32_e32 v133, v133
	v_rcp_f32_e32 v134, v134
	v_add_f32_e32 v135, 1.0, v135
	v_add_f32_e32 v136, 1.0, v136
	v_rcp_f32_e32 v135, v135
	v_rcp_f32_e32 v136, v136
	v_lshlrev_b64 v[130:131], 13, v[232:233]
	v_lshl_add_u64 v[130:131], s[36:37], 0, v[130:131]
	v_lshl_add_u64 v[130:131], v[130:131], 0, v[186:187]
	v_mul_f32_e32 v133, v133, v122
	v_mul_f32_e32 v134, v134, v123
	v_mul_f32_e32 v135, v135, v124
	v_mul_f32_e32 v125, v136, v125
	v_cvt_pk_bf16_f32 v122, v126, v127
	v_cvt_pk_bf16_f32 v123, v128, v129
	v_cvt_pk_bf16_f32 v124, v133, v134
	v_cvt_pk_bf16_f32 v125, v135, v125
	global_store_dwordx4 v[130:131], v[122:125], off sc1
	v_pk_mul_f32 v[120:121], v[120:121], v[132:133] op_sel_hi:[1,0]
	v_pk_mul_f32 v[118:119], v[118:119], v[132:133] op_sel_hi:[1,0]
	v_and_b32_e32 v123, 0xffff0000, v154
	v_lshlrev_b32_e32 v124, 16, v155
	v_lshlrev_b32_e32 v122, 16, v154
	v_mul_f32_e32 v123, 0xbfb8aa3b, v123
	v_mul_f32_e32 v124, 0xbfb8aa3b, v124
	v_mul_f32_e32 v122, 0xbfb8aa3b, v122
	v_exp_f32_e32 v123, v123
	v_exp_f32_e32 v124, v124
	v_exp_f32_e32 v122, v122
	v_and_b32_e32 v125, 0xffff0000, v155
	v_add_f32_e32 v123, 1.0, v123
	v_add_f32_e32 v124, 1.0, v124
	v_add_f32_e32 v122, 1.0, v122
	v_rcp_f32_e32 v123, v123
	v_rcp_f32_e32 v124, v124
	v_mul_f32_e32 v125, 0xbfb8aa3b, v125
	v_rcp_f32_e32 v122, v122
	v_exp_f32_e32 v125, v125
	v_mul_f32_e32 v119, v123, v119
	v_mul_f32_e32 v120, v124, v120
	v_lshlrev_b32_e32 v123, 16, v156
	v_and_b32_e32 v124, 0xffff0000, v156
	v_mul_f32_e32 v118, v122, v118
	v_add_f32_e32 v122, 1.0, v125
	v_mul_f32_e32 v123, 0xbfb8aa3b, v123
	v_mul_f32_e32 v124, 0xbfb8aa3b, v124
	v_rcp_f32_e32 v122, v122
	v_exp_f32_e32 v123, v123
	v_exp_f32_e32 v124, v124
	v_and_b32_e32 v125, 0xffff0000, v157
	v_mul_f32_e32 v121, v122, v121
	v_add_f32_e32 v122, 1.0, v123
	v_add_f32_e32 v123, 1.0, v124
	v_lshlrev_b32_e32 v124, 16, v157
	v_mul_f32_e32 v124, 0xbfb8aa3b, v124
	v_mul_f32_e32 v125, 0xbfb8aa3b, v125
	v_exp_f32_e32 v124, v124
	v_exp_f32_e32 v125, v125
	v_cvt_f32_i32_e32 v114, v114
	v_rcp_f32_e32 v122, v122
	v_add_f32_e32 v124, 1.0, v124
	v_add_f32_e32 v125, 1.0, v125
	v_rcp_f32_e32 v123, v123
	v_rcp_f32_e32 v124, v124
	v_rcp_f32_e32 v125, v125
	v_pk_mul_f32 v[116:117], v[68:69], v[116:117]
	v_pk_mul_f32 v[114:115], v[66:67], v[114:115]
	v_pk_mul_f32 v[116:117], v[116:117], v[132:133] op_sel_hi:[1,0]
	v_pk_mul_f32 v[114:115], v[114:115], v[132:133] op_sel_hi:[1,0]
	v_mul_f32_e32 v124, v124, v116
	v_mul_f32_e32 v122, v122, v114
	v_mul_f32_e32 v123, v123, v115
	v_mul_f32_e32 v117, v125, v117
	v_cvt_pk_bf16_f32 v114, v118, v119
	v_cvt_pk_bf16_f32 v115, v120, v121
	v_cvt_pk_bf16_f32 v116, v122, v123
	v_cvt_pk_bf16_f32 v117, v124, v117
	global_store_dwordx4 v[130:131], v[114:117], off offset:256 sc1
	ds_read_b32 v116, v189 offset:1152
	v_cvt_f32_i32_e32 v111, v111
	v_cvt_f32_i32_e32 v113, v113
	v_cvt_f32_i32_e32 v112, v112
	v_cvt_f32_i32_e32 v110, v110
	v_and_b32_e32 v118, 0xffff0000, v150
	v_lshlrev_b32_e32 v119, 16, v151
	v_pk_mul_f32 v[112:113], v[88:89], v[112:113]
	v_pk_mul_f32 v[110:111], v[86:87], v[110:111]
	s_waitcnt lgkmcnt(0)
; __device__ __forceinline__ unsigned cvt_pk_bf16(float lo, float hi) { unsigned r; asm volatile("v_cvt_pk_bf16_f32 %0, %1, %2" : "=v"(r) : "v"(lo), "v"(hi)); return r; }
; __device__ __forceinline__ float bf_lo(unsigned w) { return __uint_as_float(w << 16); }
; __device__ __forceinline__ float bf_hi(unsigned w) { return __uint_as_float(w & 0xffff0000u); }
; __device__ __forceinline__ float sigmoidf_(float x) { return fast_rcp(1.0f + fast_exp(-x)); }
;     __device__ __forceinline__ void operator()(const i32x4 (&acc)[2][2][4][2], const Unit& u, int wr, int wc, int fr, int fq, const PG8_LAS float* sb) const {
;     ...
;             for (int m = 0; m < 4; ++m) { const size_t row = (size_t)(row0 + ai * HALF + m * 16); bf16_t* rowp = O + row * ldc + col0; const float r = sb[256 + wr * 64 + fr + ai * HALF + m * 16];
; #pragma unroll
;                 for (int bj = 0; bj < 2; ++bj) { const u32x4 gg = g[m][bj];
;                     const f32x4 v0 = __builtin_convertvector(acc[ai][bj][m][0], f32x4) * sv[bj][0] * r, v1 = __builtin_convertvector(acc[ai][bj][m][1], f32x4) * sv[bj][1] * r;
;                     float o[8];
;                     o[0] = sigmoidf_(bf_lo(gg.x)) * v0[0]; o[1] = sigmoidf_(bf_hi(gg.x)) * v0[1]; o[2] = sigmoidf_(bf_lo(gg.y)) * v0[2]; o[3] = sigmoidf_(bf_hi(gg.y)) * v0[3];
;                     o[4] = sigmoidf_(bf_lo(gg.z)) * v1[0]; o[5] = sigmoidf_(bf_hi(gg.z)) * v1[1]; o[6] = sigmoidf_(bf_lo(gg.w)) * v1[2]; o[7] = sigmoidf_(bf_hi(gg.w)) * v1[3];
;                     u32x4 w; w.x = cvt_pk_bf16(o[0], o[1]); w.y = cvt_pk_bf16(o[2], o[3]); w.z = cvt_pk_bf16(o[4], o[5]); w.w = cvt_pk_bf16(o[6], o[7]);
;                     *(u32x4*)(rowp + bj * HALF) = w; } }
	v_pk_mul_f32 v[112:113], v[112:113], v[116:117] op_sel_hi:[1,0]
	v_pk_mul_f32 v[110:111], v[110:111], v[116:117] op_sel_hi:[1,0]
	v_lshlrev_b32_e32 v117, 16, v150
	v_mul_f32_e32 v118, 0xbfb8aa3b, v118
	v_mul_f32_e32 v119, 0xbfb8aa3b, v119
	v_cvt_f32_i32_e32 v109, v109
	v_cvt_f32_i32_e32 v108, v108
	v_cvt_f32_i32_e32 v107, v107
	v_cvt_f32_i32_e32 v106, v106
	v_mul_f32_e32 v117, 0xbfb8aa3b, v117
	v_exp_f32_e32 v118, v118
	v_exp_f32_e32 v119, v119
	v_exp_f32_e32 v117, v117
	v_pk_mul_f32 v[108:109], v[84:85], v[108:109]
	v_pk_mul_f32 v[106:107], v[82:83], v[106:107]
	v_add_f32_e32 v118, 1.0, v118
	v_add_f32_e32 v119, 1.0, v119
	v_and_b32_e32 v120, 0xffff0000, v151
	v_pk_mul_f32 v[108:109], v[108:109], v[116:117] op_sel_hi:[1,0]
	v_pk_mul_f32 v[106:107], v[106:107], v[116:117] op_sel_hi:[1,0]
	v_add_f32_e32 v117, 1.0, v117
	v_rcp_f32_e32 v118, v118
	v_rcp_f32_e32 v119, v119
	v_mul_f32_e32 v120, 0xbfb8aa3b, v120
	v_rcp_f32_e32 v117, v117
	v_exp_f32_e32 v120, v120
	v_mul_f32_e32 v111, v118, v111
	v_mul_f32_e32 v112, v119, v112
	v_lshlrev_b32_e32 v118, 16, v152
	v_and_b32_e32 v119, 0xffff0000, v152
	v_mul_f32_e32 v110, v117, v110
	v_add_f32_e32 v117, 1.0, v120
	v_mul_f32_e32 v118, 0xbfb8aa3b, v118
	v_mul_f32_e32 v119, 0xbfb8aa3b, v119
	v_rcp_f32_e32 v117, v117
	v_exp_f32_e32 v118, v118
	v_exp_f32_e32 v119, v119
	v_and_b32_e32 v120, 0xffff0000, v153
	v_mul_f32_e32 v113, v117, v113
	v_add_f32_e32 v117, 1.0, v118
	v_add_f32_e32 v118, 1.0, v119
	v_lshlrev_b32_e32 v119, 16, v153
	v_mul_f32_e32 v119, 0xbfb8aa3b, v119
	v_mul_f32_e32 v120, 0xbfb8aa3b, v120
	v_exp_f32_e32 v119, v119
	v_exp_f32_e32 v120, v120
	v_rcp_f32_e32 v117, v117
	v_rcp_f32_e32 v118, v118
	v_add_f32_e32 v119, 1.0, v119
	v_add_f32_e32 v120, 1.0, v120
	v_rcp_f32_e32 v119, v119
	v_rcp_f32_e32 v120, v120
	v_ashrrev_i32_e32 v195, 31, v194
	v_lshlrev_b64 v[114:115], 13, v[194:195]
	v_lshl_add_u64 v[114:115], s[36:37], 0, v[114:115]
	v_lshl_add_u64 v[114:115], v[114:115], 0, v[186:187]
	v_mul_f32_e32 v117, v117, v106
	v_mul_f32_e32 v118, v118, v107
	v_mul_f32_e32 v119, v119, v108
	v_mul_f32_e32 v109, v120, v109
	v_cvt_pk_bf16_f32 v106, v110, v111
	v_cvt_pk_bf16_f32 v107, v112, v113
	v_cvt_pk_bf16_f32 v108, v117, v118
	v_cvt_pk_bf16_f32 v109, v119, v109
	global_store_dwordx4 v[114:115], v[106:109], off sc1
	v_cvt_f32_i32_e32 v103, v103
	v_cvt_f32_i32_e32 v105, v105
	v_and_b32_e32 v107, 0xffff0000, v146
	v_lshlrev_b32_e32 v108, 16, v147
	v_lshlrev_b32_e32 v106, 16, v146
	v_mul_f32_e32 v107, 0xbfb8aa3b, v107
	v_mul_f32_e32 v108, 0xbfb8aa3b, v108
	v_mul_f32_e32 v106, 0xbfb8aa3b, v106
	v_exp_f32_e32 v107, v107
	v_exp_f32_e32 v108, v108
	v_exp_f32_e32 v106, v106
	v_cvt_f32_i32_e32 v104, v104
	v_cvt_f32_i32_e32 v102, v102
	v_add_f32_e32 v107, 1.0, v107
	v_add_f32_e32 v108, 1.0, v108
	v_and_b32_e32 v109, 0xffff0000, v147
	v_add_f32_e32 v106, 1.0, v106
	v_rcp_f32_e32 v107, v107
	v_rcp_f32_e32 v108, v108
	v_mul_f32_e32 v109, 0xbfb8aa3b, v109
	v_rcp_f32_e32 v106, v106
	v_exp_f32_e32 v109, v109
	v_pk_mul_f32 v[104:105], v[72:73], v[104:105]
	v_pk_mul_f32 v[102:103], v[70:71], v[102:103]
	v_pk_mul_f32 v[104:105], v[104:105], v[116:117] op_sel_hi:[1,0]
	v_pk_mul_f32 v[102:103], v[102:103], v[116:117] op_sel_hi:[1,0]
	v_mul_f32_e32 v104, v108, v104
	v_mul_f32_e32 v103, v107, v103
	v_lshlrev_b32_e32 v107, 16, v148
	v_and_b32_e32 v108, 0xffff0000, v148
	v_mul_f32_e32 v102, v106, v102
	v_add_f32_e32 v106, 1.0, v109
	v_mul_f32_e32 v107, 0xbfb8aa3b, v107
	v_mul_f32_e32 v108, 0xbfb8aa3b, v108
	v_rcp_f32_e32 v106, v106
	v_exp_f32_e32 v107, v107
	v_exp_f32_e32 v108, v108
	v_and_b32_e32 v109, 0xffff0000, v149
	v_mul_f32_e32 v105, v106, v105
	v_add_f32_e32 v106, 1.0, v107
	v_add_f32_e32 v107, 1.0, v108
	v_lshlrev_b32_e32 v108, 16, v149
	v_mul_f32_e32 v108, 0xbfb8aa3b, v108
	v_mul_f32_e32 v109, 0xbfb8aa3b, v109
	v_exp_f32_e32 v108, v108
	v_exp_f32_e32 v109, v109
	v_cvt_f32_i32_e32 v101, v101
	v_cvt_f32_i32_e32 v100, v100
	v_cvt_f32_i32_e32 v99, v99
	v_cvt_f32_i32_e32 v98, v98
	v_add_f32_e32 v108, 1.0, v108
	v_add_f32_e32 v109, 1.0, v109
	v_rcp_f32_e32 v106, v106
	v_rcp_f32_e32 v107, v107
	v_rcp_f32_e32 v108, v108
	v_rcp_f32_e32 v109, v109
	v_pk_mul_f32 v[100:101], v[68:69], v[100:101]
	v_pk_mul_f32 v[98:99], v[66:67], v[98:99]
	v_pk_mul_f32 v[100:101], v[100:101], v[116:117] op_sel_hi:[1,0]
	v_pk_mul_f32 v[98:99], v[98:99], v[116:117] op_sel_hi:[1,0]
	v_mul_f32_e32 v108, v108, v100
	v_mul_f32_e32 v106, v106, v98
	v_mul_f32_e32 v107, v107, v99
	v_mul_f32_e32 v101, v109, v101
	v_cvt_pk_bf16_f32 v98, v102, v103
	v_cvt_pk_bf16_f32 v99, v104, v105
	v_cvt_pk_bf16_f32 v100, v106, v107
	v_cvt_pk_bf16_f32 v101, v108, v101
	global_store_dwordx4 v[114:115], v[98:101], off offset:256 sc1
	ds_read_b32 v100, v189 offset:1216
	v_cvt_f32_i32_e32 v95, v95
	v_cvt_f32_i32_e32 v97, v97
	v_cvt_f32_i32_e32 v96, v96
	v_cvt_f32_i32_e32 v94, v94
	v_and_b32_e32 v102, 0xffff0000, v142
	v_lshlrev_b32_e32 v103, 16, v143
	v_pk_mul_f32 v[96:97], v[88:89], v[96:97]
	v_pk_mul_f32 v[94:95], v[86:87], v[94:95]
	s_waitcnt lgkmcnt(0)
; __device__ __forceinline__ unsigned cvt_pk_bf16(float lo, float hi) { unsigned r; asm volatile("v_cvt_pk_bf16_f32 %0, %1, %2" : "=v"(r) : "v"(lo), "v"(hi)); return r; }
; __device__ __forceinline__ float bf_lo(unsigned w) { return __uint_as_float(w << 16); }
; __device__ __forceinline__ float bf_hi(unsigned w) { return __uint_as_float(w & 0xffff0000u); }
; __device__ __forceinline__ float sigmoidf_(float x) { return fast_rcp(1.0f + fast_exp(-x)); }
;     __device__ __forceinline__ void operator()(const i32x4 (&acc)[2][2][4][2], const Unit& u, int wr, int wc, int fr, int fq, const PG8_LAS float* sb) const {
;     ...
;         for (int ai = 0; ai < 2; ++ai) {
;             u32x4 g[4][2];
; #pragma unroll
;             for (int m = 0; m < 4; ++m) { const size_t row = (size_t)(row0 + ai * HALF + m * 16);
; #pragma unroll
;                 for (int bj = 0; bj < 2; ++bj) g[m][bj] = *(const u32x4*)(Gt + row * ldg + col0 + bj * HALF); }
;             asm volatile("" ::: "memory");
; #pragma unroll
;             for (int m = 0; m < 4; ++m) { const size_t row = (size_t)(row0 + ai * HALF + m * 16); bf16_t* rowp = O + row * ldc + col0; const float r = sb[256 + wr * 64 + fr + ai * HALF + m * 16];
; #pragma unroll
;                 for (int bj = 0; bj < 2; ++bj) { const u32x4 gg = g[m][bj];
;                     const f32x4 v0 = __builtin_convertvector(acc[ai][bj][m][0], f32x4) * sv[bj][0] * r, v1 = __builtin_convertvector(acc[ai][bj][m][1], f32x4) * sv[bj][1] * r;
;                     float o[8];
;                     o[0] = sigmoidf_(bf_lo(gg.x)) * v0[0]; o[1] = sigmoidf_(bf_hi(gg.x)) * v0[1]; o[2] = sigmoidf_(bf_lo(gg.y)) * v0[2]; o[3] = sigmoidf_(bf_hi(gg.y)) * v0[3];
;                     o[4] = sigmoidf_(bf_lo(gg.z)) * v1[0]; o[5] = sigmoidf_(bf_hi(gg.z)) * v1[1]; o[6] = sigmoidf_(bf_lo(gg.w)) * v1[2]; o[7] = sigmoidf_(bf_hi(gg.w)) * v1[3];
;                     u32x4 w; w.x = cvt_pk_bf16(o[0], o[1]); w.y = cvt_pk_bf16(o[2], o[3]); w.z = cvt_pk_bf16(o[4], o[5]); w.w = cvt_pk_bf16(o[6], o[7]);
;                     *(u32x4*)(rowp + bj * HALF) = w; } }
	v_pk_mul_f32 v[96:97], v[96:97], v[100:101] op_sel_hi:[1,0]
	v_pk_mul_f32 v[94:95], v[94:95], v[100:101] op_sel_hi:[1,0]
	v_lshlrev_b32_e32 v101, 16, v142
	v_mul_f32_e32 v102, 0xbfb8aa3b, v102
	v_mul_f32_e32 v103, 0xbfb8aa3b, v103
	v_cvt_f32_i32_e32 v93, v93
	v_cvt_f32_i32_e32 v92, v92
	v_cvt_f32_i32_e32 v91, v91
	v_cvt_f32_i32_e32 v90, v90
	v_mul_f32_e32 v101, 0xbfb8aa3b, v101
	v_exp_f32_e32 v102, v102
	v_exp_f32_e32 v103, v103
	v_exp_f32_e32 v101, v101
	v_pk_mul_f32 v[92:93], v[84:85], v[92:93]
	v_pk_mul_f32 v[90:91], v[82:83], v[90:91]
	v_add_f32_e32 v102, 1.0, v102
	v_add_f32_e32 v103, 1.0, v103
	v_and_b32_e32 v104, 0xffff0000, v143
	v_pk_mul_f32 v[92:93], v[92:93], v[100:101] op_sel_hi:[1,0]
	v_pk_mul_f32 v[90:91], v[90:91], v[100:101] op_sel_hi:[1,0]
	v_add_f32_e32 v101, 1.0, v101
	v_rcp_f32_e32 v102, v102
	v_rcp_f32_e32 v103, v103
	v_mul_f32_e32 v104, 0xbfb8aa3b, v104
	v_rcp_f32_e32 v101, v101
	v_exp_f32_e32 v104, v104
	v_mul_f32_e32 v95, v102, v95
	v_mul_f32_e32 v96, v103, v96
	v_lshlrev_b32_e32 v102, 16, v144
	v_and_b32_e32 v103, 0xffff0000, v144
	v_mul_f32_e32 v94, v101, v94
	v_add_f32_e32 v101, 1.0, v104
	v_mul_f32_e32 v102, 0xbfb8aa3b, v102
	v_mul_f32_e32 v103, 0xbfb8aa3b, v103
	v_rcp_f32_e32 v101, v101
	v_exp_f32_e32 v102, v102
	v_exp_f32_e32 v103, v103
	v_and_b32_e32 v104, 0xffff0000, v145
	v_mul_f32_e32 v97, v101, v97
	v_add_f32_e32 v101, 1.0, v102
	v_add_f32_e32 v102, 1.0, v103
	v_lshlrev_b32_e32 v103, 16, v145
	v_mul_f32_e32 v103, 0xbfb8aa3b, v103
	v_mul_f32_e32 v104, 0xbfb8aa3b, v104
	v_exp_f32_e32 v103, v103
	v_exp_f32_e32 v104, v104
	v_rcp_f32_e32 v101, v101
	v_rcp_f32_e32 v102, v102
	v_add_f32_e32 v103, 1.0, v103
	v_add_f32_e32 v104, 1.0, v104
	v_rcp_f32_e32 v103, v103
	v_rcp_f32_e32 v104, v104
	v_ashrrev_i32_e32 v193, 31, v192
	v_lshlrev_b64 v[98:99], 13, v[192:193]
	v_lshl_add_u64 v[98:99], s[36:37], 0, v[98:99]
	v_lshl_add_u64 v[98:99], v[98:99], 0, v[186:187]
	v_mul_f32_e32 v101, v101, v90
	v_mul_f32_e32 v102, v102, v91
	v_mul_f32_e32 v103, v103, v92
	v_mul_f32_e32 v93, v104, v93
	v_cvt_pk_bf16_f32 v90, v94, v95
	v_cvt_pk_bf16_f32 v91, v96, v97
	v_cvt_pk_bf16_f32 v92, v101, v102
	v_cvt_pk_bf16_f32 v93, v103, v93
	global_store_dwordx4 v[98:99], v[90:93], off sc1
	v_cvt_f32_i32_e32 v79, v79
	v_cvt_f32_i32_e32 v81, v81
	v_and_b32_e32 v91, 0xffff0000, v138
	v_lshlrev_b32_e32 v92, 16, v139
	v_lshlrev_b32_e32 v90, 16, v138
	v_mul_f32_e32 v91, 0xbfb8aa3b, v91
	v_mul_f32_e32 v92, 0xbfb8aa3b, v92
	v_mul_f32_e32 v90, 0xbfb8aa3b, v90
	v_exp_f32_e32 v91, v91
	v_exp_f32_e32 v92, v92
	v_exp_f32_e32 v90, v90
	v_cvt_f32_i32_e32 v80, v80
	v_cvt_f32_i32_e32 v78, v78
	v_add_f32_e32 v91, 1.0, v91
	v_add_f32_e32 v92, 1.0, v92
	v_and_b32_e32 v93, 0xffff0000, v139
	v_add_f32_e32 v90, 1.0, v90
	v_rcp_f32_e32 v91, v91
	v_rcp_f32_e32 v92, v92
	v_mul_f32_e32 v93, 0xbfb8aa3b, v93
	v_rcp_f32_e32 v90, v90
	v_exp_f32_e32 v93, v93
	v_pk_mul_f32 v[80:81], v[72:73], v[80:81]
	v_pk_mul_f32 v[78:79], v[70:71], v[78:79]
	v_pk_mul_f32 v[80:81], v[80:81], v[100:101] op_sel_hi:[1,0]
	v_pk_mul_f32 v[78:79], v[78:79], v[100:101] op_sel_hi:[1,0]
	v_mul_f32_e32 v80, v92, v80
	v_mul_f32_e32 v79, v91, v79
	v_lshlrev_b32_e32 v91, 16, v140
	v_and_b32_e32 v92, 0xffff0000, v140
	v_mul_f32_e32 v78, v90, v78
	v_add_f32_e32 v90, 1.0, v93
	v_mul_f32_e32 v91, 0xbfb8aa3b, v91
	v_mul_f32_e32 v92, 0xbfb8aa3b, v92
	v_rcp_f32_e32 v90, v90
	v_exp_f32_e32 v91, v91
	v_exp_f32_e32 v92, v92
	v_and_b32_e32 v93, 0xffff0000, v141
	v_mul_f32_e32 v81, v90, v81
	v_add_f32_e32 v90, 1.0, v91
	v_add_f32_e32 v91, 1.0, v92
	v_lshlrev_b32_e32 v92, 16, v141
	v_mul_f32_e32 v93, 0xbfb8aa3b, v93
	v_mul_f32_e32 v92, 0xbfb8aa3b, v92
	v_exp_f32_e32 v93, v93
	v_exp_f32_e32 v92, v92
	v_cvt_f32_i32_e32 v77, v77
	v_cvt_f32_i32_e32 v76, v76
	v_cvt_f32_i32_e32 v75, v75
	v_cvt_f32_i32_e32 v74, v74
	v_add_f32_e32 v93, 1.0, v93
	v_add_f32_e32 v92, 1.0, v92
	v_rcp_f32_e32 v93, v93
	v_rcp_f32_e32 v90, v90
	v_rcp_f32_e32 v91, v91
	v_rcp_f32_e32 v92, v92
	v_pk_mul_f32 v[76:77], v[68:69], v[76:77]
	v_pk_mul_f32 v[74:75], v[66:67], v[74:75]
	v_pk_mul_f32 v[76:77], v[76:77], v[100:101] op_sel_hi:[1,0]
	v_pk_mul_f32 v[74:75], v[74:75], v[100:101] op_sel_hi:[1,0]
	v_mul_f32_e32 v77, v93, v77
	v_mul_f32_e32 v90, v90, v74
	v_mul_f32_e32 v91, v91, v75
	v_mul_f32_e32 v92, v92, v76
	v_cvt_pk_bf16_f32 v74, v78, v79
	v_cvt_pk_bf16_f32 v75, v80, v81
	v_cvt_pk_bf16_f32 v76, v90, v91
	v_cvt_pk_bf16_f32 v77, v92, v77
	global_store_dwordx4 v[98:99], v[74:77], off offset:256 sc1
	v_add_u32_e32 v118, 0x80, v188
	v_add_u32_e32 v120, 0x90, v188
	v_mad_i64_i32 v[74:75], s[26:27], v118, s21, v[190:191]
	global_load_dwordx4 v[110:113], v[74:75], off
	global_load_dwordx4 v[114:117], v[74:75], off offset:256
	v_mad_i64_i32 v[74:75], s[26:27], v120, s21, v[190:191]
	global_load_dwordx4 v[102:105], v[74:75], off
	global_load_dwordx4 v[98:101], v[74:75], off offset:256
	v_add_u32_e32 v108, 0xa0, v188
	v_mad_i64_i32 v[74:75], s[26:27], v108, s21, v[190:191]
	v_add_u32_e32 v106, 0xb0, v188
	global_load_dwordx4 v[94:97], v[74:75], off
	global_load_dwordx4 v[90:93], v[74:75], off offset:256
	v_mad_i64_i32 v[74:75], s[26:27], v106, s21, v[190:191]
	global_load_dwordx4 v[78:81], v[74:75], off
	s_nop 0
	global_load_dwordx4 v[74:77], v[74:75], off offset:256
	ds_read_b32 v122, v189 offset:1536
	v_cvt_f32_i32_e32 v63, v63
	v_cvt_f32_i32_e32 v65, v65
	v_cvt_f32_i32_e32 v64, v64
	v_cvt_f32_i32_e32 v62, v62
	v_cvt_f32_i32_e32 v61, v61
	v_cvt_f32_i32_e32 v60, v60
	v_pk_mul_f32 v[64:65], v[88:89], v[64:65]
	v_pk_mul_f32 v[62:63], v[86:87], v[62:63]
	s_waitcnt lgkmcnt(0)
; __device__ __forceinline__ unsigned cvt_pk_bf16(float lo, float hi) { unsigned r; asm volatile("v_cvt_pk_bf16_f32 %0, %1, %2" : "=v"(r) : "v"(lo), "v"(hi)); return r; }
; __device__ __forceinline__ float bf_lo(unsigned w) { return __uint_as_float(w << 16); }
; __device__ __forceinline__ float bf_hi(unsigned w) { return __uint_as_float(w & 0xffff0000u); }
; __device__ __forceinline__ float sigmoidf_(float x) { return fast_rcp(1.0f + fast_exp(-x)); }
;     __device__ __forceinline__ void operator()(const i32x4 (&acc)[2][2][4][2], const Unit& u, int wr, int wc, int fr, int fq, const PG8_LAS float* sb) const {
;     ...
;             for (int m = 0; m < 4; ++m) { const size_t row = (size_t)(row0 + ai * HALF + m * 16); bf16_t* rowp = O + row * ldc + col0; const float r = sb[256 + wr * 64 + fr + ai * HALF + m * 16];
; #pragma unroll
;                 for (int bj = 0; bj < 2; ++bj) { const u32x4 gg = g[m][bj];
;                     const f32x4 v0 = __builtin_convertvector(acc[ai][bj][m][0], f32x4) * sv[bj][0] * r, v1 = __builtin_convertvector(acc[ai][bj][m][1], f32x4) * sv[bj][1] * r;
;                     float o[8];
;                     o[0] = sigmoidf_(bf_lo(gg.x)) * v0[0]; o[1] = sigmoidf_(bf_hi(gg.x)) * v0[1]; o[2] = sigmoidf_(bf_lo(gg.y)) * v0[2]; o[3] = sigmoidf_(bf_hi(gg.y)) * v0[3];
;                     o[4] = sigmoidf_(bf_lo(gg.z)) * v1[0]; o[5] = sigmoidf_(bf_hi(gg.z)) * v1[1]; o[6] = sigmoidf_(bf_lo(gg.w)) * v1[2]; o[7] = sigmoidf_(bf_hi(gg.w)) * v1[3];
;                     u32x4 w; w.x = cvt_pk_bf16(o[0], o[1]); w.y = cvt_pk_bf16(o[2], o[3]); w.z = cvt_pk_bf16(o[4], o[5]); w.w = cvt_pk_bf16(o[6], o[7]);
;                     *(u32x4*)(rowp + bj * HALF) = w; } }
	v_pk_mul_f32 v[64:65], v[64:65], v[122:123] op_sel_hi:[1,0]
	v_pk_mul_f32 v[62:63], v[62:63], v[122:123] op_sel_hi:[1,0]
	v_cvt_f32_i32_e32 v59, v59
	v_cvt_f32_i32_e32 v58, v58
	v_pk_mul_f32 v[60:61], v[84:85], v[60:61]
	v_ashrrev_i32_e32 v119, 31, v118
	v_lshlrev_b64 v[118:119], 13, v[118:119]
	v_pk_mul_f32 v[58:59], v[82:83], v[58:59]
	v_lshl_add_u64 v[118:119], s[36:37], 0, v[118:119]
	v_lshl_add_u64 v[118:119], v[118:119], 0, v[186:187]
	v_cvt_f32_i32_e32 v55, v55
	v_cvt_f32_i32_e32 v57, v57
	v_cvt_f32_i32_e32 v56, v56
	v_cvt_f32_i32_e32 v54, v54
	v_cvt_f32_i32_e32 v53, v53
	v_cvt_f32_i32_e32 v52, v52
	v_pk_mul_f32 v[56:57], v[72:73], v[56:57]
	v_pk_mul_f32 v[54:55], v[70:71], v[54:55]
	v_cvt_f32_i32_e32 v51, v51
	v_cvt_f32_i32_e32 v50, v50
	v_pk_mul_f32 v[52:53], v[68:69], v[52:53]
	v_cvt_f32_i32_e32 v47, v47
	v_cvt_f32_i32_e32 v49, v49
	v_pk_mul_f32 v[50:51], v[66:67], v[50:51]
	v_cvt_f32_i32_e32 v48, v48
	v_cvt_f32_i32_e32 v46, v46
	v_cvt_f32_i32_e32 v45, v45
	v_cvt_f32_i32_e32 v44, v44
	v_pk_mul_f32 v[48:49], v[88:89], v[48:49]
	v_pk_mul_f32 v[46:47], v[86:87], v[46:47]
	v_cvt_f32_i32_e32 v43, v43
	v_cvt_f32_i32_e32 v42, v42
	v_pk_mul_f32 v[44:45], v[84:85], v[44:45]
	v_ashrrev_i32_e32 v121, 31, v120
	v_cvt_f32_i32_e32 v39, v39
	v_pk_mul_f32 v[42:43], v[82:83], v[42:43]
	v_cvt_f32_i32_e32 v41, v41
	v_cvt_f32_i32_e32 v40, v40
	v_cvt_f32_i32_e32 v38, v38
	v_cvt_f32_i32_e32 v37, v37
	v_cvt_f32_i32_e32 v36, v36
	v_pk_mul_f32 v[40:41], v[72:73], v[40:41]
	v_pk_mul_f32 v[38:39], v[70:71], v[38:39]
	v_cvt_f32_i32_e32 v35, v35
	v_cvt_f32_i32_e32 v34, v34
	v_pk_mul_f32 v[36:37], v[68:69], v[36:37]
	v_cvt_f32_i32_e32 v31, v31
	v_cvt_f32_i32_e32 v33, v33
	v_pk_mul_f32 v[34:35], v[66:67], v[34:35]
	v_cvt_f32_i32_e32 v32, v32
	v_cvt_f32_i32_e32 v30, v30
	v_cvt_f32_i32_e32 v29, v29
	v_cvt_f32_i32_e32 v28, v28
	v_pk_mul_f32 v[32:33], v[88:89], v[32:33]
	v_pk_mul_f32 v[30:31], v[86:87], v[30:31]
	v_cvt_f32_i32_e32 v27, v27
	v_cvt_f32_i32_e32 v26, v26
	s_waitcnt vmcnt(7)
	v_lshlrev_b32_e32 v123, 16, v110
	v_and_b32_e32 v110, 0xffff0000, v110
	v_mul_f32_e32 v110, 0xbfb8aa3b, v110
	v_exp_f32_e32 v110, v110
	v_lshlrev_b32_e32 v124, 16, v111
	v_and_b32_e32 v111, 0xffff0000, v111
	v_mul_f32_e32 v111, 0xbfb8aa3b, v111
	v_add_f32_e32 v110, 1.0, v110
	v_rcp_f32_e32 v110, v110
	v_exp_f32_e32 v111, v111
	v_mul_f32_e32 v123, 0xbfb8aa3b, v123
	v_mul_f32_e32 v124, 0xbfb8aa3b, v124
	v_mul_f32_e32 v63, v110, v63
	v_add_f32_e32 v110, 1.0, v111
	v_lshlrev_b32_e32 v111, 16, v112
	v_and_b32_e32 v112, 0xffff0000, v112
	v_mul_f32_e32 v111, 0xbfb8aa3b, v111
	v_mul_f32_e32 v112, 0xbfb8aa3b, v112
	v_rcp_f32_e32 v110, v110
	v_exp_f32_e32 v111, v111
	v_exp_f32_e32 v112, v112
	v_exp_f32_e32 v123, v123
	v_mul_f32_e32 v65, v110, v65
	v_add_f32_e32 v110, 1.0, v111
	v_add_f32_e32 v111, 1.0, v112
	v_lshlrev_b32_e32 v112, 16, v113
	v_and_b32_e32 v113, 0xffff0000, v113
	v_mul_f32_e32 v112, 0xbfb8aa3b, v112
	v_mul_f32_e32 v113, 0xbfb8aa3b, v113
	v_exp_f32_e32 v124, v124
	v_exp_f32_e32 v112, v112
	v_exp_f32_e32 v113, v113
	v_pk_mul_f32 v[60:61], v[60:61], v[122:123] op_sel_hi:[1,0]
	v_pk_mul_f32 v[58:59], v[58:59], v[122:123] op_sel_hi:[1,0]
	v_add_f32_e32 v123, 1.0, v123
	v_add_f32_e32 v124, 1.0, v124
	v_add_f32_e32 v112, 1.0, v112
	v_add_f32_e32 v113, 1.0, v113
	v_rcp_f32_e32 v123, v123
	v_rcp_f32_e32 v124, v124
	v_rcp_f32_e32 v110, v110
	v_rcp_f32_e32 v111, v111
	v_rcp_f32_e32 v112, v112
	v_rcp_f32_e32 v113, v113
	v_mul_f32_e32 v62, v123, v62
	v_mul_f32_e32 v64, v124, v64
	v_mul_f32_e32 v110, v110, v58
	v_mul_f32_e32 v111, v111, v59
	v_mul_f32_e32 v112, v112, v60
	v_mul_f32_e32 v61, v113, v61
	v_cvt_pk_bf16_f32 v58, v62, v63
	v_cvt_pk_bf16_f32 v59, v64, v65
	v_cvt_pk_bf16_f32 v60, v110, v111
	v_cvt_pk_bf16_f32 v61, v112, v61
	global_store_dwordx4 v[118:119], v[58:61], off sc1
	v_pk_mul_f32 v[56:57], v[56:57], v[122:123] op_sel_hi:[1,0]
	v_pk_mul_f32 v[54:55], v[54:55], v[122:123] op_sel_hi:[1,0]
	s_waitcnt vmcnt(7)
	v_and_b32_e32 v59, 0xffff0000, v114
	v_lshlrev_b32_e32 v60, 16, v115
	v_lshlrev_b32_e32 v58, 16, v114
	v_mul_f32_e32 v59, 0xbfb8aa3b, v59
	v_mul_f32_e32 v60, 0xbfb8aa3b, v60
	v_mul_f32_e32 v58, 0xbfb8aa3b, v58
	v_exp_f32_e32 v59, v59
	v_exp_f32_e32 v60, v60
	v_exp_f32_e32 v58, v58
	v_and_b32_e32 v61, 0xffff0000, v115
	v_add_f32_e32 v59, 1.0, v59
	v_add_f32_e32 v60, 1.0, v60
	v_add_f32_e32 v58, 1.0, v58
	v_rcp_f32_e32 v59, v59
	v_rcp_f32_e32 v60, v60
	v_mul_f32_e32 v61, 0xbfb8aa3b, v61
	v_rcp_f32_e32 v58, v58
	v_exp_f32_e32 v61, v61
	v_mul_f32_e32 v55, v59, v55
	v_mul_f32_e32 v56, v60, v56
	v_lshlrev_b32_e32 v59, 16, v116
	v_and_b32_e32 v60, 0xffff0000, v116
	v_mul_f32_e32 v54, v58, v54
	v_add_f32_e32 v58, 1.0, v61
	v_mul_f32_e32 v59, 0xbfb8aa3b, v59
	v_mul_f32_e32 v60, 0xbfb8aa3b, v60
	v_rcp_f32_e32 v58, v58
	v_exp_f32_e32 v59, v59
	v_exp_f32_e32 v60, v60
	v_and_b32_e32 v61, 0xffff0000, v117
	v_mul_f32_e32 v57, v58, v57
	v_add_f32_e32 v58, 1.0, v59
	v_add_f32_e32 v59, 1.0, v60
	v_lshlrev_b32_e32 v60, 16, v117
	v_mul_f32_e32 v60, 0xbfb8aa3b, v60
	v_mul_f32_e32 v61, 0xbfb8aa3b, v61
	v_exp_f32_e32 v60, v60
	v_exp_f32_e32 v61, v61
	v_rcp_f32_e32 v58, v58
	v_rcp_f32_e32 v59, v59
	v_add_f32_e32 v60, 1.0, v60
	v_add_f32_e32 v61, 1.0, v61
	v_rcp_f32_e32 v60, v60
	v_rcp_f32_e32 v61, v61
	v_pk_mul_f32 v[52:53], v[52:53], v[122:123] op_sel_hi:[1,0]
	v_pk_mul_f32 v[50:51], v[50:51], v[122:123] op_sel_hi:[1,0]
	v_mul_f32_e32 v60, v60, v52
	v_mul_f32_e32 v58, v58, v50
	v_mul_f32_e32 v59, v59, v51
	v_mul_f32_e32 v53, v61, v53
	v_cvt_pk_bf16_f32 v50, v54, v55
	v_cvt_pk_bf16_f32 v51, v56, v57
	v_cvt_pk_bf16_f32 v52, v58, v59
	v_cvt_pk_bf16_f32 v53, v60, v53
	global_store_dwordx4 v[118:119], v[50:53], off offset:256 sc1
	ds_read_b32 v52, v189 offset:1600
	s_waitcnt vmcnt(7)
; __device__ __forceinline__ unsigned cvt_pk_bf16(float lo, float hi) { unsigned r; asm volatile("v_cvt_pk_bf16_f32 %0, %1, %2" : "=v"(r) : "v"(lo), "v"(hi)); return r; }
; __device__ __forceinline__ float bf_lo(unsigned w) { return __uint_as_float(w << 16); }
; __device__ __forceinline__ float bf_hi(unsigned w) { return __uint_as_float(w & 0xffff0000u); }
; __device__ __forceinline__ float sigmoidf_(float x) { return fast_rcp(1.0f + fast_exp(-x)); }
;     __device__ __forceinline__ void operator()(const i32x4 (&acc)[2][2][4][2], const Unit& u, int wr, int wc, int fr, int fq, const PG8_LAS float* sb) const {
;     ...
;             for (int m = 0; m < 4; ++m) { const size_t row = (size_t)(row0 + ai * HALF + m * 16); bf16_t* rowp = O + row * ldc + col0; const float r = sb[256 + wr * 64 + fr + ai * HALF + m * 16];
; #pragma unroll
;                 for (int bj = 0; bj < 2; ++bj) { const u32x4 gg = g[m][bj];
;                     const f32x4 v0 = __builtin_convertvector(acc[ai][bj][m][0], f32x4) * sv[bj][0] * r, v1 = __builtin_convertvector(acc[ai][bj][m][1], f32x4) * sv[bj][1] * r;
;                     float o[8];
;                     o[0] = sigmoidf_(bf_lo(gg.x)) * v0[0]; o[1] = sigmoidf_(bf_hi(gg.x)) * v0[1]; o[2] = sigmoidf_(bf_lo(gg.y)) * v0[2]; o[3] = sigmoidf_(bf_hi(gg.y)) * v0[3];
;                     o[4] = sigmoidf_(bf_lo(gg.z)) * v1[0]; o[5] = sigmoidf_(bf_hi(gg.z)) * v1[1]; o[6] = sigmoidf_(bf_lo(gg.w)) * v1[2]; o[7] = sigmoidf_(bf_hi(gg.w)) * v1[3];
;                     u32x4 w; w.x = cvt_pk_bf16(o[0], o[1]); w.y = cvt_pk_bf16(o[2], o[3]); w.z = cvt_pk_bf16(o[4], o[5]); w.w = cvt_pk_bf16(o[6], o[7]);
;                     *(u32x4*)(rowp + bj * HALF) = w; } }
	v_and_b32_e32 v54, 0xffff0000, v102
	v_lshlrev_b32_e32 v55, 16, v103
	v_mul_f32_e32 v54, 0xbfb8aa3b, v54
	v_mul_f32_e32 v55, 0xbfb8aa3b, v55
	s_waitcnt lgkmcnt(0)
	v_pk_mul_f32 v[48:49], v[48:49], v[52:53] op_sel_hi:[1,0]
	v_pk_mul_f32 v[46:47], v[46:47], v[52:53] op_sel_hi:[1,0]
	v_lshlrev_b32_e32 v53, 16, v102
	v_mul_f32_e32 v53, 0xbfb8aa3b, v53
	v_exp_f32_e32 v54, v54
	v_exp_f32_e32 v55, v55
	v_exp_f32_e32 v53, v53
	v_and_b32_e32 v56, 0xffff0000, v103
	v_add_f32_e32 v54, 1.0, v54
	v_add_f32_e32 v55, 1.0, v55
	v_pk_mul_f32 v[44:45], v[44:45], v[52:53] op_sel_hi:[1,0]
	v_pk_mul_f32 v[42:43], v[42:43], v[52:53] op_sel_hi:[1,0]
	v_add_f32_e32 v53, 1.0, v53
	v_rcp_f32_e32 v54, v54
	v_rcp_f32_e32 v55, v55
	v_mul_f32_e32 v56, 0xbfb8aa3b, v56
	v_rcp_f32_e32 v53, v53
	v_exp_f32_e32 v56, v56
	v_mul_f32_e32 v47, v54, v47
	v_mul_f32_e32 v48, v55, v48
	v_lshlrev_b32_e32 v54, 16, v104
	v_and_b32_e32 v55, 0xffff0000, v104
	v_mul_f32_e32 v46, v53, v46
	v_add_f32_e32 v53, 1.0, v56
	v_mul_f32_e32 v54, 0xbfb8aa3b, v54
	v_mul_f32_e32 v55, 0xbfb8aa3b, v55
	v_rcp_f32_e32 v53, v53
	v_exp_f32_e32 v54, v54
	v_exp_f32_e32 v55, v55
	v_and_b32_e32 v56, 0xffff0000, v105
	v_mul_f32_e32 v49, v53, v49
	v_add_f32_e32 v53, 1.0, v54
	v_add_f32_e32 v54, 1.0, v55
	v_lshlrev_b32_e32 v55, 16, v105
	v_mul_f32_e32 v55, 0xbfb8aa3b, v55
	v_mul_f32_e32 v56, 0xbfb8aa3b, v56
	v_exp_f32_e32 v55, v55
	v_exp_f32_e32 v56, v56
	v_rcp_f32_e32 v53, v53
	v_rcp_f32_e32 v54, v54
	v_add_f32_e32 v55, 1.0, v55
	v_add_f32_e32 v56, 1.0, v56
	v_rcp_f32_e32 v55, v55
	v_rcp_f32_e32 v56, v56
	v_lshlrev_b64 v[50:51], 13, v[120:121]
	v_lshl_add_u64 v[50:51], s[36:37], 0, v[50:51]
	v_lshl_add_u64 v[50:51], v[50:51], 0, v[186:187]
	v_mul_f32_e32 v53, v53, v42
	v_mul_f32_e32 v54, v54, v43
	v_mul_f32_e32 v55, v55, v44
	v_mul_f32_e32 v45, v56, v45
	v_cvt_pk_bf16_f32 v42, v46, v47
	v_cvt_pk_bf16_f32 v43, v48, v49
	v_cvt_pk_bf16_f32 v44, v53, v54
	v_cvt_pk_bf16_f32 v45, v55, v45
	global_store_dwordx4 v[50:51], v[42:45], off sc1
	v_pk_mul_f32 v[40:41], v[40:41], v[52:53] op_sel_hi:[1,0]
	v_pk_mul_f32 v[38:39], v[38:39], v[52:53] op_sel_hi:[1,0]
	s_waitcnt vmcnt(7)
	v_and_b32_e32 v43, 0xffff0000, v98
	v_lshlrev_b32_e32 v44, 16, v99
	v_lshlrev_b32_e32 v42, 16, v98
	v_mul_f32_e32 v43, 0xbfb8aa3b, v43
	v_mul_f32_e32 v44, 0xbfb8aa3b, v44
	v_mul_f32_e32 v42, 0xbfb8aa3b, v42
	v_exp_f32_e32 v43, v43
	v_exp_f32_e32 v44, v44
	v_exp_f32_e32 v42, v42
	v_and_b32_e32 v45, 0xffff0000, v99
	v_add_f32_e32 v43, 1.0, v43
	v_add_f32_e32 v44, 1.0, v44
	v_add_f32_e32 v42, 1.0, v42
	v_rcp_f32_e32 v43, v43
	v_rcp_f32_e32 v44, v44
	v_mul_f32_e32 v45, 0xbfb8aa3b, v45
	v_rcp_f32_e32 v42, v42
	v_exp_f32_e32 v45, v45
	v_mul_f32_e32 v39, v43, v39
	v_mul_f32_e32 v40, v44, v40
	v_lshlrev_b32_e32 v43, 16, v100
	v_and_b32_e32 v44, 0xffff0000, v100
	v_mul_f32_e32 v38, v42, v38
	v_add_f32_e32 v42, 1.0, v45
	v_mul_f32_e32 v43, 0xbfb8aa3b, v43
	v_mul_f32_e32 v44, 0xbfb8aa3b, v44
	v_rcp_f32_e32 v42, v42
	v_exp_f32_e32 v43, v43
	v_exp_f32_e32 v44, v44
	v_and_b32_e32 v45, 0xffff0000, v101
	v_mul_f32_e32 v41, v42, v41
	v_add_f32_e32 v42, 1.0, v43
	v_add_f32_e32 v43, 1.0, v44
	v_lshlrev_b32_e32 v44, 16, v101
	v_mul_f32_e32 v44, 0xbfb8aa3b, v44
	v_mul_f32_e32 v45, 0xbfb8aa3b, v45
	v_exp_f32_e32 v44, v44
	v_exp_f32_e32 v45, v45
	v_rcp_f32_e32 v42, v42
	v_rcp_f32_e32 v43, v43
	v_add_f32_e32 v44, 1.0, v44
	v_add_f32_e32 v45, 1.0, v45
	v_rcp_f32_e32 v44, v44
	v_rcp_f32_e32 v45, v45
	v_pk_mul_f32 v[36:37], v[36:37], v[52:53] op_sel_hi:[1,0]
	v_pk_mul_f32 v[34:35], v[34:35], v[52:53] op_sel_hi:[1,0]
	v_mul_f32_e32 v44, v44, v36
	v_mul_f32_e32 v42, v42, v34
	v_mul_f32_e32 v43, v43, v35
	v_mul_f32_e32 v37, v45, v37
	v_cvt_pk_bf16_f32 v34, v38, v39
	v_cvt_pk_bf16_f32 v35, v40, v41
	v_cvt_pk_bf16_f32 v36, v42, v43
	v_cvt_pk_bf16_f32 v37, v44, v37
	global_store_dwordx4 v[50:51], v[34:37], off offset:256 sc1
	ds_read_b32 v36, v189 offset:1664
	s_waitcnt vmcnt(7)
	v_and_b32_e32 v38, 0xffff0000, v94
	v_lshlrev_b32_e32 v39, 16, v95
	v_mul_f32_e32 v38, 0xbfb8aa3b, v38
	v_mul_f32_e32 v39, 0xbfb8aa3b, v39
	s_waitcnt lgkmcnt(0)
	v_pk_mul_f32 v[32:33], v[32:33], v[36:37] op_sel_hi:[1,0]
	v_pk_mul_f32 v[30:31], v[30:31], v[36:37] op_sel_hi:[1,0]
	v_lshlrev_b32_e32 v37, 16, v94
	v_mul_f32_e32 v37, 0xbfb8aa3b, v37
	v_exp_f32_e32 v38, v38
	v_exp_f32_e32 v39, v39
	v_exp_f32_e32 v37, v37
	v_pk_mul_f32 v[28:29], v[84:85], v[28:29]
	v_pk_mul_f32 v[26:27], v[82:83], v[26:27]
	v_add_f32_e32 v38, 1.0, v38
	v_add_f32_e32 v39, 1.0, v39
	v_and_b32_e32 v40, 0xffff0000, v95
	v_pk_mul_f32 v[28:29], v[28:29], v[36:37] op_sel_hi:[1,0]
	v_pk_mul_f32 v[26:27], v[26:27], v[36:37] op_sel_hi:[1,0]
	v_add_f32_e32 v37, 1.0, v37
	v_rcp_f32_e32 v38, v38
	v_rcp_f32_e32 v39, v39
	v_mul_f32_e32 v40, 0xbfb8aa3b, v40
	v_rcp_f32_e32 v37, v37
	v_exp_f32_e32 v40, v40
	v_mul_f32_e32 v31, v38, v31
	v_mul_f32_e32 v32, v39, v32
	v_lshlrev_b32_e32 v38, 16, v96
	v_and_b32_e32 v39, 0xffff0000, v96
	v_mul_f32_e32 v30, v37, v30
	v_add_f32_e32 v37, 1.0, v40
	v_mul_f32_e32 v38, 0xbfb8aa3b, v38
	v_mul_f32_e32 v39, 0xbfb8aa3b, v39
	v_rcp_f32_e32 v37, v37
	v_exp_f32_e32 v38, v38
	v_exp_f32_e32 v39, v39
	v_and_b32_e32 v40, 0xffff0000, v97
	v_mul_f32_e32 v33, v37, v33
	v_add_f32_e32 v37, 1.0, v38
	v_add_f32_e32 v38, 1.0, v39
	v_lshlrev_b32_e32 v39, 16, v97
	v_mul_f32_e32 v39, 0xbfb8aa3b, v39
	v_mul_f32_e32 v40, 0xbfb8aa3b, v40
	v_exp_f32_e32 v39, v39
	v_exp_f32_e32 v40, v40
	v_rcp_f32_e32 v37, v37
	v_rcp_f32_e32 v38, v38
	v_add_f32_e32 v39, 1.0, v39
	v_add_f32_e32 v40, 1.0, v40
	v_rcp_f32_e32 v39, v39
	v_rcp_f32_e32 v40, v40
	v_ashrrev_i32_e32 v109, 31, v108
	v_lshlrev_b64 v[34:35], 13, v[108:109]
	v_lshl_add_u64 v[34:35], s[36:37], 0, v[34:35]
	v_lshl_add_u64 v[34:35], v[34:35], 0, v[186:187]
	v_mul_f32_e32 v37, v37, v26
	v_mul_f32_e32 v38, v38, v27
	v_mul_f32_e32 v39, v39, v28
	v_mul_f32_e32 v29, v40, v29
	v_cvt_pk_bf16_f32 v26, v30, v31
	v_cvt_pk_bf16_f32 v27, v32, v33
	v_cvt_pk_bf16_f32 v28, v37, v38
	v_cvt_pk_bf16_f32 v29, v39, v29
	global_store_dwordx4 v[34:35], v[26:29], off sc1
	v_cvt_f32_i32_e32 v23, v23
	v_cvt_f32_i32_e32 v25, v25
	s_waitcnt vmcnt(7)
; __device__ __forceinline__ unsigned cvt_pk_bf16(float lo, float hi) { unsigned r; asm volatile("v_cvt_pk_bf16_f32 %0, %1, %2" : "=v"(r) : "v"(lo), "v"(hi)); return r; }
; __device__ __forceinline__ float bf_lo(unsigned w) { return __uint_as_float(w << 16); }
; __device__ __forceinline__ float bf_hi(unsigned w) { return __uint_as_float(w & 0xffff0000u); }
; __device__ __forceinline__ float sigmoidf_(float x) { return fast_rcp(1.0f + fast_exp(-x)); }
;     __device__ __forceinline__ void operator()(const i32x4 (&acc)[2][2][4][2], const Unit& u, int wr, int wc, int fr, int fq, const PG8_LAS float* sb) const {
;     ...
;             for (int m = 0; m < 4; ++m) { const size_t row = (size_t)(row0 + ai * HALF + m * 16); bf16_t* rowp = O + row * ldc + col0; const float r = sb[256 + wr * 64 + fr + ai * HALF + m * 16];
; #pragma unroll
;                 for (int bj = 0; bj < 2; ++bj) { const u32x4 gg = g[m][bj];
;                     const f32x4 v0 = __builtin_convertvector(acc[ai][bj][m][0], f32x4) * sv[bj][0] * r, v1 = __builtin_convertvector(acc[ai][bj][m][1], f32x4) * sv[bj][1] * r;
;                     float o[8];
;                     o[0] = sigmoidf_(bf_lo(gg.x)) * v0[0]; o[1] = sigmoidf_(bf_hi(gg.x)) * v0[1]; o[2] = sigmoidf_(bf_lo(gg.y)) * v0[2]; o[3] = sigmoidf_(bf_hi(gg.y)) * v0[3];
;                     o[4] = sigmoidf_(bf_lo(gg.z)) * v1[0]; o[5] = sigmoidf_(bf_hi(gg.z)) * v1[1]; o[6] = sigmoidf_(bf_lo(gg.w)) * v1[2]; o[7] = sigmoidf_(bf_hi(gg.w)) * v1[3];
;                     u32x4 w; w.x = cvt_pk_bf16(o[0], o[1]); w.y = cvt_pk_bf16(o[2], o[3]); w.z = cvt_pk_bf16(o[4], o[5]); w.w = cvt_pk_bf16(o[6], o[7]);
;                     *(u32x4*)(rowp + bj * HALF) = w; } }
;             asm volatile("" ::: "memory");
;         }
	v_and_b32_e32 v27, 0xffff0000, v90
	v_lshlrev_b32_e32 v28, 16, v91
	v_lshlrev_b32_e32 v26, 16, v90
	v_mul_f32_e32 v27, 0xbfb8aa3b, v27
	v_mul_f32_e32 v28, 0xbfb8aa3b, v28
	v_mul_f32_e32 v26, 0xbfb8aa3b, v26
	v_exp_f32_e32 v27, v27
	v_exp_f32_e32 v28, v28
	v_exp_f32_e32 v26, v26
	v_cvt_f32_i32_e32 v24, v24
	v_cvt_f32_i32_e32 v22, v22
	v_add_f32_e32 v27, 1.0, v27
	v_add_f32_e32 v28, 1.0, v28
	v_and_b32_e32 v29, 0xffff0000, v91
	v_add_f32_e32 v26, 1.0, v26
	v_rcp_f32_e32 v27, v27
	v_rcp_f32_e32 v28, v28
	v_mul_f32_e32 v29, 0xbfb8aa3b, v29
	v_rcp_f32_e32 v26, v26
	v_exp_f32_e32 v29, v29
	v_pk_mul_f32 v[24:25], v[72:73], v[24:25]
	v_pk_mul_f32 v[22:23], v[70:71], v[22:23]
	v_pk_mul_f32 v[24:25], v[24:25], v[36:37] op_sel_hi:[1,0]
	v_pk_mul_f32 v[22:23], v[22:23], v[36:37] op_sel_hi:[1,0]
	v_mul_f32_e32 v24, v28, v24
	v_mul_f32_e32 v23, v27, v23
	v_lshlrev_b32_e32 v27, 16, v92
	v_and_b32_e32 v28, 0xffff0000, v92
	v_mul_f32_e32 v22, v26, v22
	v_add_f32_e32 v26, 1.0, v29
	v_mul_f32_e32 v27, 0xbfb8aa3b, v27
	v_mul_f32_e32 v28, 0xbfb8aa3b, v28
	v_rcp_f32_e32 v26, v26
	v_exp_f32_e32 v27, v27
	v_exp_f32_e32 v28, v28
	v_and_b32_e32 v29, 0xffff0000, v93
	v_mul_f32_e32 v25, v26, v25
	v_add_f32_e32 v26, 1.0, v27
	v_add_f32_e32 v27, 1.0, v28
	v_lshlrev_b32_e32 v28, 16, v93
	v_mul_f32_e32 v28, 0xbfb8aa3b, v28
	v_mul_f32_e32 v29, 0xbfb8aa3b, v29
	v_exp_f32_e32 v28, v28
	v_exp_f32_e32 v29, v29
	v_cvt_f32_i32_e32 v21, v21
	v_cvt_f32_i32_e32 v20, v20
	v_cvt_f32_i32_e32 v19, v19
	v_cvt_f32_i32_e32 v18, v18
	v_add_f32_e32 v28, 1.0, v28
	v_add_f32_e32 v29, 1.0, v29
	v_rcp_f32_e32 v26, v26
	v_rcp_f32_e32 v27, v27
	v_rcp_f32_e32 v28, v28
	v_rcp_f32_e32 v29, v29
	v_pk_mul_f32 v[20:21], v[68:69], v[20:21]
	v_pk_mul_f32 v[18:19], v[66:67], v[18:19]
	v_pk_mul_f32 v[20:21], v[20:21], v[36:37] op_sel_hi:[1,0]
	v_pk_mul_f32 v[18:19], v[18:19], v[36:37] op_sel_hi:[1,0]
	v_mul_f32_e32 v28, v28, v20
	v_mul_f32_e32 v26, v26, v18
	v_mul_f32_e32 v27, v27, v19
	v_mul_f32_e32 v21, v29, v21
	v_cvt_pk_bf16_f32 v18, v22, v23
	v_cvt_pk_bf16_f32 v19, v24, v25
	v_cvt_pk_bf16_f32 v20, v26, v27
	v_cvt_pk_bf16_f32 v21, v28, v21
	global_store_dwordx4 v[34:35], v[18:21], off offset:256 sc1
	ds_read_b32 v20, v189 offset:1728
	v_cvt_f32_i32_e32 v15, v15
	v_cvt_f32_i32_e32 v17, v17
	v_cvt_f32_i32_e32 v16, v16
	v_cvt_f32_i32_e32 v14, v14
	s_waitcnt vmcnt(7)
	v_and_b32_e32 v22, 0xffff0000, v78
	v_lshlrev_b32_e32 v23, 16, v79
	v_pk_mul_f32 v[16:17], v[88:89], v[16:17]
	v_pk_mul_f32 v[14:15], v[86:87], v[14:15]
	s_waitcnt lgkmcnt(0)
	v_pk_mul_f32 v[16:17], v[16:17], v[20:21] op_sel_hi:[1,0]
	v_pk_mul_f32 v[14:15], v[14:15], v[20:21] op_sel_hi:[1,0]
	v_lshlrev_b32_e32 v21, 16, v78
	v_mul_f32_e32 v22, 0xbfb8aa3b, v22
	v_mul_f32_e32 v23, 0xbfb8aa3b, v23
	v_cvt_f32_i32_e32 v13, v13
	v_cvt_f32_i32_e32 v12, v12
	v_cvt_f32_i32_e32 v11, v11
	v_cvt_f32_i32_e32 v10, v10
	v_mul_f32_e32 v21, 0xbfb8aa3b, v21
	v_exp_f32_e32 v22, v22
	v_exp_f32_e32 v23, v23
	v_exp_f32_e32 v21, v21
	v_pk_mul_f32 v[12:13], v[84:85], v[12:13]
	v_pk_mul_f32 v[10:11], v[82:83], v[10:11]
	v_add_f32_e32 v22, 1.0, v22
	v_add_f32_e32 v23, 1.0, v23
	v_and_b32_e32 v24, 0xffff0000, v79
	v_pk_mul_f32 v[12:13], v[12:13], v[20:21] op_sel_hi:[1,0]
	v_pk_mul_f32 v[10:11], v[10:11], v[20:21] op_sel_hi:[1,0]
	v_add_f32_e32 v21, 1.0, v21
	v_rcp_f32_e32 v22, v22
	v_rcp_f32_e32 v23, v23
	v_mul_f32_e32 v24, 0xbfb8aa3b, v24
	v_rcp_f32_e32 v21, v21
	v_exp_f32_e32 v24, v24
	v_mul_f32_e32 v15, v22, v15
	v_mul_f32_e32 v16, v23, v16
	v_lshlrev_b32_e32 v22, 16, v80
	v_and_b32_e32 v23, 0xffff0000, v80
	v_mul_f32_e32 v14, v21, v14
	v_add_f32_e32 v21, 1.0, v24
	v_mul_f32_e32 v22, 0xbfb8aa3b, v22
	v_mul_f32_e32 v23, 0xbfb8aa3b, v23
	v_rcp_f32_e32 v21, v21
	v_exp_f32_e32 v22, v22
	v_exp_f32_e32 v23, v23
	v_and_b32_e32 v24, 0xffff0000, v81
	v_mul_f32_e32 v17, v21, v17
	v_add_f32_e32 v21, 1.0, v22
	v_add_f32_e32 v22, 1.0, v23
	v_lshlrev_b32_e32 v23, 16, v81
	v_mul_f32_e32 v23, 0xbfb8aa3b, v23
	v_mul_f32_e32 v24, 0xbfb8aa3b, v24
	v_exp_f32_e32 v23, v23
	v_exp_f32_e32 v24, v24
	v_rcp_f32_e32 v21, v21
	v_rcp_f32_e32 v22, v22
	v_add_f32_e32 v23, 1.0, v23
	v_add_f32_e32 v24, 1.0, v24
	v_rcp_f32_e32 v23, v23
	v_rcp_f32_e32 v24, v24
	v_ashrrev_i32_e32 v107, 31, v106
	v_lshlrev_b64 v[18:19], 13, v[106:107]
	v_lshl_add_u64 v[18:19], s[36:37], 0, v[18:19]
	v_lshl_add_u64 v[18:19], v[18:19], 0, v[186:187]
	v_mul_f32_e32 v21, v21, v10
	v_mul_f32_e32 v22, v22, v11
	v_mul_f32_e32 v23, v23, v12
	v_mul_f32_e32 v13, v24, v13
	v_cvt_pk_bf16_f32 v10, v14, v15
	v_cvt_pk_bf16_f32 v11, v16, v17
	v_cvt_pk_bf16_f32 v12, v21, v22
	v_cvt_pk_bf16_f32 v13, v23, v13
	global_store_dwordx4 v[18:19], v[10:13], off sc1
	v_cvt_f32_i32_e32 v7, v7
	v_cvt_f32_i32_e32 v9, v9
	s_waitcnt vmcnt(7)
	v_and_b32_e32 v11, 0xffff0000, v74
	v_lshlrev_b32_e32 v12, 16, v75
	v_lshlrev_b32_e32 v10, 16, v74
	v_mul_f32_e32 v11, 0xbfb8aa3b, v11
	v_mul_f32_e32 v12, 0xbfb8aa3b, v12
	v_mul_f32_e32 v10, 0xbfb8aa3b, v10
	v_exp_f32_e32 v11, v11
	v_exp_f32_e32 v12, v12
	v_exp_f32_e32 v10, v10
	v_cvt_f32_i32_e32 v8, v8
	v_cvt_f32_i32_e32 v6, v6
	v_add_f32_e32 v11, 1.0, v11
	v_add_f32_e32 v12, 1.0, v12
	v_and_b32_e32 v13, 0xffff0000, v75
	v_add_f32_e32 v10, 1.0, v10
	v_rcp_f32_e32 v11, v11
	v_rcp_f32_e32 v12, v12
	v_mul_f32_e32 v13, 0xbfb8aa3b, v13
	v_rcp_f32_e32 v10, v10
	v_exp_f32_e32 v13, v13
	v_pk_mul_f32 v[8:9], v[72:73], v[8:9]
	v_pk_mul_f32 v[6:7], v[70:71], v[6:7]
	v_pk_mul_f32 v[8:9], v[8:9], v[20:21] op_sel_hi:[1,0]
	v_pk_mul_f32 v[6:7], v[6:7], v[20:21] op_sel_hi:[1,0]
	v_mul_f32_e32 v8, v12, v8
	v_mul_f32_e32 v7, v11, v7
	v_lshlrev_b32_e32 v11, 16, v76
	v_and_b32_e32 v12, 0xffff0000, v76
	v_mul_f32_e32 v6, v10, v6
	v_add_f32_e32 v10, 1.0, v13
	v_mul_f32_e32 v11, 0xbfb8aa3b, v11
	v_mul_f32_e32 v12, 0xbfb8aa3b, v12
	v_rcp_f32_e32 v10, v10
	v_exp_f32_e32 v11, v11
	v_exp_f32_e32 v12, v12
	v_and_b32_e32 v13, 0xffff0000, v77
	v_mul_f32_e32 v9, v10, v9
	v_add_f32_e32 v10, 1.0, v11
	v_add_f32_e32 v11, 1.0, v12
	v_lshlrev_b32_e32 v12, 16, v77
	v_mul_f32_e32 v13, 0xbfb8aa3b, v13
	v_mul_f32_e32 v12, 0xbfb8aa3b, v12
	v_exp_f32_e32 v13, v13
	v_exp_f32_e32 v12, v12
	v_cvt_f32_i32_e32 v5, v5
	v_cvt_f32_i32_e32 v4, v4
	v_cvt_f32_i32_e32 v3, v3
	v_cvt_f32_i32_e32 v2, v2
	v_add_f32_e32 v13, 1.0, v13
	v_add_f32_e32 v12, 1.0, v12
	v_rcp_f32_e32 v13, v13
	v_rcp_f32_e32 v10, v10
	v_rcp_f32_e32 v11, v11
	v_rcp_f32_e32 v12, v12
	v_pk_mul_f32 v[4:5], v[68:69], v[4:5]
	v_pk_mul_f32 v[2:3], v[66:67], v[2:3]
	v_pk_mul_f32 v[4:5], v[4:5], v[20:21] op_sel_hi:[1,0]
	v_pk_mul_f32 v[2:3], v[2:3], v[20:21] op_sel_hi:[1,0]
	v_mul_f32_e32 v5, v13, v5
	v_mul_f32_e32 v10, v10, v2
	v_mul_f32_e32 v11, v11, v3
	v_mul_f32_e32 v12, v12, v4
	v_cvt_pk_bf16_f32 v2, v6, v7
	v_cvt_pk_bf16_f32 v3, v8, v9
	v_cvt_pk_bf16_f32 v4, v10, v11
	v_cvt_pk_bf16_f32 v5, v12, v5
	global_store_dwordx4 v[18:19], v[2:5], off offset:256 sc1
	s_andn2_b64 vcc, exec, s[4:5]
	s_mov_b64 s[4:5], -1
	s_cbranch_vccnz .LBB0_547
; #define PG8_LAS __attribute__((address_space(3)))
; #define PG8_BAR __builtin_amdgcn_s_barrier()
; __device__ __forceinline__ void stage_scales(PG8_LAS unsigned char* sb, const float* cs_tile, const float* rs_tile, int tid, int wid) {
;     const float* src = (tid < 256) ? cs_tile + tid : rs_tile + (tid - 256);
;     __builtin_amdgcn_global_load_lds((const unsigned*)src, (PG8_LAS unsigned*)(sb + wid * 256), 4, 0, 0);
; }
; template <class Epi, class Sched, bool ALIGN_EPI = false, bool SP2 = false>
; __device__ __forceinline__ void gemm_phase(PG8_LAS unsigned char* lds, const Gemm g, const Sched& S, const Epi& E) {
;     ...
;         if constexpr (Epi::I8) stage_scales(lds + SCB_OFF + (ui & 1) * 2048, E.cs + (size_t)cur.pn * BM, E.rs + (size_t)cur.pm * BM, tid, wid);
;         if constexpr (ALIGN_EPI) { if (wr == 1) PG8_BAR; }
	s_lshl_b32 s4, s25, 11
	s_lshl_b64 s[26:27], s[54:55], 10
	s_and_b32 s28, s4, 0x800
	s_lshl_b64 s[4:5], s[0:1], 10
	v_lshl_add_u64 v[4:5], v[172:173], 0, s[26:27]
	v_lshl_add_u64 v[2:3], v[170:171], 0, s[4:5]
	v_lshl_add_u64 v[4:5], v[4:5], 0, s[40:41]
	v_cndmask_b32_e64 v3, v5, v3, s[2:3]
	v_cndmask_b32_e64 v2, v4, v2, s[2:3]
	s_add_i32 m0, s8, s28
	s_andn2_b64 vcc, exec, s[42:43]
	global_load_lds_dword v[2:3], off
	s_cbranch_vccnz .LBB0_546
	s_barrier
	s_branch .LBB0_546

; __device__ __forceinline__ unsigned cvt_pk_bf16(float lo, float hi) { unsigned r; asm volatile("v_cvt_pk_bf16_f32 %0, %1, %2" : "=v"(r) : "v"(lo), "v"(hi)); return r; }
; __device__ __forceinline__ float bf_lo(unsigned w) { return __uint_as_float(w << 16); }
; __device__ __forceinline__ float bf_hi(unsigned w) { return __uint_as_float(w & 0xffff0000u); }
; __device__ __forceinline__ float sigmoidf_(float x) { return fast_rcp(1.0f + fast_exp(-x)); }
;     __device__ __forceinline__ void operator()(const f32x4 (&acc)[2][2][4][2], const Unit& u, int wr, int wc, int fr, int fq) const {
;         const int row0 = u.pm * BM + wr * 64 + fr, col0 = u.pn * BM + wc * 32 + 8 * fq;
; #pragma unroll
;         for (int ai = 0; ai < 2; ++ai) {
;             u32x4 g[4][2], p[4][2];
; #pragma unroll
;             for (int m = 0; m < 4; ++m) { const size_t row = (size_t)(row0 + ai * HALF + m * 16);
; #pragma unroll
;                 for (int bj = 0; bj < 2; ++bj) { g[m][bj] = *(const u32x4*)(Gt + row * ldg + col0 + bj * HALF); if (ADD) p[m][bj] = *(const u32x4*)(O + row * ldc + col0 + bj * HALF); } }
;             asm volatile("" ::: "memory");
; #pragma unroll
;             for (int m = 0; m < 4; ++m) { const size_t row = (size_t)(row0 + ai * HALF + m * 16); bf16_t* rowp = O + row * ldc + col0;
; #pragma unroll
;                 for (int bj = 0; bj < 2; ++bj) { const u32x4 gg = g[m][bj]; const f32x4 v0 = acc[ai][bj][m][0], v1 = acc[ai][bj][m][1];
;                     float o[8];
;                     o[0] = sigmoidf_(bf_lo(gg.x)) * v0[0]; o[1] = sigmoidf_(bf_hi(gg.x)) * v0[1]; o[2] = sigmoidf_(bf_lo(gg.y)) * v0[2]; o[3] = sigmoidf_(bf_hi(gg.y)) * v0[3];
;                     o[4] = sigmoidf_(bf_lo(gg.z)) * v1[0]; o[5] = sigmoidf_(bf_hi(gg.z)) * v1[1]; o[6] = sigmoidf_(bf_lo(gg.w)) * v1[2]; o[7] = sigmoidf_(bf_hi(gg.w)) * v1[3];
;                     if (ADD) { const u32x4 pp = p[m][bj];
;                         o[0] += bf_lo(pp.x); o[1] += bf_hi(pp.x); o[2] += bf_lo(pp.y); o[3] += bf_hi(pp.y); o[4] += bf_lo(pp.z); o[5] += bf_hi(pp.z); o[6] += bf_lo(pp.w); o[7] += bf_hi(pp.w); }
;                     u32x4 w; w.x = cvt_pk_bf16(o[0], o[1]); w.y = cvt_pk_bf16(o[2], o[3]); w.z = cvt_pk_bf16(o[4], o[5]); w.w = cvt_pk_bf16(o[6], o[7]);
;                     *(u32x4*)(rowp + bj * HALF) = w; } }
.LBB0_582:
	v_lshl_or_b32 v130, s23, 8, v213
	v_ashrrev_i32_e32 v131, 31, v130
	v_lshlrev_b64 v[198:199], 1, v[130:131]
	v_lshl_add_u32 v200, s54, 8, v181
	v_lshl_add_u64 v[202:203], s[4:5], 0, v[198:199]
	v_mad_i64_i32 v[130:131], s[24:25], v200, s19, v[202:203]
	global_load_dwordx4 v[216:219], v[130:131], off
	global_load_dwordx4 v[224:227], v[130:131], off offset:256
	v_readlane_b32 s26, v249, 35
	v_ashrrev_i32_e32 v201, 31, v200
	v_readlane_b32 s27, v249, 36
	v_lshlrev_b64 v[132:133], 13, v[200:201]
	v_or_b32_e32 v136, 16, v200
	v_lshl_add_u64 v[204:205], s[26:27], 0, v[198:199]
	v_lshl_add_u64 v[134:135], v[204:205], 0, v[132:133]
	global_load_dwordx4 v[220:223], v[134:135], off
	v_or_b32_e32 v138, 32, v200
	v_or_b32_e32 v140, 48, v200
	v_ashrrev_i32_e32 v137, 31, v136
	v_ashrrev_i32_e32 v139, 31, v138
	v_ashrrev_i32_e32 v141, 31, v140
	v_lshlrev_b64 v[232:233], 13, v[136:137]
	v_lshlrev_b64 v[208:209], 13, v[138:139]
	v_lshlrev_b64 v[206:207], 13, v[140:141]
	v_lshl_add_u64 v[132:133], s[26:27], 0, v[132:133]
	v_mad_i64_i32 v[136:137], s[24:25], v136, s19, v[202:203]
	v_lshl_add_u64 v[142:143], v[204:205], 0, v[232:233]
	v_mad_i64_i32 v[138:139], s[24:25], v138, s19, v[202:203]
	v_lshl_add_u64 v[130:131], v[204:205], 0, v[208:209]
	v_mad_i64_i32 v[140:141], s[24:25], v140, s19, v[202:203]
	v_lshl_add_u64 v[234:235], v[204:205], 0, v[206:207]
	v_lshl_add_u64 v[236:237], v[132:133], 0, v[198:199]
	global_load_dwordx4 v[228:231], v[134:135], off offset:256
	global_load_dwordx4 v[174:177], v[136:137], off
	global_load_dwordx4 v[166:169], v[136:137], off offset:256
	global_load_dwordx4 v[170:173], v[142:143], off
	global_load_dwordx4 v[162:165], v[142:143], off offset:256
	global_load_dwordx4 v[158:161], v[138:139], off
	global_load_dwordx4 v[150:153], v[138:139], off offset:256
	global_load_dwordx4 v[154:157], v[130:131], off
	global_load_dwordx4 v[146:149], v[130:131], off offset:256
	s_nop 0
	global_load_dwordx4 v[142:145], v[140:141], off
	global_load_dwordx4 v[134:137], v[140:141], off offset:256
	s_nop 0
	global_load_dwordx4 v[138:141], v[234:235], off
	global_load_dwordx4 v[130:133], v[234:235], off offset:256
	s_andn2_b64 vcc, exec, s[2:3]
	s_mov_b64 s[2:3], -1
	s_waitcnt vmcnt(0)
	v_lshlrev_b32_e32 v201, 16, v216
	v_and_b32_e32 v216, 0xffff0000, v216
	v_lshlrev_b32_e32 v234, 16, v217
	v_lshlrev_b32_e32 v235, 16, v218
	v_and_b32_e32 v218, 0xffff0000, v218
	v_lshlrev_b32_e32 v238, 16, v219
	v_mul_f32_e32 v201, 0xbfb8aa3b, v201
	v_mul_f32_e32 v216, 0xbfb8aa3b, v216
	v_and_b32_e32 v217, 0xffff0000, v217
	v_and_b32_e32 v219, 0xffff0000, v219
	v_mul_f32_e32 v234, 0xbfb8aa3b, v234
	v_mul_f32_e32 v218, 0xbfb8aa3b, v218
	v_mul_f32_e32 v238, 0xbfb8aa3b, v238
	v_exp_f32_e32 v201, v201
	v_exp_f32_e32 v216, v216
	v_mul_f32_e32 v217, 0xbfb8aa3b, v217
	v_mul_f32_e32 v235, 0xbfb8aa3b, v235
	v_mul_f32_e32 v219, 0xbfb8aa3b, v219
	v_exp_f32_e32 v234, v234
	v_exp_f32_e32 v218, v218
	v_exp_f32_e32 v238, v238
	v_exp_f32_e32 v217, v217
	v_exp_f32_e32 v235, v235
	v_exp_f32_e32 v219, v219
	v_add_f32_e32 v201, 1.0, v201
	v_add_f32_e32 v216, 1.0, v216
	v_add_f32_e32 v234, 1.0, v234
	v_add_f32_e32 v218, 1.0, v218
	v_add_f32_e32 v238, 1.0, v238
	v_rcp_f32_e32 v201, v201
	v_rcp_f32_e32 v216, v216
	v_add_f32_e32 v217, 1.0, v217
	v_add_f32_e32 v235, 1.0, v235
	v_add_f32_e32 v219, 1.0, v219
	v_rcp_f32_e32 v234, v234
	v_rcp_f32_e32 v218, v218
	v_rcp_f32_e32 v238, v238
	v_rcp_f32_e32 v217, v217
	v_rcp_f32_e32 v235, v235
	v_rcp_f32_e32 v219, v219
	v_lshlrev_b32_e32 v239, 16, v220
	v_and_b32_e32 v220, 0xffff0000, v220
	v_lshlrev_b32_e32 v240, 16, v221
	v_fmac_f32_e32 v239, v126, v201
	v_fmac_f32_e32 v220, v127, v216
	v_and_b32_e32 v126, 0xffff0000, v222
	v_lshlrev_b32_e32 v127, 16, v223
	v_and_b32_e32 v221, 0xffff0000, v221
	v_lshlrev_b32_e32 v241, 16, v222
	v_fmac_f32_e32 v240, v128, v234
	v_fmac_f32_e32 v126, v123, v218
	v_fmac_f32_e32 v127, v124, v238
	v_and_b32_e32 v128, 0xffff0000, v223
	v_fmac_f32_e32 v221, v129, v217
	v_fmac_f32_e32 v241, v122, v235
	v_fmac_f32_e32 v128, v125, v219
	v_cvt_pk_bf16_f32 v122, v239, v220
	v_cvt_pk_bf16_f32 v123, v240, v221
	v_cvt_pk_bf16_f32 v124, v241, v126
	v_cvt_pk_bf16_f32 v125, v127, v128
	v_lshlrev_b32_e32 v126, 16, v224
	v_and_b32_e32 v127, 0xffff0000, v224
	v_mul_f32_e32 v126, 0xbfb8aa3b, v126
	v_mul_f32_e32 v127, 0xbfb8aa3b, v127
	v_exp_f32_e32 v126, v126
	v_exp_f32_e32 v127, v127
	global_store_dwordx4 v[236:237], v[122:125], off sc1
	v_lshlrev_b32_e32 v128, 16, v227
	v_mul_f32_e32 v128, 0xbfb8aa3b, v128
	v_lshlrev_b32_e32 v124, 16, v225
	v_mul_f32_e32 v124, 0xbfb8aa3b, v124
	v_and_b32_e32 v125, 0xffff0000, v225
	v_add_f32_e32 v122, 1.0, v126
	v_add_f32_e32 v123, 1.0, v127
	v_exp_f32_e32 v124, v124
	v_mul_f32_e32 v125, 0xbfb8aa3b, v125
	v_lshlrev_b32_e32 v126, 16, v226
	v_and_b32_e32 v127, 0xffff0000, v226
	v_exp_f32_e32 v125, v125
	v_mul_f32_e32 v126, 0xbfb8aa3b, v126
	v_mul_f32_e32 v127, 0xbfb8aa3b, v127
	v_and_b32_e32 v129, 0xffff0000, v227
	v_exp_f32_e32 v126, v126
	v_exp_f32_e32 v127, v127
	v_exp_f32_e32 v128, v128
	v_mul_f32_e32 v129, 0xbfb8aa3b, v129
	v_rcp_f32_e32 v122, v122
	v_exp_f32_e32 v129, v129
	v_rcp_f32_e32 v123, v123
	v_add_f32_e32 v124, 1.0, v124
	v_rcp_f32_e32 v124, v124
	v_add_f32_e32 v125, 1.0, v125
	v_rcp_f32_e32 v125, v125
	v_add_f32_e32 v126, 1.0, v126
	v_add_f32_e32 v127, 1.0, v127
	v_add_f32_e32 v128, 1.0, v128
	v_lshlrev_b32_e32 v201, 16, v228
	v_rcp_f32_e32 v126, v126
	v_rcp_f32_e32 v127, v127
	v_rcp_f32_e32 v128, v128
	v_add_f32_e32 v129, 1.0, v129
	v_fmac_f32_e32 v201, v118, v122
	v_and_b32_e32 v118, 0xffff0000, v228
	v_rcp_f32_e32 v129, v129
	v_fmac_f32_e32 v118, v119, v123
; __device__ __forceinline__ unsigned cvt_pk_bf16(float lo, float hi) { unsigned r; asm volatile("v_cvt_pk_bf16_f32 %0, %1, %2" : "=v"(r) : "v"(lo), "v"(hi)); return r; }
; __device__ __forceinline__ float bf_lo(unsigned w) { return __uint_as_float(w << 16); }
; __device__ __forceinline__ float bf_hi(unsigned w) { return __uint_as_float(w & 0xffff0000u); }
; __device__ __forceinline__ float sigmoidf_(float x) { return fast_rcp(1.0f + fast_exp(-x)); }
;     __device__ __forceinline__ void operator()(const f32x4 (&acc)[2][2][4][2], const Unit& u, int wr, int wc, int fr, int fq) const {
;     ...
;             for (int m = 0; m < 4; ++m) { const size_t row = (size_t)(row0 + ai * HALF + m * 16); bf16_t* rowp = O + row * ldc + col0;
; #pragma unroll
;                 for (int bj = 0; bj < 2; ++bj) { const u32x4 gg = g[m][bj]; const f32x4 v0 = acc[ai][bj][m][0], v1 = acc[ai][bj][m][1];
;                     float o[8];
;                     o[0] = sigmoidf_(bf_lo(gg.x)) * v0[0]; o[1] = sigmoidf_(bf_hi(gg.x)) * v0[1]; o[2] = sigmoidf_(bf_lo(gg.y)) * v0[2]; o[3] = sigmoidf_(bf_hi(gg.y)) * v0[3];
;                     o[4] = sigmoidf_(bf_lo(gg.z)) * v1[0]; o[5] = sigmoidf_(bf_hi(gg.z)) * v1[1]; o[6] = sigmoidf_(bf_lo(gg.w)) * v1[2]; o[7] = sigmoidf_(bf_hi(gg.w)) * v1[3];
;                     if (ADD) { const u32x4 pp = p[m][bj];
;                         o[0] += bf_lo(pp.x); o[1] += bf_hi(pp.x); o[2] += bf_lo(pp.y); o[3] += bf_hi(pp.y); o[4] += bf_lo(pp.z); o[5] += bf_hi(pp.z); o[6] += bf_lo(pp.w); o[7] += bf_hi(pp.w); }
;                     u32x4 w; w.x = cvt_pk_bf16(o[0], o[1]); w.y = cvt_pk_bf16(o[2], o[3]); w.z = cvt_pk_bf16(o[4], o[5]); w.w = cvt_pk_bf16(o[6], o[7]);
;                     *(u32x4*)(rowp + bj * HALF) = w; } }
	v_lshlrev_b32_e32 v119, 16, v229
	v_fmac_f32_e32 v119, v120, v124
	v_and_b32_e32 v120, 0xffff0000, v229
	v_fmac_f32_e32 v120, v121, v125
	v_lshlrev_b32_e32 v121, 16, v230
	v_and_b32_e32 v122, 0xffff0000, v230
	v_lshlrev_b32_e32 v123, 16, v231
	v_fmac_f32_e32 v121, v114, v126
	v_fmac_f32_e32 v122, v115, v127
	v_fmac_f32_e32 v123, v116, v128
	v_and_b32_e32 v124, 0xffff0000, v231
	v_cvt_pk_bf16_f32 v114, v201, v118
	v_cvt_pk_bf16_f32 v115, v119, v120
	v_cvt_pk_bf16_f32 v116, v121, v122
	v_fmac_f32_e32 v124, v117, v129
	v_cvt_pk_bf16_f32 v117, v123, v124
	global_store_dwordx4 v[236:237], v[114:117], off offset:256 sc1
	v_lshlrev_b32_e32 v118, 16, v175
	v_mul_f32_e32 v118, 0xbfb8aa3b, v118
	v_lshlrev_b32_e32 v116, 16, v174
	v_mul_f32_e32 v116, 0xbfb8aa3b, v116
	v_and_b32_e32 v117, 0xffff0000, v174
	v_exp_f32_e32 v116, v116
	v_mul_f32_e32 v117, 0xbfb8aa3b, v117
	v_exp_f32_e32 v117, v117
	v_and_b32_e32 v119, 0xffff0000, v175
	v_exp_f32_e32 v118, v118
	v_mul_f32_e32 v119, 0xbfb8aa3b, v119
	v_lshlrev_b32_e32 v120, 16, v176
	v_and_b32_e32 v121, 0xffff0000, v176
	v_exp_f32_e32 v119, v119
	v_mul_f32_e32 v120, 0xbfb8aa3b, v120
	v_mul_f32_e32 v121, 0xbfb8aa3b, v121
	v_add_f32_e32 v116, 1.0, v116
	v_exp_f32_e32 v120, v120
	v_exp_f32_e32 v121, v121
	v_rcp_f32_e32 v116, v116
	v_add_f32_e32 v117, 1.0, v117
	v_lshlrev_b32_e32 v122, 16, v177
	v_rcp_f32_e32 v117, v117
	v_add_f32_e32 v118, 1.0, v118
	v_mul_f32_e32 v122, 0xbfb8aa3b, v122
	v_and_b32_e32 v123, 0xffff0000, v177
	v_rcp_f32_e32 v118, v118
	v_add_f32_e32 v119, 1.0, v119
	v_exp_f32_e32 v122, v122
	v_mul_f32_e32 v123, 0xbfb8aa3b, v123
	v_rcp_f32_e32 v119, v119
	v_add_f32_e32 v120, 1.0, v120
	v_add_f32_e32 v121, 1.0, v121
	v_exp_f32_e32 v123, v123
	v_lshlrev_b32_e32 v124, 16, v170
	v_rcp_f32_e32 v120, v120
	v_rcp_f32_e32 v121, v121
	v_fmac_f32_e32 v124, v110, v116
	v_and_b32_e32 v110, 0xffff0000, v170
	v_fmac_f32_e32 v110, v111, v117
	v_lshlrev_b32_e32 v111, 16, v171
	v_add_f32_e32 v122, 1.0, v122
	v_fmac_f32_e32 v111, v112, v118
	v_and_b32_e32 v112, 0xffff0000, v171
	v_rcp_f32_e32 v122, v122
	v_add_f32_e32 v123, 1.0, v123
	v_fmac_f32_e32 v112, v113, v119
	v_lshlrev_b32_e32 v113, 16, v172
	v_and_b32_e32 v116, 0xffff0000, v172
	v_rcp_f32_e32 v123, v123
	v_fmac_f32_e32 v113, v106, v120
	v_fmac_f32_e32 v116, v107, v121
	v_cvt_pk_bf16_f32 v106, v124, v110
	v_cvt_pk_bf16_f32 v107, v111, v112
	v_lshlrev_b32_e32 v110, 16, v166
	v_and_b32_e32 v111, 0xffff0000, v166
	v_mul_f32_e32 v110, 0xbfb8aa3b, v110
	v_mul_f32_e32 v111, 0xbfb8aa3b, v111
	v_lshl_add_u64 v[114:115], s[26:27], 0, v[232:233]
	v_lshlrev_b32_e32 v117, 16, v173
	v_exp_f32_e32 v110, v110
	v_exp_f32_e32 v111, v111
	v_lshl_add_u64 v[114:115], v[114:115], 0, v[198:199]
	v_fmac_f32_e32 v117, v108, v122
	v_and_b32_e32 v118, 0xffff0000, v173
	v_cvt_pk_bf16_f32 v108, v113, v116
	v_fmac_f32_e32 v118, v109, v123
	v_cvt_pk_bf16_f32 v109, v117, v118
	global_store_dwordx4 v[114:115], v[106:109], off sc1
	v_lshlrev_b32_e32 v112, 16, v169
	v_mul_f32_e32 v112, 0xbfb8aa3b, v112
	v_lshlrev_b32_e32 v108, 16, v167
	v_mul_f32_e32 v108, 0xbfb8aa3b, v108
	v_and_b32_e32 v109, 0xffff0000, v167
	v_add_f32_e32 v106, 1.0, v110
	v_add_f32_e32 v107, 1.0, v111
	v_exp_f32_e32 v108, v108
	v_mul_f32_e32 v109, 0xbfb8aa3b, v109
	v_lshlrev_b32_e32 v110, 16, v168
	v_and_b32_e32 v111, 0xffff0000, v168
	v_exp_f32_e32 v109, v109
	v_mul_f32_e32 v110, 0xbfb8aa3b, v110
	v_mul_f32_e32 v111, 0xbfb8aa3b, v111
	v_and_b32_e32 v113, 0xffff0000, v169
	v_exp_f32_e32 v110, v110
	v_exp_f32_e32 v111, v111
	v_exp_f32_e32 v112, v112
	v_mul_f32_e32 v113, 0xbfb8aa3b, v113
	v_rcp_f32_e32 v106, v106
	v_exp_f32_e32 v113, v113
	v_rcp_f32_e32 v107, v107
	v_add_f32_e32 v108, 1.0, v108
	v_rcp_f32_e32 v108, v108
	v_add_f32_e32 v109, 1.0, v109
	v_rcp_f32_e32 v109, v109
	v_add_f32_e32 v110, 1.0, v110
	v_add_f32_e32 v111, 1.0, v111
	v_add_f32_e32 v112, 1.0, v112
	v_lshlrev_b32_e32 v116, 16, v162
	v_rcp_f32_e32 v110, v110
	v_rcp_f32_e32 v111, v111
	v_rcp_f32_e32 v112, v112
	v_add_f32_e32 v113, 1.0, v113
	v_fmac_f32_e32 v116, v102, v106
	v_and_b32_e32 v102, 0xffff0000, v162
	v_rcp_f32_e32 v113, v113
	v_fmac_f32_e32 v102, v103, v107
	v_lshlrev_b32_e32 v103, 16, v163
	v_fmac_f32_e32 v103, v104, v108
	v_and_b32_e32 v104, 0xffff0000, v163
	v_fmac_f32_e32 v104, v105, v109
	v_lshlrev_b32_e32 v105, 16, v164
	v_and_b32_e32 v106, 0xffff0000, v164
	v_lshlrev_b32_e32 v107, 16, v165
	v_fmac_f32_e32 v105, v98, v110
	v_fmac_f32_e32 v106, v99, v111
	v_fmac_f32_e32 v107, v100, v112
	v_and_b32_e32 v108, 0xffff0000, v165
	v_cvt_pk_bf16_f32 v98, v116, v102
	v_cvt_pk_bf16_f32 v99, v103, v104
	v_cvt_pk_bf16_f32 v100, v105, v106
	v_fmac_f32_e32 v108, v101, v113
	v_cvt_pk_bf16_f32 v101, v107, v108
	global_store_dwordx4 v[114:115], v[98:101], off offset:256 sc1
	v_lshlrev_b32_e32 v102, 16, v159
	v_mul_f32_e32 v102, 0xbfb8aa3b, v102
	v_lshlrev_b32_e32 v100, 16, v158
	v_mul_f32_e32 v100, 0xbfb8aa3b, v100
	v_and_b32_e32 v101, 0xffff0000, v158
	v_exp_f32_e32 v100, v100
	v_mul_f32_e32 v101, 0xbfb8aa3b, v101
	v_exp_f32_e32 v101, v101
	v_and_b32_e32 v103, 0xffff0000, v159
	v_exp_f32_e32 v102, v102
	v_mul_f32_e32 v103, 0xbfb8aa3b, v103
	v_lshlrev_b32_e32 v104, 16, v160
	v_and_b32_e32 v105, 0xffff0000, v160
	v_exp_f32_e32 v103, v103
	v_mul_f32_e32 v104, 0xbfb8aa3b, v104
	v_mul_f32_e32 v105, 0xbfb8aa3b, v105
	v_add_f32_e32 v100, 1.0, v100
	v_exp_f32_e32 v104, v104
	v_exp_f32_e32 v105, v105
	v_rcp_f32_e32 v100, v100
	v_add_f32_e32 v101, 1.0, v101
	v_lshlrev_b32_e32 v106, 16, v161
	v_rcp_f32_e32 v101, v101
	v_add_f32_e32 v102, 1.0, v102
	v_mul_f32_e32 v106, 0xbfb8aa3b, v106
	v_and_b32_e32 v107, 0xffff0000, v161
	v_rcp_f32_e32 v102, v102
; __device__ __forceinline__ unsigned cvt_pk_bf16(float lo, float hi) { unsigned r; asm volatile("v_cvt_pk_bf16_f32 %0, %1, %2" : "=v"(r) : "v"(lo), "v"(hi)); return r; }
; __device__ __forceinline__ float bf_lo(unsigned w) { return __uint_as_float(w << 16); }
; __device__ __forceinline__ float bf_hi(unsigned w) { return __uint_as_float(w & 0xffff0000u); }
; __device__ __forceinline__ float sigmoidf_(float x) { return fast_rcp(1.0f + fast_exp(-x)); }
;     __device__ __forceinline__ void operator()(const f32x4 (&acc)[2][2][4][2], const Unit& u, int wr, int wc, int fr, int fq) const {
;     ...
;             for (int m = 0; m < 4; ++m) { const size_t row = (size_t)(row0 + ai * HALF + m * 16); bf16_t* rowp = O + row * ldc + col0;
; #pragma unroll
;                 for (int bj = 0; bj < 2; ++bj) { const u32x4 gg = g[m][bj]; const f32x4 v0 = acc[ai][bj][m][0], v1 = acc[ai][bj][m][1];
;                     float o[8];
;                     o[0] = sigmoidf_(bf_lo(gg.x)) * v0[0]; o[1] = sigmoidf_(bf_hi(gg.x)) * v0[1]; o[2] = sigmoidf_(bf_lo(gg.y)) * v0[2]; o[3] = sigmoidf_(bf_hi(gg.y)) * v0[3];
;                     o[4] = sigmoidf_(bf_lo(gg.z)) * v1[0]; o[5] = sigmoidf_(bf_hi(gg.z)) * v1[1]; o[6] = sigmoidf_(bf_lo(gg.w)) * v1[2]; o[7] = sigmoidf_(bf_hi(gg.w)) * v1[3];
;                     if (ADD) { const u32x4 pp = p[m][bj];
;                         o[0] += bf_lo(pp.x); o[1] += bf_hi(pp.x); o[2] += bf_lo(pp.y); o[3] += bf_hi(pp.y); o[4] += bf_lo(pp.z); o[5] += bf_hi(pp.z); o[6] += bf_lo(pp.w); o[7] += bf_hi(pp.w); }
;                     u32x4 w; w.x = cvt_pk_bf16(o[0], o[1]); w.y = cvt_pk_bf16(o[2], o[3]); w.z = cvt_pk_bf16(o[4], o[5]); w.w = cvt_pk_bf16(o[6], o[7]);
;                     *(u32x4*)(rowp + bj * HALF) = w; } }
	v_add_f32_e32 v103, 1.0, v103
	v_exp_f32_e32 v106, v106
	v_mul_f32_e32 v107, 0xbfb8aa3b, v107
	v_rcp_f32_e32 v103, v103
	v_add_f32_e32 v104, 1.0, v104
	v_add_f32_e32 v105, 1.0, v105
	v_exp_f32_e32 v107, v107
	v_lshlrev_b32_e32 v108, 16, v154
	v_rcp_f32_e32 v104, v104
	v_rcp_f32_e32 v105, v105
	v_fmac_f32_e32 v108, v94, v100
	v_and_b32_e32 v94, 0xffff0000, v154
	v_fmac_f32_e32 v94, v95, v101
	v_lshlrev_b32_e32 v95, 16, v155
	v_add_f32_e32 v106, 1.0, v106
	v_fmac_f32_e32 v95, v96, v102
	v_and_b32_e32 v96, 0xffff0000, v155
	v_rcp_f32_e32 v106, v106
	v_add_f32_e32 v107, 1.0, v107
	v_fmac_f32_e32 v96, v97, v103
	v_lshlrev_b32_e32 v97, 16, v156
	v_and_b32_e32 v100, 0xffff0000, v156
	v_rcp_f32_e32 v107, v107
	v_fmac_f32_e32 v97, v90, v104
	v_fmac_f32_e32 v100, v91, v105
	v_cvt_pk_bf16_f32 v90, v108, v94
	v_cvt_pk_bf16_f32 v91, v95, v96
	v_lshlrev_b32_e32 v94, 16, v150
	v_and_b32_e32 v95, 0xffff0000, v150
	v_mul_f32_e32 v94, 0xbfb8aa3b, v94
	v_mul_f32_e32 v95, 0xbfb8aa3b, v95
	v_lshl_add_u64 v[98:99], s[26:27], 0, v[208:209]
	v_lshlrev_b32_e32 v101, 16, v157
	v_exp_f32_e32 v94, v94
	v_exp_f32_e32 v95, v95
	v_lshl_add_u64 v[98:99], v[98:99], 0, v[198:199]
	v_fmac_f32_e32 v101, v92, v106
	v_and_b32_e32 v102, 0xffff0000, v157
	v_cvt_pk_bf16_f32 v92, v97, v100
	v_fmac_f32_e32 v102, v93, v107
	v_cvt_pk_bf16_f32 v93, v101, v102
	global_store_dwordx4 v[98:99], v[90:93], off sc1
	v_lshlrev_b32_e32 v96, 16, v153
	v_mul_f32_e32 v96, 0xbfb8aa3b, v96
	v_lshlrev_b32_e32 v92, 16, v151
	v_mul_f32_e32 v92, 0xbfb8aa3b, v92
	v_and_b32_e32 v93, 0xffff0000, v151
	v_add_f32_e32 v90, 1.0, v94
	v_add_f32_e32 v91, 1.0, v95
	v_exp_f32_e32 v92, v92
	v_mul_f32_e32 v93, 0xbfb8aa3b, v93
	v_lshlrev_b32_e32 v94, 16, v152
	v_and_b32_e32 v95, 0xffff0000, v152
	v_exp_f32_e32 v93, v93
	v_mul_f32_e32 v94, 0xbfb8aa3b, v94
	v_mul_f32_e32 v95, 0xbfb8aa3b, v95
	v_and_b32_e32 v97, 0xffff0000, v153
	v_exp_f32_e32 v94, v94
	v_exp_f32_e32 v95, v95
	v_exp_f32_e32 v96, v96
	v_mul_f32_e32 v97, 0xbfb8aa3b, v97
	v_rcp_f32_e32 v90, v90
	v_exp_f32_e32 v97, v97
	v_rcp_f32_e32 v91, v91
	v_add_f32_e32 v92, 1.0, v92
	v_rcp_f32_e32 v92, v92
	v_add_f32_e32 v93, 1.0, v93
	v_rcp_f32_e32 v93, v93
	v_add_f32_e32 v94, 1.0, v94
	v_add_f32_e32 v95, 1.0, v95
	v_add_f32_e32 v96, 1.0, v96
	v_lshlrev_b32_e32 v100, 16, v146
	v_rcp_f32_e32 v94, v94
	v_rcp_f32_e32 v95, v95
	v_rcp_f32_e32 v96, v96
	v_add_f32_e32 v97, 1.0, v97
	v_fmac_f32_e32 v100, v86, v90
	v_and_b32_e32 v86, 0xffff0000, v146
	v_rcp_f32_e32 v97, v97
	v_fmac_f32_e32 v86, v87, v91
	v_lshlrev_b32_e32 v87, 16, v147
	v_fmac_f32_e32 v87, v88, v92
	v_and_b32_e32 v88, 0xffff0000, v147
	v_fmac_f32_e32 v88, v89, v93
	v_lshlrev_b32_e32 v89, 16, v148
	v_and_b32_e32 v90, 0xffff0000, v148
	v_lshlrev_b32_e32 v91, 16, v149
	v_fmac_f32_e32 v89, v82, v94
	v_fmac_f32_e32 v90, v83, v95
	v_fmac_f32_e32 v91, v84, v96
	v_and_b32_e32 v92, 0xffff0000, v149
	v_cvt_pk_bf16_f32 v82, v100, v86
	v_cvt_pk_bf16_f32 v83, v87, v88
	v_cvt_pk_bf16_f32 v84, v89, v90
	v_fmac_f32_e32 v92, v85, v97
	v_cvt_pk_bf16_f32 v85, v91, v92
	global_store_dwordx4 v[98:99], v[82:85], off offset:256 sc1
	v_lshlrev_b32_e32 v86, 16, v143
	v_mul_f32_e32 v86, 0xbfb8aa3b, v86
	v_lshlrev_b32_e32 v84, 16, v142
	v_mul_f32_e32 v84, 0xbfb8aa3b, v84
	v_and_b32_e32 v85, 0xffff0000, v142
	v_exp_f32_e32 v84, v84
	v_mul_f32_e32 v85, 0xbfb8aa3b, v85
	v_exp_f32_e32 v85, v85
	v_and_b32_e32 v87, 0xffff0000, v143
	v_exp_f32_e32 v86, v86
	v_mul_f32_e32 v87, 0xbfb8aa3b, v87
	v_lshlrev_b32_e32 v88, 16, v144
	v_exp_f32_e32 v87, v87
	v_mul_f32_e32 v88, 0xbfb8aa3b, v88
	v_and_b32_e32 v89, 0xffff0000, v144
	v_add_f32_e32 v84, 1.0, v84
	v_exp_f32_e32 v88, v88
	v_mul_f32_e32 v89, 0xbfb8aa3b, v89
	v_rcp_f32_e32 v84, v84
	v_add_f32_e32 v85, 1.0, v85
	v_exp_f32_e32 v89, v89
	v_lshlrev_b32_e32 v90, 16, v145
	v_rcp_f32_e32 v85, v85
	v_add_f32_e32 v86, 1.0, v86
	v_mul_f32_e32 v90, 0xbfb8aa3b, v90
	v_and_b32_e32 v91, 0xffff0000, v145
	v_rcp_f32_e32 v86, v86
	v_add_f32_e32 v87, 1.0, v87
	v_exp_f32_e32 v90, v90
	v_mul_f32_e32 v91, 0xbfb8aa3b, v91
	v_rcp_f32_e32 v87, v87
	v_add_f32_e32 v88, 1.0, v88
	v_exp_f32_e32 v91, v91
	v_lshlrev_b32_e32 v92, 16, v138
	v_rcp_f32_e32 v88, v88
	v_add_f32_e32 v89, 1.0, v89
	v_fmac_f32_e32 v92, v78, v84
	v_and_b32_e32 v78, 0xffff0000, v138
	v_rcp_f32_e32 v89, v89
	v_fmac_f32_e32 v78, v79, v85
	v_lshlrev_b32_e32 v79, 16, v139
	v_add_f32_e32 v90, 1.0, v90
	v_fmac_f32_e32 v79, v80, v86
	v_and_b32_e32 v80, 0xffff0000, v139
	v_rcp_f32_e32 v90, v90
	v_add_f32_e32 v91, 1.0, v91
	v_fmac_f32_e32 v80, v81, v87
	v_lshlrev_b32_e32 v81, 16, v140
	v_rcp_f32_e32 v91, v91
	v_fmac_f32_e32 v81, v74, v88
	v_and_b32_e32 v84, 0xffff0000, v140
	v_cvt_pk_bf16_f32 v74, v92, v78
	v_lshlrev_b32_e32 v78, 16, v134
	v_fmac_f32_e32 v84, v75, v89
	v_cvt_pk_bf16_f32 v75, v79, v80
	v_mul_f32_e32 v78, 0xbfb8aa3b, v78
	v_and_b32_e32 v79, 0xffff0000, v134
	v_lshl_add_u64 v[82:83], s[26:27], 0, v[206:207]
	v_lshlrev_b32_e32 v85, 16, v141
	v_exp_f32_e32 v78, v78
	v_mul_f32_e32 v79, 0xbfb8aa3b, v79
	v_lshl_add_u64 v[82:83], v[82:83], 0, v[198:199]
	v_fmac_f32_e32 v85, v76, v90
	v_and_b32_e32 v86, 0xffff0000, v141
	v_cvt_pk_bf16_f32 v76, v81, v84
	v_exp_f32_e32 v79, v79
	v_fmac_f32_e32 v86, v77, v91
	v_cvt_pk_bf16_f32 v77, v85, v86
	global_store_dwordx4 v[82:83], v[74:77], off sc1
	v_lshlrev_b32_e32 v80, 16, v137
	v_and_b32_e32 v81, 0xffff0000, v137
	v_lshlrev_b32_e32 v76, 16, v135
	v_mul_f32_e32 v76, 0xbfb8aa3b, v76
	v_and_b32_e32 v77, 0xffff0000, v135
	v_add_f32_e32 v74, 1.0, v78
	v_exp_f32_e32 v76, v76
	v_mul_f32_e32 v77, 0xbfb8aa3b, v77
	v_lshlrev_b32_e32 v78, 16, v136
	v_add_f32_e32 v75, 1.0, v79
	v_exp_f32_e32 v77, v77
; __device__ __forceinline__ unsigned cvt_pk_bf16(float lo, float hi) { unsigned r; asm volatile("v_cvt_pk_bf16_f32 %0, %1, %2" : "=v"(r) : "v"(lo), "v"(hi)); return r; }
; __device__ __forceinline__ float bf_lo(unsigned w) { return __uint_as_float(w << 16); }
; __device__ __forceinline__ float bf_hi(unsigned w) { return __uint_as_float(w & 0xffff0000u); }
; __device__ __forceinline__ float sigmoidf_(float x) { return fast_rcp(1.0f + fast_exp(-x)); }
;     __device__ __forceinline__ void operator()(const f32x4 (&acc)[2][2][4][2], const Unit& u, int wr, int wc, int fr, int fq) const {
;     ...
;             for (int m = 0; m < 4; ++m) { const size_t row = (size_t)(row0 + ai * HALF + m * 16);
; #pragma unroll
;                 for (int bj = 0; bj < 2; ++bj) { g[m][bj] = *(const u32x4*)(Gt + row * ldg + col0 + bj * HALF); if (ADD) p[m][bj] = *(const u32x4*)(O + row * ldc + col0 + bj * HALF); } }
;             asm volatile("" ::: "memory");
; #pragma unroll
;             for (int m = 0; m < 4; ++m) { const size_t row = (size_t)(row0 + ai * HALF + m * 16); bf16_t* rowp = O + row * ldc + col0;
; #pragma unroll
;                 for (int bj = 0; bj < 2; ++bj) { const u32x4 gg = g[m][bj]; const f32x4 v0 = acc[ai][bj][m][0], v1 = acc[ai][bj][m][1];
;                     float o[8];
;                     o[0] = sigmoidf_(bf_lo(gg.x)) * v0[0]; o[1] = sigmoidf_(bf_hi(gg.x)) * v0[1]; o[2] = sigmoidf_(bf_lo(gg.y)) * v0[2]; o[3] = sigmoidf_(bf_hi(gg.y)) * v0[3];
;                     o[4] = sigmoidf_(bf_lo(gg.z)) * v1[0]; o[5] = sigmoidf_(bf_hi(gg.z)) * v1[1]; o[6] = sigmoidf_(bf_lo(gg.w)) * v1[2]; o[7] = sigmoidf_(bf_hi(gg.w)) * v1[3];
;                     if (ADD) { const u32x4 pp = p[m][bj];
;                         o[0] += bf_lo(pp.x); o[1] += bf_hi(pp.x); o[2] += bf_lo(pp.y); o[3] += bf_hi(pp.y); o[4] += bf_lo(pp.z); o[5] += bf_hi(pp.z); o[6] += bf_lo(pp.w); o[7] += bf_hi(pp.w); }
;                     u32x4 w; w.x = cvt_pk_bf16(o[0], o[1]); w.y = cvt_pk_bf16(o[2], o[3]); w.z = cvt_pk_bf16(o[4], o[5]); w.w = cvt_pk_bf16(o[6], o[7]);
;                     *(u32x4*)(rowp + bj * HALF) = w; } }
	v_mul_f32_e32 v78, 0xbfb8aa3b, v78
	v_and_b32_e32 v79, 0xffff0000, v136
	v_exp_f32_e32 v78, v78
	v_mul_f32_e32 v79, 0xbfb8aa3b, v79
	v_mul_f32_e32 v80, 0xbfb8aa3b, v80
	v_mul_f32_e32 v81, 0xbfb8aa3b, v81
	v_rcp_f32_e32 v74, v74
	v_exp_f32_e32 v79, v79
	v_exp_f32_e32 v80, v80
	v_exp_f32_e32 v81, v81
	v_rcp_f32_e32 v75, v75
	v_add_f32_e32 v76, 1.0, v76
	v_rcp_f32_e32 v76, v76
	v_add_f32_e32 v77, 1.0, v77
	v_rcp_f32_e32 v77, v77
	v_add_f32_e32 v78, 1.0, v78
	v_lshlrev_b32_e32 v84, 16, v130
	v_rcp_f32_e32 v78, v78
	v_add_f32_e32 v79, 1.0, v79
	v_add_f32_e32 v80, 1.0, v80
	v_add_f32_e32 v81, 1.0, v81
	v_fmac_f32_e32 v84, v70, v74
	v_and_b32_e32 v70, 0xffff0000, v130
	v_rcp_f32_e32 v79, v79
	v_rcp_f32_e32 v80, v80
	v_rcp_f32_e32 v81, v81
	v_fmac_f32_e32 v70, v71, v75
	v_lshlrev_b32_e32 v71, 16, v131
	v_fmac_f32_e32 v71, v72, v76
	v_and_b32_e32 v72, 0xffff0000, v131
	v_fmac_f32_e32 v72, v73, v77
	v_lshlrev_b32_e32 v73, 16, v132
	v_fmac_f32_e32 v73, v66, v78
	v_and_b32_e32 v74, 0xffff0000, v132
	v_lshlrev_b32_e32 v75, 16, v133
	v_and_b32_e32 v76, 0xffff0000, v133
	v_cvt_pk_bf16_f32 v66, v84, v70
	v_fmac_f32_e32 v74, v67, v79
	v_fmac_f32_e32 v75, v68, v80
	v_fmac_f32_e32 v76, v69, v81
	v_cvt_pk_bf16_f32 v67, v71, v72
	v_cvt_pk_bf16_f32 v68, v73, v74
	v_cvt_pk_bf16_f32 v69, v75, v76
	global_store_dwordx4 v[82:83], v[66:69], off offset:256 sc1
	s_nop 1
	v_add_u32_e32 v66, 0x80, v200
	v_mad_i64_i32 v[68:69], s[24:25], v66, s19, v[202:203]
	global_load_dwordx4 v[114:117], v[68:69], off
	v_ashrrev_i32_e32 v67, 31, v66
	v_lshlrev_b64 v[134:135], 13, v[66:67]
	v_lshl_add_u64 v[66:67], v[204:205], 0, v[134:135]
	global_load_dwordx4 v[118:121], v[66:67], off
	global_load_dwordx4 v[122:125], v[68:69], off offset:256
	global_load_dwordx4 v[126:129], v[66:67], off offset:256
	v_add_u32_e32 v66, 0x90, v200
	v_ashrrev_i32_e32 v67, 31, v66
	v_mad_i64_i32 v[68:69], s[24:25], v66, s19, v[202:203]
	v_lshlrev_b64 v[136:137], 13, v[66:67]
	v_lshl_add_u64 v[66:67], v[204:205], 0, v[136:137]
	global_load_dwordx4 v[130:133], v[68:69], off
	global_load_dwordx4 v[102:105], v[68:69], off offset:256
	global_load_dwordx4 v[106:109], v[66:67], off
	global_load_dwordx4 v[98:101], v[66:67], off offset:256
	v_add_u32_e32 v66, 0xa0, v200
	v_ashrrev_i32_e32 v67, 31, v66
	v_mad_i64_i32 v[68:69], s[24:25], v66, s19, v[202:203]
	v_lshlrev_b64 v[112:113], 13, v[66:67]
	v_lshl_add_u64 v[66:67], v[204:205], 0, v[112:113]
	global_load_dwordx4 v[94:97], v[68:69], off
	global_load_dwordx4 v[86:89], v[68:69], off offset:256
	global_load_dwordx4 v[90:93], v[66:67], off
	global_load_dwordx4 v[82:85], v[66:67], off offset:256
	v_add_u32_e32 v66, 0xb0, v200
	v_ashrrev_i32_e32 v67, 31, v66
	v_lshlrev_b64 v[110:111], 13, v[66:67]
	v_mad_i64_i32 v[68:69], s[24:25], v66, s19, v[202:203]
	v_lshl_add_u64 v[66:67], v[204:205], 0, v[110:111]
	global_load_dwordx4 v[78:81], v[68:69], off
	global_load_dwordx4 v[70:73], v[68:69], off offset:256
	global_load_dwordx4 v[74:77], v[66:67], off
	s_nop 0
	global_load_dwordx4 v[66:69], v[66:67], off offset:256
	v_lshl_add_u64 v[134:135], s[26:27], 0, v[134:135]
	v_lshl_add_u64 v[134:135], v[134:135], 0, v[198:199]
	s_waitcnt vmcnt(15)
	v_lshlrev_b32_e32 v138, 16, v114
	v_mul_f32_e32 v138, 0xbfb8aa3b, v138
	v_and_b32_e32 v114, 0xffff0000, v114
	v_exp_f32_e32 v138, v138
	v_mul_f32_e32 v114, 0xbfb8aa3b, v114
	v_lshlrev_b32_e32 v139, 16, v115
	v_exp_f32_e32 v114, v114
	v_mul_f32_e32 v139, 0xbfb8aa3b, v139
	v_and_b32_e32 v115, 0xffff0000, v115
	v_exp_f32_e32 v139, v139
	v_mul_f32_e32 v115, 0xbfb8aa3b, v115
	v_lshlrev_b32_e32 v140, 16, v116
	v_and_b32_e32 v116, 0xffff0000, v116
	v_exp_f32_e32 v115, v115
	v_mul_f32_e32 v140, 0xbfb8aa3b, v140
	v_mul_f32_e32 v116, 0xbfb8aa3b, v116
	v_add_f32_e32 v138, 1.0, v138
	v_exp_f32_e32 v140, v140
	v_exp_f32_e32 v116, v116
	v_rcp_f32_e32 v138, v138
	v_add_f32_e32 v114, 1.0, v114
	v_lshlrev_b32_e32 v141, 16, v117
	v_rcp_f32_e32 v114, v114
	v_add_f32_e32 v139, 1.0, v139
	v_mul_f32_e32 v141, 0xbfb8aa3b, v141
	v_and_b32_e32 v117, 0xffff0000, v117
	v_rcp_f32_e32 v139, v139
	v_add_f32_e32 v115, 1.0, v115
	v_exp_f32_e32 v141, v141
	v_mul_f32_e32 v117, 0xbfb8aa3b, v117
	v_rcp_f32_e32 v115, v115
	v_add_f32_e32 v140, 1.0, v140
	v_add_f32_e32 v116, 1.0, v116
	v_exp_f32_e32 v117, v117
	s_waitcnt vmcnt(14)
	v_lshlrev_b32_e32 v142, 16, v118
	v_rcp_f32_e32 v140, v140
	v_rcp_f32_e32 v116, v116
	v_fmac_f32_e32 v142, v62, v138
	v_and_b32_e32 v62, 0xffff0000, v118
	v_fmac_f32_e32 v62, v63, v114
	v_lshlrev_b32_e32 v63, 16, v119
	v_add_f32_e32 v141, 1.0, v141
	v_fmac_f32_e32 v63, v64, v139
	v_and_b32_e32 v64, 0xffff0000, v119
	v_rcp_f32_e32 v141, v141
	v_add_f32_e32 v117, 1.0, v117
	v_fmac_f32_e32 v64, v65, v115
	v_lshlrev_b32_e32 v65, 16, v120
	v_and_b32_e32 v114, 0xffff0000, v120
	v_rcp_f32_e32 v117, v117
	v_fmac_f32_e32 v65, v58, v140
	v_fmac_f32_e32 v114, v59, v116
	v_cvt_pk_bf16_f32 v58, v142, v62
	v_cvt_pk_bf16_f32 v59, v63, v64
	s_waitcnt vmcnt(13)
	v_lshlrev_b32_e32 v62, 16, v122
	v_and_b32_e32 v63, 0xffff0000, v122
	v_mul_f32_e32 v62, 0xbfb8aa3b, v62
	v_mul_f32_e32 v63, 0xbfb8aa3b, v63
	v_lshlrev_b32_e32 v115, 16, v121
	v_exp_f32_e32 v62, v62
	v_exp_f32_e32 v63, v63
	v_fmac_f32_e32 v115, v60, v141
	v_and_b32_e32 v116, 0xffff0000, v121
	v_cvt_pk_bf16_f32 v60, v65, v114
	v_fmac_f32_e32 v116, v61, v117
	v_cvt_pk_bf16_f32 v61, v115, v116
	global_store_dwordx4 v[134:135], v[58:61], off sc1
	v_lshlrev_b32_e32 v64, 16, v125
	v_mul_f32_e32 v64, 0xbfb8aa3b, v64
	v_lshlrev_b32_e32 v60, 16, v123
	v_mul_f32_e32 v60, 0xbfb8aa3b, v60
	v_and_b32_e32 v61, 0xffff0000, v123
	v_add_f32_e32 v58, 1.0, v62
	v_add_f32_e32 v59, 1.0, v63
	v_exp_f32_e32 v60, v60
	v_mul_f32_e32 v61, 0xbfb8aa3b, v61
	v_lshlrev_b32_e32 v62, 16, v124
	v_and_b32_e32 v63, 0xffff0000, v124
	v_exp_f32_e32 v61, v61
	v_mul_f32_e32 v62, 0xbfb8aa3b, v62
	v_mul_f32_e32 v63, 0xbfb8aa3b, v63
	v_and_b32_e32 v65, 0xffff0000, v125
	v_exp_f32_e32 v62, v62
	v_exp_f32_e32 v63, v63
	v_exp_f32_e32 v64, v64
	v_mul_f32_e32 v65, 0xbfb8aa3b, v65
	v_rcp_f32_e32 v58, v58
	v_exp_f32_e32 v65, v65
	v_rcp_f32_e32 v59, v59
	v_add_f32_e32 v60, 1.0, v60
	v_rcp_f32_e32 v60, v60
	v_add_f32_e32 v61, 1.0, v61
	v_rcp_f32_e32 v61, v61
	v_add_f32_e32 v62, 1.0, v62
	v_add_f32_e32 v63, 1.0, v63
	v_add_f32_e32 v64, 1.0, v64
	s_waitcnt vmcnt(13)
; __device__ __forceinline__ unsigned cvt_pk_bf16(float lo, float hi) { unsigned r; asm volatile("v_cvt_pk_bf16_f32 %0, %1, %2" : "=v"(r) : "v"(lo), "v"(hi)); return r; }
; __device__ __forceinline__ float bf_lo(unsigned w) { return __uint_as_float(w << 16); }
; __device__ __forceinline__ float bf_hi(unsigned w) { return __uint_as_float(w & 0xffff0000u); }
; __device__ __forceinline__ float sigmoidf_(float x) { return fast_rcp(1.0f + fast_exp(-x)); }
;     __device__ __forceinline__ void operator()(const f32x4 (&acc)[2][2][4][2], const Unit& u, int wr, int wc, int fr, int fq) const {
;     ...
;             for (int m = 0; m < 4; ++m) { const size_t row = (size_t)(row0 + ai * HALF + m * 16); bf16_t* rowp = O + row * ldc + col0;
; #pragma unroll
;                 for (int bj = 0; bj < 2; ++bj) { const u32x4 gg = g[m][bj]; const f32x4 v0 = acc[ai][bj][m][0], v1 = acc[ai][bj][m][1];
;                     float o[8];
;                     o[0] = sigmoidf_(bf_lo(gg.x)) * v0[0]; o[1] = sigmoidf_(bf_hi(gg.x)) * v0[1]; o[2] = sigmoidf_(bf_lo(gg.y)) * v0[2]; o[3] = sigmoidf_(bf_hi(gg.y)) * v0[3];
;                     o[4] = sigmoidf_(bf_lo(gg.z)) * v1[0]; o[5] = sigmoidf_(bf_hi(gg.z)) * v1[1]; o[6] = sigmoidf_(bf_lo(gg.w)) * v1[2]; o[7] = sigmoidf_(bf_hi(gg.w)) * v1[3];
;                     if (ADD) { const u32x4 pp = p[m][bj];
;                         o[0] += bf_lo(pp.x); o[1] += bf_hi(pp.x); o[2] += bf_lo(pp.y); o[3] += bf_hi(pp.y); o[4] += bf_lo(pp.z); o[5] += bf_hi(pp.z); o[6] += bf_lo(pp.w); o[7] += bf_hi(pp.w); }
;                     u32x4 w; w.x = cvt_pk_bf16(o[0], o[1]); w.y = cvt_pk_bf16(o[2], o[3]); w.z = cvt_pk_bf16(o[4], o[5]); w.w = cvt_pk_bf16(o[6], o[7]);
;                     *(u32x4*)(rowp + bj * HALF) = w; } }
	v_lshlrev_b32_e32 v114, 16, v126
	v_rcp_f32_e32 v62, v62
	v_rcp_f32_e32 v63, v63
	v_rcp_f32_e32 v64, v64
	v_add_f32_e32 v65, 1.0, v65
	v_fmac_f32_e32 v114, v54, v58
	v_and_b32_e32 v54, 0xffff0000, v126
	v_rcp_f32_e32 v65, v65
	v_fmac_f32_e32 v54, v55, v59
	v_lshlrev_b32_e32 v55, 16, v127
	v_fmac_f32_e32 v55, v56, v60
	v_and_b32_e32 v56, 0xffff0000, v127
	v_fmac_f32_e32 v56, v57, v61
	v_lshlrev_b32_e32 v57, 16, v128
	v_and_b32_e32 v58, 0xffff0000, v128
	v_lshlrev_b32_e32 v59, 16, v129
	v_fmac_f32_e32 v57, v50, v62
	v_fmac_f32_e32 v58, v51, v63
	v_fmac_f32_e32 v59, v52, v64
	v_and_b32_e32 v60, 0xffff0000, v129
	v_cvt_pk_bf16_f32 v50, v114, v54
	v_cvt_pk_bf16_f32 v51, v55, v56
	v_cvt_pk_bf16_f32 v52, v57, v58
	v_fmac_f32_e32 v60, v53, v65
	v_cvt_pk_bf16_f32 v53, v59, v60
	global_store_dwordx4 v[134:135], v[50:53], off offset:256 sc1
	s_waitcnt vmcnt(13)
	v_lshlrev_b32_e32 v54, 16, v131
	v_mul_f32_e32 v54, 0xbfb8aa3b, v54
	v_lshlrev_b32_e32 v52, 16, v130
	v_mul_f32_e32 v52, 0xbfb8aa3b, v52
	v_and_b32_e32 v53, 0xffff0000, v130
	v_exp_f32_e32 v52, v52
	v_mul_f32_e32 v53, 0xbfb8aa3b, v53
	v_exp_f32_e32 v53, v53
	v_and_b32_e32 v55, 0xffff0000, v131
	v_exp_f32_e32 v54, v54
	v_mul_f32_e32 v55, 0xbfb8aa3b, v55
	v_lshlrev_b32_e32 v56, 16, v132
	v_and_b32_e32 v57, 0xffff0000, v132
	v_exp_f32_e32 v55, v55
	v_mul_f32_e32 v56, 0xbfb8aa3b, v56
	v_mul_f32_e32 v57, 0xbfb8aa3b, v57
	v_add_f32_e32 v52, 1.0, v52
	v_exp_f32_e32 v56, v56
	v_exp_f32_e32 v57, v57
	v_rcp_f32_e32 v52, v52
	v_add_f32_e32 v53, 1.0, v53
	v_lshlrev_b32_e32 v58, 16, v133
	v_rcp_f32_e32 v53, v53
	v_add_f32_e32 v54, 1.0, v54
	v_mul_f32_e32 v58, 0xbfb8aa3b, v58
	v_and_b32_e32 v59, 0xffff0000, v133
	v_rcp_f32_e32 v54, v54
	v_add_f32_e32 v55, 1.0, v55
	v_exp_f32_e32 v58, v58
	v_mul_f32_e32 v59, 0xbfb8aa3b, v59
	v_rcp_f32_e32 v55, v55
	v_add_f32_e32 v56, 1.0, v56
	v_add_f32_e32 v57, 1.0, v57
	v_exp_f32_e32 v59, v59
	s_waitcnt vmcnt(11)
	v_lshlrev_b32_e32 v60, 16, v106
	v_rcp_f32_e32 v56, v56
	v_rcp_f32_e32 v57, v57
	v_fmac_f32_e32 v60, v46, v52
	v_and_b32_e32 v46, 0xffff0000, v106
	v_fmac_f32_e32 v46, v47, v53
	v_lshlrev_b32_e32 v47, 16, v107
	v_add_f32_e32 v58, 1.0, v58
	v_fmac_f32_e32 v47, v48, v54
	v_and_b32_e32 v48, 0xffff0000, v107
	v_rcp_f32_e32 v58, v58
	v_add_f32_e32 v59, 1.0, v59
	v_fmac_f32_e32 v48, v49, v55
	v_lshlrev_b32_e32 v49, 16, v108
	v_and_b32_e32 v52, 0xffff0000, v108
	v_rcp_f32_e32 v59, v59
	v_fmac_f32_e32 v49, v42, v56
	v_fmac_f32_e32 v52, v43, v57
	v_cvt_pk_bf16_f32 v42, v60, v46
	v_cvt_pk_bf16_f32 v43, v47, v48
	v_lshlrev_b32_e32 v46, 16, v102
	v_and_b32_e32 v47, 0xffff0000, v102
	v_mul_f32_e32 v46, 0xbfb8aa3b, v46
	v_mul_f32_e32 v47, 0xbfb8aa3b, v47
	v_lshl_add_u64 v[50:51], s[26:27], 0, v[136:137]
	v_lshlrev_b32_e32 v53, 16, v109
	v_exp_f32_e32 v46, v46
	v_exp_f32_e32 v47, v47
	v_lshl_add_u64 v[50:51], v[50:51], 0, v[198:199]
	v_fmac_f32_e32 v53, v44, v58
	v_and_b32_e32 v54, 0xffff0000, v109
	v_cvt_pk_bf16_f32 v44, v49, v52
	v_fmac_f32_e32 v54, v45, v59
	v_cvt_pk_bf16_f32 v45, v53, v54
	global_store_dwordx4 v[50:51], v[42:45], off sc1
	v_lshlrev_b32_e32 v48, 16, v105
	v_mul_f32_e32 v48, 0xbfb8aa3b, v48
	v_lshlrev_b32_e32 v44, 16, v103
	v_mul_f32_e32 v44, 0xbfb8aa3b, v44
	v_and_b32_e32 v45, 0xffff0000, v103
	v_add_f32_e32 v42, 1.0, v46
	v_add_f32_e32 v43, 1.0, v47
	v_exp_f32_e32 v44, v44
	v_mul_f32_e32 v45, 0xbfb8aa3b, v45
	v_lshlrev_b32_e32 v46, 16, v104
	v_and_b32_e32 v47, 0xffff0000, v104
	v_exp_f32_e32 v45, v45
	v_mul_f32_e32 v46, 0xbfb8aa3b, v46
	v_mul_f32_e32 v47, 0xbfb8aa3b, v47
	v_and_b32_e32 v49, 0xffff0000, v105
	v_exp_f32_e32 v46, v46
	v_exp_f32_e32 v47, v47
	v_exp_f32_e32 v48, v48
	v_mul_f32_e32 v49, 0xbfb8aa3b, v49
	v_rcp_f32_e32 v42, v42
	v_exp_f32_e32 v49, v49
	v_rcp_f32_e32 v43, v43
	v_add_f32_e32 v44, 1.0, v44
	v_rcp_f32_e32 v44, v44
	v_add_f32_e32 v45, 1.0, v45
	v_rcp_f32_e32 v45, v45
	v_add_f32_e32 v46, 1.0, v46
	v_add_f32_e32 v47, 1.0, v47
	v_add_f32_e32 v48, 1.0, v48
	s_waitcnt vmcnt(11)
	v_lshlrev_b32_e32 v52, 16, v98
	v_rcp_f32_e32 v46, v46
	v_rcp_f32_e32 v47, v47
	v_rcp_f32_e32 v48, v48
	v_add_f32_e32 v49, 1.0, v49
	v_fmac_f32_e32 v52, v38, v42
	v_and_b32_e32 v38, 0xffff0000, v98
	v_rcp_f32_e32 v49, v49
	v_fmac_f32_e32 v38, v39, v43
	v_lshlrev_b32_e32 v39, 16, v99
	v_fmac_f32_e32 v39, v40, v44
	v_and_b32_e32 v40, 0xffff0000, v99
	v_fmac_f32_e32 v40, v41, v45
	v_lshlrev_b32_e32 v41, 16, v100
	v_and_b32_e32 v42, 0xffff0000, v100
	v_lshlrev_b32_e32 v43, 16, v101
	v_fmac_f32_e32 v41, v34, v46
	v_fmac_f32_e32 v42, v35, v47
	v_fmac_f32_e32 v43, v36, v48
	v_and_b32_e32 v44, 0xffff0000, v101
	v_cvt_pk_bf16_f32 v34, v52, v38
	v_cvt_pk_bf16_f32 v35, v39, v40
	v_cvt_pk_bf16_f32 v36, v41, v42
	v_fmac_f32_e32 v44, v37, v49
	v_cvt_pk_bf16_f32 v37, v43, v44
	global_store_dwordx4 v[50:51], v[34:37], off offset:256 sc1
	s_waitcnt vmcnt(11)
	v_lshlrev_b32_e32 v38, 16, v95
	v_mul_f32_e32 v38, 0xbfb8aa3b, v38
	v_lshlrev_b32_e32 v36, 16, v94
	v_mul_f32_e32 v36, 0xbfb8aa3b, v36
	v_and_b32_e32 v37, 0xffff0000, v94
	v_exp_f32_e32 v36, v36
	v_mul_f32_e32 v37, 0xbfb8aa3b, v37
	v_exp_f32_e32 v37, v37
	v_and_b32_e32 v39, 0xffff0000, v95
	v_exp_f32_e32 v38, v38
	v_mul_f32_e32 v39, 0xbfb8aa3b, v39
	v_lshlrev_b32_e32 v40, 16, v96
	v_and_b32_e32 v41, 0xffff0000, v96
	v_exp_f32_e32 v39, v39
	v_mul_f32_e32 v40, 0xbfb8aa3b, v40
	v_mul_f32_e32 v41, 0xbfb8aa3b, v41
	v_add_f32_e32 v36, 1.0, v36
	v_exp_f32_e32 v40, v40
	v_exp_f32_e32 v41, v41
	v_rcp_f32_e32 v36, v36
	v_add_f32_e32 v37, 1.0, v37
	v_lshlrev_b32_e32 v42, 16, v97
	v_rcp_f32_e32 v37, v37
	v_add_f32_e32 v38, 1.0, v38
	v_mul_f32_e32 v42, 0xbfb8aa3b, v42
	v_and_b32_e32 v43, 0xffff0000, v97
	v_rcp_f32_e32 v38, v38
	v_add_f32_e32 v39, 1.0, v39
	v_exp_f32_e32 v42, v42
	v_mul_f32_e32 v43, 0xbfb8aa3b, v43
	v_rcp_f32_e32 v39, v39
	v_add_f32_e32 v40, 1.0, v40
	v_add_f32_e32 v41, 1.0, v41
	v_exp_f32_e32 v43, v43
	s_waitcnt vmcnt(9)
; __device__ __forceinline__ unsigned cvt_pk_bf16(float lo, float hi) { unsigned r; asm volatile("v_cvt_pk_bf16_f32 %0, %1, %2" : "=v"(r) : "v"(lo), "v"(hi)); return r; }
; __device__ __forceinline__ float bf_lo(unsigned w) { return __uint_as_float(w << 16); }
; __device__ __forceinline__ float bf_hi(unsigned w) { return __uint_as_float(w & 0xffff0000u); }
; __device__ __forceinline__ float sigmoidf_(float x) { return fast_rcp(1.0f + fast_exp(-x)); }
;     __device__ __forceinline__ void operator()(const f32x4 (&acc)[2][2][4][2], const Unit& u, int wr, int wc, int fr, int fq) const {
;     ...
;             for (int m = 0; m < 4; ++m) { const size_t row = (size_t)(row0 + ai * HALF + m * 16); bf16_t* rowp = O + row * ldc + col0;
; #pragma unroll
;                 for (int bj = 0; bj < 2; ++bj) { const u32x4 gg = g[m][bj]; const f32x4 v0 = acc[ai][bj][m][0], v1 = acc[ai][bj][m][1];
;                     float o[8];
;                     o[0] = sigmoidf_(bf_lo(gg.x)) * v0[0]; o[1] = sigmoidf_(bf_hi(gg.x)) * v0[1]; o[2] = sigmoidf_(bf_lo(gg.y)) * v0[2]; o[3] = sigmoidf_(bf_hi(gg.y)) * v0[3];
;                     o[4] = sigmoidf_(bf_lo(gg.z)) * v1[0]; o[5] = sigmoidf_(bf_hi(gg.z)) * v1[1]; o[6] = sigmoidf_(bf_lo(gg.w)) * v1[2]; o[7] = sigmoidf_(bf_hi(gg.w)) * v1[3];
;                     if (ADD) { const u32x4 pp = p[m][bj];
;                         o[0] += bf_lo(pp.x); o[1] += bf_hi(pp.x); o[2] += bf_lo(pp.y); o[3] += bf_hi(pp.y); o[4] += bf_lo(pp.z); o[5] += bf_hi(pp.z); o[6] += bf_lo(pp.w); o[7] += bf_hi(pp.w); }
;                     u32x4 w; w.x = cvt_pk_bf16(o[0], o[1]); w.y = cvt_pk_bf16(o[2], o[3]); w.z = cvt_pk_bf16(o[4], o[5]); w.w = cvt_pk_bf16(o[6], o[7]);
;                     *(u32x4*)(rowp + bj * HALF) = w; } }
;             asm volatile("" ::: "memory");
;         }
	v_lshlrev_b32_e32 v44, 16, v90
	v_rcp_f32_e32 v40, v40
	v_rcp_f32_e32 v41, v41
	v_fmac_f32_e32 v44, v30, v36
	v_and_b32_e32 v30, 0xffff0000, v90
	v_fmac_f32_e32 v30, v31, v37
	v_lshlrev_b32_e32 v31, 16, v91
	v_add_f32_e32 v42, 1.0, v42
	v_fmac_f32_e32 v31, v32, v38
	v_and_b32_e32 v32, 0xffff0000, v91
	v_rcp_f32_e32 v42, v42
	v_add_f32_e32 v43, 1.0, v43
	v_fmac_f32_e32 v32, v33, v39
	v_lshlrev_b32_e32 v33, 16, v92
	v_and_b32_e32 v36, 0xffff0000, v92
	v_rcp_f32_e32 v43, v43
	v_fmac_f32_e32 v33, v26, v40
	v_fmac_f32_e32 v36, v27, v41
	v_cvt_pk_bf16_f32 v26, v44, v30
	v_cvt_pk_bf16_f32 v27, v31, v32
	v_lshlrev_b32_e32 v30, 16, v86
	v_and_b32_e32 v31, 0xffff0000, v86
	v_mul_f32_e32 v30, 0xbfb8aa3b, v30
	v_mul_f32_e32 v31, 0xbfb8aa3b, v31
	v_lshl_add_u64 v[34:35], s[26:27], 0, v[112:113]
	v_lshlrev_b32_e32 v37, 16, v93
	v_exp_f32_e32 v30, v30
	v_exp_f32_e32 v31, v31
	v_lshl_add_u64 v[34:35], v[34:35], 0, v[198:199]
	v_fmac_f32_e32 v37, v28, v42
	v_and_b32_e32 v38, 0xffff0000, v93
	v_cvt_pk_bf16_f32 v28, v33, v36
	v_fmac_f32_e32 v38, v29, v43
	v_cvt_pk_bf16_f32 v29, v37, v38
	global_store_dwordx4 v[34:35], v[26:29], off sc1
	v_lshlrev_b32_e32 v32, 16, v89
	v_mul_f32_e32 v32, 0xbfb8aa3b, v32
	v_lshlrev_b32_e32 v28, 16, v87
	v_mul_f32_e32 v28, 0xbfb8aa3b, v28
	v_and_b32_e32 v29, 0xffff0000, v87
	v_add_f32_e32 v26, 1.0, v30
	v_add_f32_e32 v27, 1.0, v31
	v_exp_f32_e32 v28, v28
	v_mul_f32_e32 v29, 0xbfb8aa3b, v29
	v_lshlrev_b32_e32 v30, 16, v88
	v_and_b32_e32 v31, 0xffff0000, v88
	v_exp_f32_e32 v29, v29
	v_mul_f32_e32 v30, 0xbfb8aa3b, v30
	v_mul_f32_e32 v31, 0xbfb8aa3b, v31
	v_and_b32_e32 v33, 0xffff0000, v89
	v_exp_f32_e32 v30, v30
	v_exp_f32_e32 v31, v31
	v_exp_f32_e32 v32, v32
	v_mul_f32_e32 v33, 0xbfb8aa3b, v33
	v_rcp_f32_e32 v26, v26
	v_exp_f32_e32 v33, v33
	v_rcp_f32_e32 v27, v27
	v_add_f32_e32 v28, 1.0, v28
	v_rcp_f32_e32 v28, v28
	v_add_f32_e32 v29, 1.0, v29
	v_rcp_f32_e32 v29, v29
	v_add_f32_e32 v30, 1.0, v30
	v_add_f32_e32 v31, 1.0, v31
	v_add_f32_e32 v32, 1.0, v32
	s_waitcnt vmcnt(9)
	v_lshlrev_b32_e32 v36, 16, v82
	v_rcp_f32_e32 v30, v30
	v_rcp_f32_e32 v31, v31
	v_rcp_f32_e32 v32, v32
	v_add_f32_e32 v33, 1.0, v33
	v_fmac_f32_e32 v36, v22, v26
	v_and_b32_e32 v22, 0xffff0000, v82
	v_rcp_f32_e32 v33, v33
	v_fmac_f32_e32 v22, v23, v27
	v_lshlrev_b32_e32 v23, 16, v83
	v_fmac_f32_e32 v23, v24, v28
	v_and_b32_e32 v24, 0xffff0000, v83
	v_fmac_f32_e32 v24, v25, v29
	v_lshlrev_b32_e32 v25, 16, v84
	v_and_b32_e32 v26, 0xffff0000, v84
	v_lshlrev_b32_e32 v27, 16, v85
	v_fmac_f32_e32 v25, v18, v30
	v_fmac_f32_e32 v26, v19, v31
	v_fmac_f32_e32 v27, v20, v32
	v_and_b32_e32 v28, 0xffff0000, v85
	v_cvt_pk_bf16_f32 v18, v36, v22
	v_cvt_pk_bf16_f32 v19, v23, v24
	v_cvt_pk_bf16_f32 v20, v25, v26
	v_fmac_f32_e32 v28, v21, v33
	v_cvt_pk_bf16_f32 v21, v27, v28
	global_store_dwordx4 v[34:35], v[18:21], off offset:256 sc1
	s_waitcnt vmcnt(9)
	v_lshlrev_b32_e32 v22, 16, v79
	v_mul_f32_e32 v22, 0xbfb8aa3b, v22
	v_lshlrev_b32_e32 v20, 16, v78
	v_mul_f32_e32 v20, 0xbfb8aa3b, v20
	v_and_b32_e32 v21, 0xffff0000, v78
	v_exp_f32_e32 v20, v20
	v_mul_f32_e32 v21, 0xbfb8aa3b, v21
	v_exp_f32_e32 v21, v21
	v_and_b32_e32 v23, 0xffff0000, v79
	v_exp_f32_e32 v22, v22
	v_mul_f32_e32 v23, 0xbfb8aa3b, v23
	v_lshlrev_b32_e32 v24, 16, v80
	v_and_b32_e32 v25, 0xffff0000, v80
	v_exp_f32_e32 v23, v23
	v_mul_f32_e32 v24, 0xbfb8aa3b, v24
	v_mul_f32_e32 v25, 0xbfb8aa3b, v25
	v_add_f32_e32 v20, 1.0, v20
	v_exp_f32_e32 v24, v24
	v_exp_f32_e32 v25, v25
	v_rcp_f32_e32 v20, v20
	v_add_f32_e32 v21, 1.0, v21
	v_lshlrev_b32_e32 v26, 16, v81
	v_rcp_f32_e32 v21, v21
	v_add_f32_e32 v22, 1.0, v22
	v_mul_f32_e32 v26, 0xbfb8aa3b, v26
	v_and_b32_e32 v27, 0xffff0000, v81
	v_rcp_f32_e32 v22, v22
	v_add_f32_e32 v23, 1.0, v23
	v_exp_f32_e32 v26, v26
	v_mul_f32_e32 v27, 0xbfb8aa3b, v27
	v_rcp_f32_e32 v23, v23
	v_add_f32_e32 v24, 1.0, v24
	v_add_f32_e32 v25, 1.0, v25
	v_exp_f32_e32 v27, v27
	s_waitcnt vmcnt(7)
	v_lshlrev_b32_e32 v28, 16, v74
	v_rcp_f32_e32 v24, v24
	v_rcp_f32_e32 v25, v25
	v_fmac_f32_e32 v28, v14, v20
	v_and_b32_e32 v14, 0xffff0000, v74
	v_fmac_f32_e32 v14, v15, v21
	v_lshlrev_b32_e32 v15, 16, v75
	v_add_f32_e32 v26, 1.0, v26
	v_fmac_f32_e32 v15, v16, v22
	v_and_b32_e32 v16, 0xffff0000, v75
	v_rcp_f32_e32 v26, v26
	v_add_f32_e32 v27, 1.0, v27
	v_fmac_f32_e32 v16, v17, v23
	v_lshlrev_b32_e32 v17, 16, v76
	v_and_b32_e32 v20, 0xffff0000, v76
	v_rcp_f32_e32 v27, v27
	v_fmac_f32_e32 v17, v10, v24
	v_fmac_f32_e32 v20, v11, v25
	v_cvt_pk_bf16_f32 v10, v28, v14
	v_cvt_pk_bf16_f32 v11, v15, v16
	v_lshlrev_b32_e32 v14, 16, v70
	v_and_b32_e32 v15, 0xffff0000, v70
	v_mul_f32_e32 v14, 0xbfb8aa3b, v14
	v_mul_f32_e32 v15, 0xbfb8aa3b, v15
	v_lshl_add_u64 v[18:19], s[26:27], 0, v[110:111]
	v_lshlrev_b32_e32 v21, 16, v77
	v_exp_f32_e32 v14, v14
	v_exp_f32_e32 v15, v15
	v_lshl_add_u64 v[18:19], v[18:19], 0, v[198:199]
	v_fmac_f32_e32 v21, v12, v26
	v_and_b32_e32 v22, 0xffff0000, v77
	v_cvt_pk_bf16_f32 v12, v17, v20
	v_fmac_f32_e32 v22, v13, v27
	v_cvt_pk_bf16_f32 v13, v21, v22
	global_store_dwordx4 v[18:19], v[10:13], off sc1
	v_lshlrev_b32_e32 v16, 16, v73
	v_and_b32_e32 v17, 0xffff0000, v73
	v_lshlrev_b32_e32 v12, 16, v71
	v_mul_f32_e32 v12, 0xbfb8aa3b, v12
	v_and_b32_e32 v13, 0xffff0000, v71
	v_add_f32_e32 v10, 1.0, v14
	v_add_f32_e32 v11, 1.0, v15
	v_exp_f32_e32 v12, v12
	v_mul_f32_e32 v13, 0xbfb8aa3b, v13
	v_lshlrev_b32_e32 v14, 16, v72
	v_and_b32_e32 v15, 0xffff0000, v72
	v_exp_f32_e32 v13, v13
	v_mul_f32_e32 v14, 0xbfb8aa3b, v14
	v_mul_f32_e32 v15, 0xbfb8aa3b, v15
	v_mul_f32_e32 v16, 0xbfb8aa3b, v16
	v_mul_f32_e32 v17, 0xbfb8aa3b, v17
	v_exp_f32_e32 v14, v14
	v_exp_f32_e32 v15, v15
	v_exp_f32_e32 v16, v16
	v_exp_f32_e32 v17, v17
	v_rcp_f32_e32 v10, v10
	v_rcp_f32_e32 v11, v11
	v_add_f32_e32 v12, 1.0, v12
	v_rcp_f32_e32 v12, v12
	v_add_f32_e32 v13, 1.0, v13
	v_rcp_f32_e32 v13, v13
	v_add_f32_e32 v14, 1.0, v14
	v_add_f32_e32 v15, 1.0, v15
	v_add_f32_e32 v16, 1.0, v16
	v_add_f32_e32 v17, 1.0, v17
	s_waitcnt vmcnt(7)
	v_lshlrev_b32_e32 v20, 16, v66
	v_rcp_f32_e32 v14, v14
	v_rcp_f32_e32 v15, v15
	v_rcp_f32_e32 v16, v16
	v_rcp_f32_e32 v17, v17
	v_fmac_f32_e32 v20, v6, v10
	v_and_b32_e32 v6, 0xffff0000, v66
	v_fmac_f32_e32 v6, v7, v11
	v_lshlrev_b32_e32 v7, 16, v67
	v_fmac_f32_e32 v7, v8, v12
	v_and_b32_e32 v8, 0xffff0000, v67
	v_fmac_f32_e32 v8, v9, v13
	v_lshlrev_b32_e32 v9, 16, v68
	v_and_b32_e32 v10, 0xffff0000, v68
	v_lshlrev_b32_e32 v11, 16, v69
	v_and_b32_e32 v12, 0xffff0000, v69
	v_fmac_f32_e32 v9, v2, v14
	v_fmac_f32_e32 v10, v3, v15
	v_fmac_f32_e32 v11, v4, v16
	v_fmac_f32_e32 v12, v5, v17
	v_cvt_pk_bf16_f32 v2, v20, v6
	v_cvt_pk_bf16_f32 v3, v7, v8
	v_cvt_pk_bf16_f32 v4, v9, v10
	v_cvt_pk_bf16_f32 v5, v11, v12
	global_store_dwordx4 v[18:19], v[2:5], off offset:256 sc1
	s_cbranch_vccnz .LBB0_571
	s_andn2_b64 vcc, exec, s[0:1]
	s_cbranch_vccnz .LBB0_570
	s_barrier
	s_branch .LBB0_570

; __device__ __forceinline__ unsigned cvt_pk_bf16(float lo, float hi) { unsigned r; asm volatile("v_cvt_pk_bf16_f32 %0, %1, %2" : "=v"(r) : "v"(lo), "v"(hi)); return r; }
;     __device__ __forceinline__ void operator()(const f32x4 (&acc)[2][2][4][2], const Unit& u, int wr, int wc, int fr, int fq) const {
;         const int row0 = u.pm * BM + wr * 64 + fr, col0 = u.pn * BM + wc * 32 + 8 * fq;
; #pragma unroll
;         for (int ai = 0; ai < 2; ++ai)
; #pragma unroll
;             for (int m = 0; m < 4; ++m) { bf16_t* rowp = O + (size_t)(row0 + ai * HALF + m * 16) * ldc + col0;
; #pragma unroll
;                 for (int bj = 0; bj < 2; ++bj) { const f32x4 v0 = acc[ai][bj][m][0], v1 = acc[ai][bj][m][1];
;                     u32x4 w; w.x = cvt_pk_bf16(v0[0], v0[1]); w.y = cvt_pk_bf16(v0[2], v0[3]); w.z = cvt_pk_bf16(v1[0], v1[1]); w.w = cvt_pk_bf16(v1[2], v1[3]);
;                     *(u32x4*)(rowp + bj * HALF) = w; } }
.LBB0_663:
	v_lshl_add_u32 v154, s62, 8, v1
	v_lshl_or_b32 v146, s26, 8, v149
	v_ashrrev_i32_e32 v155, 31, v154
	v_ashrrev_i32_e32 v147, 31, v146
	v_lshlrev_b64 v[156:157], 13, v[154:155]
	v_lshl_add_u64 v[156:157], s[14:15], 0, v[156:157]
	v_lshlrev_b64 v[158:159], 1, v[146:147]
	v_lshl_add_u64 v[146:147], v[156:157], 0, v[158:159]
	v_cvt_pk_bf16_f32 v126, v126, v127
	v_cvt_pk_bf16_f32 v127, v128, v129
	v_cvt_pk_bf16_f32 v128, v122, v123
	v_cvt_pk_bf16_f32 v129, v124, v125
	global_store_dwordx4 v[146:147], v[126:129], off sc1
	v_cvt_pk_bf16_f32 v114, v114, v115
	v_cvt_pk_bf16_f32 v115, v116, v117
	v_cvt_pk_bf16_f32 v116, v106, v107
	v_or_b32_e32 v106, 16, v154
	v_ashrrev_i32_e32 v107, 31, v106
	v_lshlrev_b64 v[106:107], 13, v[106:107]
	v_lshl_add_u64 v[106:107], s[14:15], 0, v[106:107]
	v_cvt_pk_bf16_f32 v117, v108, v109
	global_store_dwordx4 v[146:147], v[114:117], off offset:256 sc1
	s_mov_b64 s[0:1], -1
	s_nop 0
	v_lshl_add_u64 v[114:115], v[106:107], 0, v[158:159]
	v_cvt_pk_bf16_f32 v106, v118, v119
	v_cvt_pk_bf16_f32 v107, v120, v121
	v_cvt_pk_bf16_f32 v108, v110, v111
	v_cvt_pk_bf16_f32 v109, v112, v113
	global_store_dwordx4 v[114:115], v[106:109], off sc1
	v_cvt_pk_bf16_f32 v98, v98, v99
	v_cvt_pk_bf16_f32 v99, v100, v101
	v_cvt_pk_bf16_f32 v100, v90, v91
	v_or_b32_e32 v90, 32, v154
	v_ashrrev_i32_e32 v91, 31, v90
	v_lshlrev_b64 v[90:91], 13, v[90:91]
	v_lshl_add_u64 v[90:91], s[14:15], 0, v[90:91]
	v_cvt_pk_bf16_f32 v101, v92, v93
	global_store_dwordx4 v[114:115], v[98:101], off offset:256 sc1
	s_nop 1
	v_lshl_add_u64 v[98:99], v[90:91], 0, v[158:159]
	v_cvt_pk_bf16_f32 v90, v102, v103
	v_cvt_pk_bf16_f32 v91, v104, v105
	v_cvt_pk_bf16_f32 v92, v94, v95
	v_cvt_pk_bf16_f32 v93, v96, v97
	global_store_dwordx4 v[98:99], v[90:93], off sc1
	v_cvt_pk_bf16_f32 v82, v82, v83
	v_cvt_pk_bf16_f32 v83, v84, v85
	v_cvt_pk_bf16_f32 v84, v74, v75
	v_or_b32_e32 v74, 48, v154
	v_ashrrev_i32_e32 v75, 31, v74
	v_lshlrev_b64 v[74:75], 13, v[74:75]
	v_lshl_add_u64 v[74:75], s[14:15], 0, v[74:75]
	v_cvt_pk_bf16_f32 v85, v76, v77
	global_store_dwordx4 v[98:99], v[82:85], off offset:256 sc1
	s_nop 1
	v_lshl_add_u64 v[82:83], v[74:75], 0, v[158:159]
	v_cvt_pk_bf16_f32 v74, v86, v87
	v_cvt_pk_bf16_f32 v75, v88, v89
	v_cvt_pk_bf16_f32 v76, v78, v79
	v_cvt_pk_bf16_f32 v77, v80, v81
	global_store_dwordx4 v[82:83], v[74:77], off sc1
	v_cvt_pk_bf16_f32 v70, v70, v71
	v_cvt_pk_bf16_f32 v71, v72, v73
	v_cvt_pk_bf16_f32 v72, v66, v67
	v_cvt_pk_bf16_f32 v73, v68, v69
	global_store_dwordx4 v[82:83], v[70:73], off offset:256 sc1
	v_cvt_pk_bf16_f32 v62, v62, v63
	v_cvt_pk_bf16_f32 v63, v64, v65
	v_cvt_pk_bf16_f32 v64, v58, v59
	v_add_co_u32_e32 v58, vcc, s22, v146
	v_lshl_add_u64 v[66:67], v[146:147], 0, s[4:5]
	s_nop 0
	v_addc_co_u32_e32 v59, vcc, 0, v147, vcc
	v_cvt_pk_bf16_f32 v65, v60, v61
	global_store_dwordx4 v[58:59], v[62:65], off sc1
	v_cvt_pk_bf16_f32 v50, v50, v51
	v_cvt_pk_bf16_f32 v51, v52, v53
	v_cvt_pk_bf16_f32 v52, v42, v43
	v_cvt_pk_bf16_f32 v53, v44, v45
	global_store_dwordx4 v[66:67], v[50:53], off offset:256 sc1
	v_cvt_pk_bf16_f32 v42, v54, v55
	v_cvt_pk_bf16_f32 v43, v56, v57
	v_cvt_pk_bf16_f32 v44, v46, v47
	v_add_co_u32_e32 v46, vcc, s23, v146
	s_nop 0
	v_lshl_add_u64 v[50:51], v[146:147], 0, s[48:49]
	v_addc_co_u32_e32 v47, vcc, 0, v147, vcc
	v_cvt_pk_bf16_f32 v45, v48, v49
	global_store_dwordx4 v[46:47], v[42:45], off sc1
	v_cvt_pk_bf16_f32 v34, v34, v35
	v_cvt_pk_bf16_f32 v35, v36, v37
	v_cvt_pk_bf16_f32 v36, v26, v27
	v_cvt_pk_bf16_f32 v37, v28, v29
	global_store_dwordx4 v[50:51], v[34:37], off offset:256 sc1
	v_cvt_pk_bf16_f32 v26, v38, v39
	v_cvt_pk_bf16_f32 v27, v40, v41
	v_cvt_pk_bf16_f32 v28, v30, v31
	v_add_co_u32_e32 v30, vcc, s24, v146
	s_nop 0
	v_lshl_add_u64 v[34:35], v[146:147], 0, s[50:51]
	v_addc_co_u32_e32 v31, vcc, 0, v147, vcc
	v_cvt_pk_bf16_f32 v29, v32, v33
	global_store_dwordx4 v[30:31], v[26:29], off sc1
	v_cvt_pk_bf16_f32 v18, v18, v19
	v_cvt_pk_bf16_f32 v19, v20, v21
	v_cvt_pk_bf16_f32 v20, v10, v11
	v_cvt_pk_bf16_f32 v21, v12, v13
	global_store_dwordx4 v[34:35], v[18:21], off offset:256 sc1
	v_cvt_pk_bf16_f32 v10, v22, v23
	v_cvt_pk_bf16_f32 v11, v24, v25
	v_cvt_pk_bf16_f32 v12, v14, v15
	v_add_co_u32_e32 v14, vcc, s25, v146
	s_nop 0
	v_lshl_add_u64 v[18:19], v[146:147], 0, s[52:53]
	v_addc_co_u32_e32 v15, vcc, 0, v147, vcc
	s_and_b64 vcc, exec, s[2:3]
	v_cvt_pk_bf16_f32 v13, v16, v17
	global_store_dwordx4 v[14:15], v[10:13], off sc1
	v_cvt_pk_bf16_f32 v6, v6, v7
	v_cvt_pk_bf16_f32 v7, v8, v9
	v_cvt_pk_bf16_f32 v8, v2, v3
	v_cvt_pk_bf16_f32 v9, v4, v5
	global_store_dwordx4 v[18:19], v[6:9], off offset:256 sc1
	s_cbranch_vccnz .LBB0_650
	s_andn2_b64 vcc, exec, s[38:39]
	s_cbranch_vccnz .LBB0_649
	s_barrier
	s_branch .LBB0_649

; #define PG8_LAS __attribute__((address_space(3)))
; __device__ __forceinline__ unsigned cvt_pk_bf16(float lo, float hi) { unsigned r; asm volatile("v_cvt_pk_bf16_f32 %0, %1, %2" : "=v"(r) : "v"(lo), "v"(hi)); return r; }
; __device__ __forceinline__ float siluf_(float x) { return x * sigmoidf_(x); }
;     __device__ __forceinline__ void operator()(const i32x4 (&acc)[2][2][4][2], const Unit& u, int wr, int wc, int fr, int fq, const PG8_LAS float* sb) const {
;         const int row0 = u.pm * BM + wr * 64 + fr, col0 = u.pn * HALF + wc * 32 + 8 * fq, ccol0 = u.pn * BM + wc * 32 + 8 * fq;
;         f32x4 sv[2][2];
; #pragma unroll
;         for (int bj = 0; bj < 2; ++bj)
; #pragma unroll
;             for (int n = 0; n < 2; ++n) sv[bj][n] = *(const PG8_LAS f32x4*)(sb + wc * 32 + 8 * fq + bj * HALF + 4 * n);
; #pragma unroll
;         for (int ai = 0; ai < 2; ++ai)
; #pragma unroll
;             for (int m = 0; m < 4; ++m) { const int row = row0 + ai * HALF + m * 16; const float r = sb[256 + wr * 64 + fr + ai * HALF + m * 16]; bf16_t* rowp = O + (size_t)row * ldc + col0;
;                 const f32x4 g0 = __builtin_convertvector(acc[ai][0][m][0], f32x4) * sv[0][0] * r, g1 = __builtin_convertvector(acc[ai][0][m][1], f32x4) * sv[0][1] * r;
;                 const f32x4 u0 = __builtin_convertvector(acc[ai][1][m][0], f32x4) * sv[1][0] * r, u1 = __builtin_convertvector(acc[ai][1][m][1], f32x4) * sv[1][1] * r;
;                 u32x4 w; w.x = cvt_pk_bf16(siluf_(g0[0]) * u0[0], siluf_(g0[1]) * u0[1]); w.y = cvt_pk_bf16(siluf_(g0[2]) * u0[2], siluf_(g0[3]) * u0[3]);
;                 w.z = cvt_pk_bf16(siluf_(g1[0]) * u1[0], siluf_(g1[1]) * u1[1]); w.w = cvt_pk_bf16(siluf_(g1[2]) * u1[2], siluf_(g1[3]) * u1[3]);
;                 *(u32x4*)rowp = w; }
.LBB0_844:
	s_lshl_b32 s55, s55, 11
	s_and_b32 s55, s55, 0x800
	s_add_i32 s55, s55, 0
	s_add_i32 s55, s55, 0x20400
	v_lshl_add_u32 v176, s54, 8, v170
	s_lshl_b32 s54, s21, 2
	v_lshl_or_b32 v182, s35, 7, v172
	s_lshl_b32 s35, s20, 2
	s_add_i32 s54, s55, s54
	s_add_i32 s55, s55, s35
	v_lshl_add_u32 v90, v168, 2, s54
	v_lshl_add_u32 v177, v169, 2, s55
	ds_read_b128 v[106:109], v90
	ds_read_b128 v[98:101], v90 offset:16
	ds_read_b128 v[94:97], v90 offset:512
	ds_read_b128 v[90:93], v90 offset:528
	ds_read_b32 v184, v177 offset:1024
	v_cvt_f32_i32_e32 v189, v143
	v_cvt_f32_i32_e32 v188, v142
	v_cvt_f32_i32_e32 v145, v145
	v_cvt_f32_i32_e32 v144, v144
	v_cvt_f32_i32_e32 v139, v139
	v_cvt_f32_i32_e32 v141, v141
	v_cvt_f32_i32_e32 v140, v140
	v_cvt_f32_i32_e32 v138, v138
	v_cvt_f32_i32_e32 v135, v135
	v_cvt_f32_i32_e32 v137, v137
	v_cvt_f32_i32_e32 v136, v136
	v_cvt_f32_i32_e32 v134, v134
	v_ashrrev_i32_e32 v183, 31, v182
	v_mov_b64_e32 v[166:167], s[22:23]
	v_mad_i64_i32 v[186:187], s[54:55], v176, s29, v[166:167]
	v_lshlrev_b64 v[142:143], 1, v[182:183]
	v_lshl_add_u64 v[182:183], v[186:187], 0, v[142:143]
	s_waitcnt lgkmcnt(0)
	v_pk_mul_f32 v[186:187], v[106:107], v[188:189]
	v_pk_mul_f32 v[144:145], v[108:109], v[144:145]
	v_pk_mul_f32 v[186:187], v[186:187], v[184:185] op_sel_hi:[1,0]
	v_pk_mul_f32 v[140:141], v[100:101], v[140:141]
	v_pk_mul_f32 v[138:139], v[98:99], v[138:139]
	v_pk_mul_f32 v[136:137], v[96:97], v[136:137]
	v_pk_mul_f32 v[134:135], v[94:95], v[134:135]
	v_pk_mul_f32 v[144:145], v[144:145], v[184:185] op_sel_hi:[1,0]
	v_pk_mul_f32 v[140:141], v[140:141], v[184:185] op_sel_hi:[1,0]
	v_pk_mul_f32 v[138:139], v[138:139], v[184:185] op_sel_hi:[1,0]
	v_cvt_f32_i32_e32 v133, v133
	v_cvt_f32_i32_e32 v132, v132
	v_pk_mul_f32 v[136:137], v[136:137], v[184:185] op_sel_hi:[1,0]
	v_pk_mul_f32 v[134:135], v[134:135], v[184:185] op_sel_hi:[1,0]
	v_mul_f32_e32 v181, 0xbfb8aa3b, v186
	v_mul_f32_e32 v185, 0xbfb8aa3b, v187
	v_exp_f32_e32 v181, v181
	v_exp_f32_e32 v185, v185
	v_pk_mul_f32 v[132:133], v[92:93], v[132:133]
	v_cvt_f32_i32_e32 v131, v131
	v_cvt_f32_i32_e32 v130, v130
	v_pk_mul_f32 v[188:189], v[132:133], v[184:185] op_sel_hi:[1,0]
	v_add_f32_e32 v132, 1.0, v181
	v_rcp_f32_e32 v181, v132
	v_add_f32_e32 v132, 1.0, v185
	v_rcp_f32_e32 v185, v132
	v_pk_mul_f32 v[130:131], v[90:91], v[130:131]
	v_cvt_f32_i32_e32 v127, v127
	v_cvt_f32_i32_e32 v126, v126
	v_pk_mul_f32 v[132:133], v[130:131], v[184:185] op_sel_hi:[1,0]
	v_mul_f32_e32 v130, v186, v181
	v_mul_f32_e32 v130, v134, v130
	v_mul_f32_e32 v134, 0xbfb8aa3b, v144
	v_mul_f32_e32 v181, 0xbfb8aa3b, v145
	v_exp_f32_e32 v134, v134
	v_exp_f32_e32 v181, v181
	v_mul_f32_e32 v131, v187, v185
	v_mul_f32_e32 v131, v135, v131
	v_add_f32_e32 v134, 1.0, v134
	v_add_f32_e32 v135, 1.0, v181
	v_rcp_f32_e32 v134, v134
	v_rcp_f32_e32 v135, v135
	v_cvt_pk_bf16_f32 v130, v130, v131
	v_cvt_f32_i32_e32 v129, v129
	v_mul_f32_e32 v131, v144, v134
	v_mul_f32_e32 v134, v145, v135
	v_mul_f32_e32 v135, 0xbfb8aa3b, v138
	v_mul_f32_e32 v131, v136, v131
	v_exp_f32_e32 v135, v135
	v_mul_f32_e32 v136, 0xbfb8aa3b, v139
	v_exp_f32_e32 v136, v136
	v_mul_f32_e32 v134, v137, v134
	v_add_f32_e32 v135, 1.0, v135
	v_rcp_f32_e32 v135, v135
	v_add_f32_e32 v136, 1.0, v136
	v_rcp_f32_e32 v136, v136
	v_cvt_pk_bf16_f32 v131, v131, v134
	v_mul_f32_e32 v134, v138, v135
	v_mul_f32_e32 v135, 0xbfb8aa3b, v140
	v_mul_f32_e32 v132, v132, v134
	v_mul_f32_e32 v134, v139, v136
	v_exp_f32_e32 v135, v135
	v_mul_f32_e32 v136, 0xbfb8aa3b, v141
	v_exp_f32_e32 v136, v136
	v_mul_f32_e32 v133, v133, v134
	v_add_f32_e32 v134, 1.0, v135
	v_rcp_f32_e32 v134, v134
	v_add_f32_e32 v135, 1.0, v136
	v_rcp_f32_e32 v135, v135
	v_cvt_pk_bf16_f32 v132, v132, v133
	v_mul_f32_e32 v133, v140, v134
	v_mul_f32_e32 v133, v188, v133
	v_mul_f32_e32 v134, v141, v135
	v_mul_f32_e32 v134, v189, v134
	v_cvt_pk_bf16_f32 v133, v133, v134
	global_store_dwordx4 v[182:183], v[130:133], off sc1
	ds_read_b32 v130, v177 offset:1088
	v_cvt_f32_i32_e32 v128, v128
	v_cvt_f32_i32_e32 v123, v123
	v_cvt_f32_i32_e32 v125, v125
	v_cvt_f32_i32_e32 v124, v124
	v_cvt_f32_i32_e32 v122, v122
	v_cvt_f32_i32_e32 v119, v119
	v_cvt_f32_i32_e32 v121, v121
	v_cvt_f32_i32_e32 v120, v120
	v_cvt_f32_i32_e32 v118, v118
	v_or_b32_e32 v131, 16, v176
	v_pk_mul_f32 v[126:127], v[106:107], v[126:127]
	v_pk_mul_f32 v[128:129], v[108:109], v[128:129]
	s_waitcnt lgkmcnt(0)
; __device__ __forceinline__ unsigned cvt_pk_bf16(float lo, float hi) { unsigned r; asm volatile("v_cvt_pk_bf16_f32 %0, %1, %2" : "=v"(r) : "v"(lo), "v"(hi)); return r; }
; __device__ __forceinline__ float siluf_(float x) { return x * sigmoidf_(x); }
;     __device__ __forceinline__ void operator()(const i32x4 (&acc)[2][2][4][2], const Unit& u, int wr, int wc, int fr, int fq, const PG8_LAS float* sb) const {
;     ...
;             for (int m = 0; m < 4; ++m) { const int row = row0 + ai * HALF + m * 16; const float r = sb[256 + wr * 64 + fr + ai * HALF + m * 16]; bf16_t* rowp = O + (size_t)row * ldc + col0;
;                 const f32x4 g0 = __builtin_convertvector(acc[ai][0][m][0], f32x4) * sv[0][0] * r, g1 = __builtin_convertvector(acc[ai][0][m][1], f32x4) * sv[0][1] * r;
;                 const f32x4 u0 = __builtin_convertvector(acc[ai][1][m][0], f32x4) * sv[1][0] * r, u1 = __builtin_convertvector(acc[ai][1][m][1], f32x4) * sv[1][1] * r;
;                 u32x4 w; w.x = cvt_pk_bf16(siluf_(g0[0]) * u0[0], siluf_(g0[1]) * u0[1]); w.y = cvt_pk_bf16(siluf_(g0[2]) * u0[2], siluf_(g0[3]) * u0[3]);
;                 w.z = cvt_pk_bf16(siluf_(g1[0]) * u1[0], siluf_(g1[1]) * u1[1]); w.w = cvt_pk_bf16(siluf_(g1[2]) * u1[2], siluf_(g1[3]) * u1[3]);
;                 *(u32x4*)rowp = w; }
	v_pk_mul_f32 v[126:127], v[126:127], v[130:131] op_sel_hi:[1,0]
	v_pk_mul_f32 v[124:125], v[100:101], v[124:125]
	v_pk_mul_f32 v[122:123], v[98:99], v[122:123]
	v_pk_mul_f32 v[120:121], v[96:97], v[120:121]
	v_pk_mul_f32 v[118:119], v[94:95], v[118:119]
	v_mad_i64_i32 v[132:133], s[54:55], v131, s29, v[166:167]
	v_pk_mul_f32 v[128:129], v[128:129], v[130:131] op_sel_hi:[1,0]
	v_pk_mul_f32 v[124:125], v[124:125], v[130:131] op_sel_hi:[1,0]
	v_pk_mul_f32 v[122:123], v[122:123], v[130:131] op_sel_hi:[1,0]
	v_cvt_f32_i32_e32 v117, v117
	v_cvt_f32_i32_e32 v116, v116
	v_pk_mul_f32 v[120:121], v[120:121], v[130:131] op_sel_hi:[1,0]
	v_pk_mul_f32 v[118:119], v[118:119], v[130:131] op_sel_hi:[1,0]
	v_mul_f32_e32 v131, 0xbfb8aa3b, v126
	v_exp_f32_e32 v131, v131
	v_pk_mul_f32 v[116:117], v[92:93], v[116:117]
	v_mul_f32_e32 v134, 0xbfb8aa3b, v127
	v_cvt_f32_i32_e32 v115, v115
	v_cvt_f32_i32_e32 v114, v114
	v_exp_f32_e32 v136, v134
	v_pk_mul_f32 v[134:135], v[116:117], v[130:131] op_sel_hi:[1,0]
	v_add_f32_e32 v116, 1.0, v131
	v_rcp_f32_e32 v131, v116
	v_pk_mul_f32 v[114:115], v[90:91], v[114:115]
	v_add_f32_e32 v116, 1.0, v136
	v_rcp_f32_e32 v136, v116
	v_pk_mul_f32 v[116:117], v[114:115], v[130:131] op_sel_hi:[1,0]
	v_mul_f32_e32 v114, v126, v131
	v_mul_f32_e32 v114, v118, v114
	v_mul_f32_e32 v118, 0xbfb8aa3b, v128
	v_mul_f32_e32 v126, 0xbfb8aa3b, v129
	v_exp_f32_e32 v118, v118
	v_exp_f32_e32 v126, v126
	v_mul_f32_e32 v115, v127, v136
	v_mul_f32_e32 v115, v119, v115
	v_add_f32_e32 v118, 1.0, v118
	v_add_f32_e32 v119, 1.0, v126
	v_rcp_f32_e32 v118, v118
	v_rcp_f32_e32 v119, v119
	v_cvt_pk_bf16_f32 v114, v114, v115
	v_lshl_add_u64 v[132:133], v[132:133], 0, v[142:143]
	v_mul_f32_e32 v115, v128, v118
	v_mul_f32_e32 v118, v129, v119
	v_mul_f32_e32 v119, 0xbfb8aa3b, v122
	v_mul_f32_e32 v115, v120, v115
	v_exp_f32_e32 v119, v119
	v_mul_f32_e32 v120, 0xbfb8aa3b, v123
	v_exp_f32_e32 v120, v120
	v_mul_f32_e32 v118, v121, v118
	v_add_f32_e32 v119, 1.0, v119
	v_rcp_f32_e32 v119, v119
	v_add_f32_e32 v120, 1.0, v120
	v_rcp_f32_e32 v120, v120
	v_cvt_pk_bf16_f32 v115, v115, v118
	v_mul_f32_e32 v118, v122, v119
	v_mul_f32_e32 v119, 0xbfb8aa3b, v124
	v_mul_f32_e32 v116, v116, v118
	v_mul_f32_e32 v118, v123, v120
	v_exp_f32_e32 v119, v119
	v_mul_f32_e32 v120, 0xbfb8aa3b, v125
	v_exp_f32_e32 v120, v120
	v_mul_f32_e32 v117, v117, v118
	v_add_f32_e32 v118, 1.0, v119
	v_rcp_f32_e32 v118, v118
	v_add_f32_e32 v119, 1.0, v120
	v_rcp_f32_e32 v119, v119
	v_cvt_pk_bf16_f32 v116, v116, v117
	v_mul_f32_e32 v117, v124, v118
	v_mul_f32_e32 v117, v134, v117
	v_mul_f32_e32 v118, v125, v119
	v_mul_f32_e32 v118, v135, v118
	v_cvt_pk_bf16_f32 v117, v117, v118
	global_store_dwordx4 v[132:133], v[114:117], off sc1
	ds_read_b32 v114, v177 offset:1152
	v_cvt_f32_i32_e32 v111, v111
	v_cvt_f32_i32_e32 v110, v110
	v_cvt_f32_i32_e32 v113, v113
	v_cvt_f32_i32_e32 v112, v112
	v_cvt_f32_i32_e32 v103, v103
	v_cvt_f32_i32_e32 v105, v105
	v_cvt_f32_i32_e32 v104, v104
	v_cvt_f32_i32_e32 v102, v102
	v_cvt_f32_i32_e32 v87, v87
	v_cvt_f32_i32_e32 v89, v89
	v_cvt_f32_i32_e32 v88, v88
	v_cvt_f32_i32_e32 v86, v86
	v_or_b32_e32 v115, 32, v176
	v_pk_mul_f32 v[110:111], v[106:107], v[110:111]
	v_pk_mul_f32 v[112:113], v[108:109], v[112:113]
	s_waitcnt lgkmcnt(0)
	v_pk_mul_f32 v[110:111], v[110:111], v[114:115] op_sel_hi:[1,0]
	v_pk_mul_f32 v[104:105], v[100:101], v[104:105]
	v_pk_mul_f32 v[102:103], v[98:99], v[102:103]
	v_pk_mul_f32 v[88:89], v[96:97], v[88:89]
	v_pk_mul_f32 v[86:87], v[94:95], v[86:87]
	v_mad_i64_i32 v[116:117], s[54:55], v115, s29, v[166:167]
	v_pk_mul_f32 v[112:113], v[112:113], v[114:115] op_sel_hi:[1,0]
	v_pk_mul_f32 v[104:105], v[104:105], v[114:115] op_sel_hi:[1,0]
	v_pk_mul_f32 v[102:103], v[102:103], v[114:115] op_sel_hi:[1,0]
	v_cvt_f32_i32_e32 v85, v85
	v_cvt_f32_i32_e32 v84, v84
	v_pk_mul_f32 v[88:89], v[88:89], v[114:115] op_sel_hi:[1,0]
	v_pk_mul_f32 v[86:87], v[86:87], v[114:115] op_sel_hi:[1,0]
	v_mul_f32_e32 v115, 0xbfb8aa3b, v110
	v_exp_f32_e32 v115, v115
	v_pk_mul_f32 v[84:85], v[92:93], v[84:85]
	v_mul_f32_e32 v118, 0xbfb8aa3b, v111
	v_cvt_f32_i32_e32 v83, v83
	v_cvt_f32_i32_e32 v82, v82
	v_exp_f32_e32 v120, v118
	v_pk_mul_f32 v[118:119], v[84:85], v[114:115] op_sel_hi:[1,0]
	v_add_f32_e32 v84, 1.0, v115
	v_rcp_f32_e32 v115, v84
	v_pk_mul_f32 v[82:83], v[90:91], v[82:83]
	v_add_f32_e32 v84, 1.0, v120
	v_rcp_f32_e32 v120, v84
	v_pk_mul_f32 v[84:85], v[82:83], v[114:115] op_sel_hi:[1,0]
	v_mul_f32_e32 v82, v110, v115
	v_mul_f32_e32 v82, v86, v82
	v_mul_f32_e32 v86, 0xbfb8aa3b, v112
	v_mul_f32_e32 v110, 0xbfb8aa3b, v113
	v_exp_f32_e32 v86, v86
	v_exp_f32_e32 v110, v110
	v_mul_f32_e32 v83, v111, v120
	v_mul_f32_e32 v83, v87, v83
	v_add_f32_e32 v86, 1.0, v86
	v_add_f32_e32 v87, 1.0, v110
	v_rcp_f32_e32 v86, v86
	v_rcp_f32_e32 v87, v87
	v_cvt_pk_bf16_f32 v82, v82, v83
	v_lshl_add_u64 v[116:117], v[116:117], 0, v[142:143]
	v_mul_f32_e32 v83, v112, v86
	v_mul_f32_e32 v86, v113, v87
	v_mul_f32_e32 v87, 0xbfb8aa3b, v102
	v_mul_f32_e32 v83, v88, v83
	v_exp_f32_e32 v87, v87
	v_mul_f32_e32 v88, 0xbfb8aa3b, v103
	v_exp_f32_e32 v88, v88
	v_mul_f32_e32 v86, v89, v86
	v_add_f32_e32 v87, 1.0, v87
	v_rcp_f32_e32 v87, v87
	v_add_f32_e32 v88, 1.0, v88
	v_rcp_f32_e32 v88, v88
	v_cvt_pk_bf16_f32 v83, v83, v86
	v_mul_f32_e32 v86, v102, v87
	v_mul_f32_e32 v87, 0xbfb8aa3b, v104
	v_mul_f32_e32 v84, v84, v86
	v_mul_f32_e32 v86, v103, v88
	v_exp_f32_e32 v87, v87
	v_mul_f32_e32 v88, 0xbfb8aa3b, v105
	v_exp_f32_e32 v88, v88
	v_mul_f32_e32 v85, v85, v86
	v_add_f32_e32 v86, 1.0, v87
	v_rcp_f32_e32 v86, v86
	v_add_f32_e32 v87, 1.0, v88
	v_rcp_f32_e32 v87, v87
	v_cvt_pk_bf16_f32 v84, v84, v85
	v_mul_f32_e32 v85, v104, v86
	v_mul_f32_e32 v85, v118, v85
	v_mul_f32_e32 v86, v105, v87
	v_mul_f32_e32 v86, v119, v86
	v_cvt_pk_bf16_f32 v85, v85, v86
	global_store_dwordx4 v[116:117], v[82:85], off sc1
	ds_read_b32 v82, v177 offset:1216
	v_cvt_f32_i32_e32 v79, v79
	v_cvt_f32_i32_e32 v78, v78
	v_cvt_f32_i32_e32 v81, v81
	v_cvt_f32_i32_e32 v80, v80
	v_cvt_f32_i32_e32 v75, v75
	v_cvt_f32_i32_e32 v77, v77
	v_cvt_f32_i32_e32 v76, v76
	v_cvt_f32_i32_e32 v74, v74
	v_cvt_f32_i32_e32 v71, v71
	v_cvt_f32_i32_e32 v73, v73
	v_cvt_f32_i32_e32 v72, v72
	v_cvt_f32_i32_e32 v70, v70
	v_or_b32_e32 v83, 48, v176
	v_pk_mul_f32 v[78:79], v[106:107], v[78:79]
	v_pk_mul_f32 v[80:81], v[108:109], v[80:81]
	s_waitcnt lgkmcnt(0)
; __device__ __forceinline__ unsigned cvt_pk_bf16(float lo, float hi) { unsigned r; asm volatile("v_cvt_pk_bf16_f32 %0, %1, %2" : "=v"(r) : "v"(lo), "v"(hi)); return r; }
; __device__ __forceinline__ float siluf_(float x) { return x * sigmoidf_(x); }
;     __device__ __forceinline__ void operator()(const i32x4 (&acc)[2][2][4][2], const Unit& u, int wr, int wc, int fr, int fq, const PG8_LAS float* sb) const {
;     ...
;             for (int m = 0; m < 4; ++m) { const int row = row0 + ai * HALF + m * 16; const float r = sb[256 + wr * 64 + fr + ai * HALF + m * 16]; bf16_t* rowp = O + (size_t)row * ldc + col0;
;                 const f32x4 g0 = __builtin_convertvector(acc[ai][0][m][0], f32x4) * sv[0][0] * r, g1 = __builtin_convertvector(acc[ai][0][m][1], f32x4) * sv[0][1] * r;
;                 const f32x4 u0 = __builtin_convertvector(acc[ai][1][m][0], f32x4) * sv[1][0] * r, u1 = __builtin_convertvector(acc[ai][1][m][1], f32x4) * sv[1][1] * r;
;                 u32x4 w; w.x = cvt_pk_bf16(siluf_(g0[0]) * u0[0], siluf_(g0[1]) * u0[1]); w.y = cvt_pk_bf16(siluf_(g0[2]) * u0[2], siluf_(g0[3]) * u0[3]);
;                 w.z = cvt_pk_bf16(siluf_(g1[0]) * u1[0], siluf_(g1[1]) * u1[1]); w.w = cvt_pk_bf16(siluf_(g1[2]) * u1[2], siluf_(g1[3]) * u1[3]);
;                 *(u32x4*)rowp = w; }
	v_pk_mul_f32 v[78:79], v[78:79], v[82:83] op_sel_hi:[1,0]
	v_pk_mul_f32 v[76:77], v[100:101], v[76:77]
	v_pk_mul_f32 v[74:75], v[98:99], v[74:75]
	v_pk_mul_f32 v[72:73], v[96:97], v[72:73]
	v_pk_mul_f32 v[70:71], v[94:95], v[70:71]
	v_mad_i64_i32 v[84:85], s[54:55], v83, s29, v[166:167]
	v_pk_mul_f32 v[80:81], v[80:81], v[82:83] op_sel_hi:[1,0]
	v_pk_mul_f32 v[76:77], v[76:77], v[82:83] op_sel_hi:[1,0]
	v_pk_mul_f32 v[74:75], v[74:75], v[82:83] op_sel_hi:[1,0]
	v_cvt_f32_i32_e32 v69, v69
	v_cvt_f32_i32_e32 v68, v68
	v_pk_mul_f32 v[72:73], v[72:73], v[82:83] op_sel_hi:[1,0]
	v_pk_mul_f32 v[70:71], v[70:71], v[82:83] op_sel_hi:[1,0]
	v_mul_f32_e32 v83, 0xbfb8aa3b, v78
	v_exp_f32_e32 v83, v83
	v_pk_mul_f32 v[68:69], v[92:93], v[68:69]
	v_mul_f32_e32 v86, 0xbfb8aa3b, v79
	v_cvt_f32_i32_e32 v67, v67
	v_cvt_f32_i32_e32 v66, v66
	v_exp_f32_e32 v88, v86
	v_pk_mul_f32 v[86:87], v[68:69], v[82:83] op_sel_hi:[1,0]
	v_add_f32_e32 v68, 1.0, v83
	v_rcp_f32_e32 v83, v68
	v_pk_mul_f32 v[66:67], v[90:91], v[66:67]
	v_add_f32_e32 v68, 1.0, v88
	v_rcp_f32_e32 v88, v68
	v_pk_mul_f32 v[68:69], v[66:67], v[82:83] op_sel_hi:[1,0]
	v_mul_f32_e32 v66, v78, v83
	v_mul_f32_e32 v66, v70, v66
	v_mul_f32_e32 v70, 0xbfb8aa3b, v80
	v_mul_f32_e32 v78, 0xbfb8aa3b, v81
	v_exp_f32_e32 v70, v70
	v_exp_f32_e32 v78, v78
	v_mul_f32_e32 v67, v79, v88
	v_mul_f32_e32 v67, v71, v67
	v_add_f32_e32 v70, 1.0, v70
	v_add_f32_e32 v71, 1.0, v78
	v_rcp_f32_e32 v70, v70
	v_rcp_f32_e32 v71, v71
	v_cvt_pk_bf16_f32 v66, v66, v67
	v_lshl_add_u64 v[84:85], v[84:85], 0, v[142:143]
	v_mul_f32_e32 v67, v80, v70
	v_mul_f32_e32 v70, v81, v71
	v_mul_f32_e32 v71, 0xbfb8aa3b, v74
	v_mul_f32_e32 v67, v72, v67
	v_exp_f32_e32 v71, v71
	v_mul_f32_e32 v72, 0xbfb8aa3b, v75
	v_exp_f32_e32 v72, v72
	v_mul_f32_e32 v70, v73, v70
	v_add_f32_e32 v71, 1.0, v71
	v_rcp_f32_e32 v71, v71
	v_add_f32_e32 v72, 1.0, v72
	v_rcp_f32_e32 v72, v72
	v_cvt_pk_bf16_f32 v67, v67, v70
	v_mul_f32_e32 v70, v74, v71
	v_mul_f32_e32 v71, 0xbfb8aa3b, v76
	v_mul_f32_e32 v68, v68, v70
	v_mul_f32_e32 v70, v75, v72
	v_exp_f32_e32 v71, v71
	v_mul_f32_e32 v72, 0xbfb8aa3b, v77
	v_exp_f32_e32 v72, v72
	v_mul_f32_e32 v69, v69, v70
	v_add_f32_e32 v70, 1.0, v71
	v_rcp_f32_e32 v70, v70
	v_add_f32_e32 v71, 1.0, v72
	v_rcp_f32_e32 v71, v71
	v_cvt_pk_bf16_f32 v68, v68, v69
	v_mul_f32_e32 v69, v76, v70
	v_mul_f32_e32 v69, v86, v69
	v_mul_f32_e32 v70, v77, v71
	v_mul_f32_e32 v70, v87, v70
	v_cvt_pk_bf16_f32 v69, v69, v70
	global_store_dwordx4 v[84:85], v[66:69], off sc1
	ds_read_b32 v66, v177 offset:1536
	v_cvt_f32_i32_e32 v63, v63
	v_cvt_f32_i32_e32 v62, v62
	v_cvt_f32_i32_e32 v65, v65
	v_cvt_f32_i32_e32 v64, v64
	v_cvt_f32_i32_e32 v59, v59
	v_cvt_f32_i32_e32 v61, v61
	v_cvt_f32_i32_e32 v60, v60
	v_cvt_f32_i32_e32 v58, v58
	v_cvt_f32_i32_e32 v55, v55
	v_cvt_f32_i32_e32 v57, v57
	v_cvt_f32_i32_e32 v56, v56
	v_cvt_f32_i32_e32 v54, v54
	v_add_u32_e32 v67, 0x80, v176
	v_pk_mul_f32 v[62:63], v[106:107], v[62:63]
	v_pk_mul_f32 v[64:65], v[108:109], v[64:65]
	s_waitcnt lgkmcnt(0)
	v_pk_mul_f32 v[62:63], v[62:63], v[66:67] op_sel_hi:[1,0]
	v_pk_mul_f32 v[60:61], v[100:101], v[60:61]
	v_pk_mul_f32 v[58:59], v[98:99], v[58:59]
	v_pk_mul_f32 v[56:57], v[96:97], v[56:57]
	v_pk_mul_f32 v[54:55], v[94:95], v[54:55]
	v_mad_i64_i32 v[68:69], s[54:55], v67, s29, v[166:167]
	v_pk_mul_f32 v[64:65], v[64:65], v[66:67] op_sel_hi:[1,0]
	v_pk_mul_f32 v[60:61], v[60:61], v[66:67] op_sel_hi:[1,0]
	v_pk_mul_f32 v[58:59], v[58:59], v[66:67] op_sel_hi:[1,0]
	v_cvt_f32_i32_e32 v53, v53
	v_cvt_f32_i32_e32 v52, v52
	v_pk_mul_f32 v[56:57], v[56:57], v[66:67] op_sel_hi:[1,0]
	v_pk_mul_f32 v[54:55], v[54:55], v[66:67] op_sel_hi:[1,0]
	v_mul_f32_e32 v67, 0xbfb8aa3b, v62
	v_exp_f32_e32 v67, v67
	v_pk_mul_f32 v[52:53], v[92:93], v[52:53]
	v_mul_f32_e32 v70, 0xbfb8aa3b, v63
	v_cvt_f32_i32_e32 v51, v51
	v_cvt_f32_i32_e32 v50, v50
	v_exp_f32_e32 v72, v70
	v_pk_mul_f32 v[70:71], v[52:53], v[66:67] op_sel_hi:[1,0]
	v_add_f32_e32 v52, 1.0, v67
	v_rcp_f32_e32 v67, v52
	v_pk_mul_f32 v[50:51], v[90:91], v[50:51]
	v_add_f32_e32 v52, 1.0, v72
	v_rcp_f32_e32 v72, v52
	v_pk_mul_f32 v[52:53], v[50:51], v[66:67] op_sel_hi:[1,0]
	v_mul_f32_e32 v50, v62, v67
	v_mul_f32_e32 v50, v54, v50
	v_mul_f32_e32 v54, 0xbfb8aa3b, v64
	v_mul_f32_e32 v62, 0xbfb8aa3b, v65
	v_exp_f32_e32 v54, v54
	v_exp_f32_e32 v62, v62
	v_mul_f32_e32 v51, v63, v72
	v_mul_f32_e32 v51, v55, v51
	v_add_f32_e32 v54, 1.0, v54
	v_add_f32_e32 v55, 1.0, v62
	v_rcp_f32_e32 v54, v54
	v_rcp_f32_e32 v55, v55
	v_cvt_pk_bf16_f32 v50, v50, v51
	v_lshl_add_u64 v[68:69], v[68:69], 0, v[142:143]
	v_mul_f32_e32 v51, v64, v54
	v_mul_f32_e32 v54, v65, v55
	v_mul_f32_e32 v55, 0xbfb8aa3b, v58
	v_mul_f32_e32 v51, v56, v51
	v_exp_f32_e32 v55, v55
	v_mul_f32_e32 v56, 0xbfb8aa3b, v59
	v_exp_f32_e32 v56, v56
	v_mul_f32_e32 v54, v57, v54
	v_add_f32_e32 v55, 1.0, v55
	v_rcp_f32_e32 v55, v55
	v_add_f32_e32 v56, 1.0, v56
	v_rcp_f32_e32 v56, v56
	v_cvt_pk_bf16_f32 v51, v51, v54
	v_mul_f32_e32 v54, v58, v55
	v_mul_f32_e32 v55, 0xbfb8aa3b, v60
	v_mul_f32_e32 v52, v52, v54
	v_mul_f32_e32 v54, v59, v56
	v_exp_f32_e32 v55, v55
	v_mul_f32_e32 v56, 0xbfb8aa3b, v61
	v_exp_f32_e32 v56, v56
	v_mul_f32_e32 v53, v53, v54
	v_add_f32_e32 v54, 1.0, v55
	v_rcp_f32_e32 v54, v54
	v_add_f32_e32 v55, 1.0, v56
	v_rcp_f32_e32 v55, v55
	v_cvt_pk_bf16_f32 v52, v52, v53
	v_mul_f32_e32 v53, v60, v54
	v_mul_f32_e32 v53, v70, v53
	v_mul_f32_e32 v54, v61, v55
	v_mul_f32_e32 v54, v71, v54
	v_cvt_pk_bf16_f32 v53, v53, v54
	global_store_dwordx4 v[68:69], v[50:53], off sc1
	ds_read_b32 v50, v177 offset:1600
	v_cvt_f32_i32_e32 v47, v47
	v_cvt_f32_i32_e32 v46, v46
	v_cvt_f32_i32_e32 v49, v49
	v_cvt_f32_i32_e32 v48, v48
	v_cvt_f32_i32_e32 v43, v43
	v_cvt_f32_i32_e32 v45, v45
	v_cvt_f32_i32_e32 v44, v44
	v_cvt_f32_i32_e32 v42, v42
	v_cvt_f32_i32_e32 v39, v39
	v_cvt_f32_i32_e32 v41, v41
	v_cvt_f32_i32_e32 v40, v40
	v_cvt_f32_i32_e32 v38, v38
	v_add_u32_e32 v51, 0x90, v176
	v_pk_mul_f32 v[46:47], v[106:107], v[46:47]
	v_pk_mul_f32 v[48:49], v[108:109], v[48:49]
	s_waitcnt lgkmcnt(0)
; __device__ __forceinline__ unsigned cvt_pk_bf16(float lo, float hi) { unsigned r; asm volatile("v_cvt_pk_bf16_f32 %0, %1, %2" : "=v"(r) : "v"(lo), "v"(hi)); return r; }
; __device__ __forceinline__ float siluf_(float x) { return x * sigmoidf_(x); }
;     __device__ __forceinline__ void operator()(const i32x4 (&acc)[2][2][4][2], const Unit& u, int wr, int wc, int fr, int fq, const PG8_LAS float* sb) const {
;     ...
;             for (int m = 0; m < 4; ++m) { const int row = row0 + ai * HALF + m * 16; const float r = sb[256 + wr * 64 + fr + ai * HALF + m * 16]; bf16_t* rowp = O + (size_t)row * ldc + col0;
;                 const f32x4 g0 = __builtin_convertvector(acc[ai][0][m][0], f32x4) * sv[0][0] * r, g1 = __builtin_convertvector(acc[ai][0][m][1], f32x4) * sv[0][1] * r;
;                 const f32x4 u0 = __builtin_convertvector(acc[ai][1][m][0], f32x4) * sv[1][0] * r, u1 = __builtin_convertvector(acc[ai][1][m][1], f32x4) * sv[1][1] * r;
;                 u32x4 w; w.x = cvt_pk_bf16(siluf_(g0[0]) * u0[0], siluf_(g0[1]) * u0[1]); w.y = cvt_pk_bf16(siluf_(g0[2]) * u0[2], siluf_(g0[3]) * u0[3]);
;                 w.z = cvt_pk_bf16(siluf_(g1[0]) * u1[0], siluf_(g1[1]) * u1[1]); w.w = cvt_pk_bf16(siluf_(g1[2]) * u1[2], siluf_(g1[3]) * u1[3]);
;                 *(u32x4*)rowp = w; }
	v_pk_mul_f32 v[46:47], v[46:47], v[50:51] op_sel_hi:[1,0]
	v_pk_mul_f32 v[44:45], v[100:101], v[44:45]
	v_pk_mul_f32 v[42:43], v[98:99], v[42:43]
	v_pk_mul_f32 v[40:41], v[96:97], v[40:41]
	v_pk_mul_f32 v[38:39], v[94:95], v[38:39]
	v_mad_i64_i32 v[52:53], s[54:55], v51, s29, v[166:167]
	v_pk_mul_f32 v[48:49], v[48:49], v[50:51] op_sel_hi:[1,0]
	v_pk_mul_f32 v[44:45], v[44:45], v[50:51] op_sel_hi:[1,0]
	v_pk_mul_f32 v[42:43], v[42:43], v[50:51] op_sel_hi:[1,0]
	v_cvt_f32_i32_e32 v37, v37
	v_cvt_f32_i32_e32 v36, v36
	v_pk_mul_f32 v[40:41], v[40:41], v[50:51] op_sel_hi:[1,0]
	v_pk_mul_f32 v[38:39], v[38:39], v[50:51] op_sel_hi:[1,0]
	v_mul_f32_e32 v51, 0xbfb8aa3b, v46
	v_exp_f32_e32 v51, v51
	v_pk_mul_f32 v[36:37], v[92:93], v[36:37]
	v_mul_f32_e32 v54, 0xbfb8aa3b, v47
	v_cvt_f32_i32_e32 v35, v35
	v_cvt_f32_i32_e32 v34, v34
	v_exp_f32_e32 v56, v54
	v_pk_mul_f32 v[54:55], v[36:37], v[50:51] op_sel_hi:[1,0]
	v_add_f32_e32 v36, 1.0, v51
	v_rcp_f32_e32 v51, v36
	v_pk_mul_f32 v[34:35], v[90:91], v[34:35]
	v_add_f32_e32 v36, 1.0, v56
	v_rcp_f32_e32 v56, v36
	v_pk_mul_f32 v[36:37], v[34:35], v[50:51] op_sel_hi:[1,0]
	v_mul_f32_e32 v34, v46, v51
	v_mul_f32_e32 v34, v38, v34
	v_mul_f32_e32 v38, 0xbfb8aa3b, v48
	v_mul_f32_e32 v46, 0xbfb8aa3b, v49
	v_exp_f32_e32 v38, v38
	v_exp_f32_e32 v46, v46
	v_mul_f32_e32 v35, v47, v56
	v_mul_f32_e32 v35, v39, v35
	v_add_f32_e32 v38, 1.0, v38
	v_add_f32_e32 v39, 1.0, v46
	v_rcp_f32_e32 v38, v38
	v_rcp_f32_e32 v39, v39
	v_cvt_pk_bf16_f32 v34, v34, v35
	v_lshl_add_u64 v[52:53], v[52:53], 0, v[142:143]
	v_mul_f32_e32 v35, v48, v38
	v_mul_f32_e32 v38, v49, v39
	v_mul_f32_e32 v39, 0xbfb8aa3b, v42
	v_mul_f32_e32 v35, v40, v35
	v_exp_f32_e32 v39, v39
	v_mul_f32_e32 v40, 0xbfb8aa3b, v43
	v_exp_f32_e32 v40, v40
	v_mul_f32_e32 v38, v41, v38
	v_add_f32_e32 v39, 1.0, v39
	v_rcp_f32_e32 v39, v39
	v_add_f32_e32 v40, 1.0, v40
	v_rcp_f32_e32 v40, v40
	v_cvt_pk_bf16_f32 v35, v35, v38
	v_mul_f32_e32 v38, v42, v39
	v_mul_f32_e32 v39, 0xbfb8aa3b, v44
	v_mul_f32_e32 v36, v36, v38
	v_mul_f32_e32 v38, v43, v40
	v_exp_f32_e32 v39, v39
	v_mul_f32_e32 v40, 0xbfb8aa3b, v45
	v_exp_f32_e32 v40, v40
	v_mul_f32_e32 v37, v37, v38
	v_add_f32_e32 v38, 1.0, v39
	v_rcp_f32_e32 v38, v38
	v_add_f32_e32 v39, 1.0, v40
	v_rcp_f32_e32 v39, v39
	v_cvt_pk_bf16_f32 v36, v36, v37
	v_mul_f32_e32 v37, v44, v38
	v_mul_f32_e32 v37, v54, v37
	v_mul_f32_e32 v38, v45, v39
	v_mul_f32_e32 v38, v55, v38
	v_cvt_pk_bf16_f32 v37, v37, v38
	global_store_dwordx4 v[52:53], v[34:37], off sc1
	ds_read_b32 v34, v177 offset:1664
	v_cvt_f32_i32_e32 v31, v31
	v_cvt_f32_i32_e32 v30, v30
	v_cvt_f32_i32_e32 v33, v33
	v_cvt_f32_i32_e32 v32, v32
	v_cvt_f32_i32_e32 v27, v27
	v_cvt_f32_i32_e32 v29, v29
	v_cvt_f32_i32_e32 v28, v28
	v_cvt_f32_i32_e32 v26, v26
	v_cvt_f32_i32_e32 v23, v23
	v_cvt_f32_i32_e32 v25, v25
	v_cvt_f32_i32_e32 v24, v24
	v_cvt_f32_i32_e32 v22, v22
	v_add_u32_e32 v35, 0xa0, v176
	v_pk_mul_f32 v[30:31], v[106:107], v[30:31]
	v_pk_mul_f32 v[32:33], v[108:109], v[32:33]
	s_waitcnt lgkmcnt(0)
; #define PG8_LAS __attribute__((address_space(3)))
; __device__ __forceinline__ unsigned cvt_pk_bf16(float lo, float hi) { unsigned r; asm volatile("v_cvt_pk_bf16_f32 %0, %1, %2" : "=v"(r) : "v"(lo), "v"(hi)); return r; }
; __device__ __forceinline__ float siluf_(float x) { return x * sigmoidf_(x); }
;     __device__ __forceinline__ void operator()(const i32x4 (&acc)[2][2][4][2], const Unit& u, int wr, int wc, int fr, int fq, const PG8_LAS float* sb) const {
;     ...
;             for (int m = 0; m < 4; ++m) { const int row = row0 + ai * HALF + m * 16; const float r = sb[256 + wr * 64 + fr + ai * HALF + m * 16]; bf16_t* rowp = O + (size_t)row * ldc + col0;
;                 const f32x4 g0 = __builtin_convertvector(acc[ai][0][m][0], f32x4) * sv[0][0] * r, g1 = __builtin_convertvector(acc[ai][0][m][1], f32x4) * sv[0][1] * r;
;                 const f32x4 u0 = __builtin_convertvector(acc[ai][1][m][0], f32x4) * sv[1][0] * r, u1 = __builtin_convertvector(acc[ai][1][m][1], f32x4) * sv[1][1] * r;
;                 u32x4 w; w.x = cvt_pk_bf16(siluf_(g0[0]) * u0[0], siluf_(g0[1]) * u0[1]); w.y = cvt_pk_bf16(siluf_(g0[2]) * u0[2], siluf_(g0[3]) * u0[3]);
;                 w.z = cvt_pk_bf16(siluf_(g1[0]) * u1[0], siluf_(g1[1]) * u1[1]); w.w = cvt_pk_bf16(siluf_(g1[2]) * u1[2], siluf_(g1[3]) * u1[3]);
;                 *(u32x4*)rowp = w; }
; __device__ __forceinline__ void stage_scales(PG8_LAS unsigned char* sb, const float* cs_tile, const float* rs_tile, int tid, int wid) {
;     const float* src = (tid < 256) ? cs_tile + tid : rs_tile + (tid - 256);
;     __builtin_amdgcn_global_load_lds((const unsigned*)src, (PG8_LAS unsigned*)(sb + wid * 256), 4, 0, 0);
; }
	v_pk_mul_f32 v[30:31], v[30:31], v[34:35] op_sel_hi:[1,0]
	v_pk_mul_f32 v[28:29], v[100:101], v[28:29]
	v_pk_mul_f32 v[26:27], v[98:99], v[26:27]
	v_pk_mul_f32 v[24:25], v[96:97], v[24:25]
	v_pk_mul_f32 v[22:23], v[94:95], v[22:23]
	v_mad_i64_i32 v[36:37], s[54:55], v35, s29, v[166:167]
	v_pk_mul_f32 v[32:33], v[32:33], v[34:35] op_sel_hi:[1,0]
	v_pk_mul_f32 v[28:29], v[28:29], v[34:35] op_sel_hi:[1,0]
	v_pk_mul_f32 v[26:27], v[26:27], v[34:35] op_sel_hi:[1,0]
	v_cvt_f32_i32_e32 v21, v21
	v_cvt_f32_i32_e32 v20, v20
	v_pk_mul_f32 v[24:25], v[24:25], v[34:35] op_sel_hi:[1,0]
	v_pk_mul_f32 v[22:23], v[22:23], v[34:35] op_sel_hi:[1,0]
	v_mul_f32_e32 v35, 0xbfb8aa3b, v30
	v_exp_f32_e32 v35, v35
	v_pk_mul_f32 v[20:21], v[92:93], v[20:21]
	v_mul_f32_e32 v38, 0xbfb8aa3b, v31
	v_cvt_f32_i32_e32 v19, v19
	v_cvt_f32_i32_e32 v18, v18
	v_exp_f32_e32 v40, v38
	v_pk_mul_f32 v[38:39], v[20:21], v[34:35] op_sel_hi:[1,0]
	v_add_f32_e32 v20, 1.0, v35
	v_rcp_f32_e32 v35, v20
	v_pk_mul_f32 v[18:19], v[90:91], v[18:19]
	v_add_f32_e32 v20, 1.0, v40
	v_rcp_f32_e32 v40, v20
	v_pk_mul_f32 v[20:21], v[18:19], v[34:35] op_sel_hi:[1,0]
	v_mul_f32_e32 v18, v30, v35
	v_mul_f32_e32 v18, v22, v18
	v_mul_f32_e32 v22, 0xbfb8aa3b, v32
	v_mul_f32_e32 v30, 0xbfb8aa3b, v33
	v_exp_f32_e32 v22, v22
	v_exp_f32_e32 v30, v30
	v_mul_f32_e32 v19, v31, v40
	v_mul_f32_e32 v19, v23, v19
	v_add_f32_e32 v22, 1.0, v22
	v_add_f32_e32 v23, 1.0, v30
	v_rcp_f32_e32 v22, v22
	v_rcp_f32_e32 v23, v23
	v_cvt_pk_bf16_f32 v18, v18, v19
	v_lshl_add_u64 v[36:37], v[36:37], 0, v[142:143]
	v_mul_f32_e32 v19, v32, v22
	v_mul_f32_e32 v22, v33, v23
	v_mul_f32_e32 v23, 0xbfb8aa3b, v26
	v_mul_f32_e32 v19, v24, v19
	v_exp_f32_e32 v23, v23
	v_mul_f32_e32 v24, 0xbfb8aa3b, v27
	v_exp_f32_e32 v24, v24
	v_mul_f32_e32 v22, v25, v22
	v_add_f32_e32 v23, 1.0, v23
	v_rcp_f32_e32 v23, v23
	v_add_f32_e32 v24, 1.0, v24
	v_rcp_f32_e32 v24, v24
	v_cvt_pk_bf16_f32 v19, v19, v22
	v_mul_f32_e32 v22, v26, v23
	v_mul_f32_e32 v23, 0xbfb8aa3b, v28
	v_mul_f32_e32 v20, v20, v22
	v_mul_f32_e32 v22, v27, v24
	v_exp_f32_e32 v23, v23
	v_mul_f32_e32 v24, 0xbfb8aa3b, v29
	v_exp_f32_e32 v24, v24
	v_mul_f32_e32 v21, v21, v22
	v_add_f32_e32 v22, 1.0, v23
	v_rcp_f32_e32 v22, v22
	v_add_f32_e32 v23, 1.0, v24
	v_rcp_f32_e32 v23, v23
	v_cvt_pk_bf16_f32 v20, v20, v21
	v_mul_f32_e32 v21, v28, v22
	v_mul_f32_e32 v21, v38, v21
	v_mul_f32_e32 v22, v29, v23
	v_mul_f32_e32 v22, v39, v22
	v_cvt_pk_bf16_f32 v21, v21, v22
	global_store_dwordx4 v[36:37], v[18:21], off sc1
	ds_read_b32 v18, v177 offset:1728
	v_cvt_f32_i32_e32 v15, v15
	v_cvt_f32_i32_e32 v14, v14
	v_cvt_f32_i32_e32 v17, v17
	v_cvt_f32_i32_e32 v16, v16
	v_cvt_f32_i32_e32 v11, v11
	v_cvt_f32_i32_e32 v13, v13
	v_cvt_f32_i32_e32 v12, v12
	v_cvt_f32_i32_e32 v10, v10
	v_cvt_f32_i32_e32 v7, v7
	v_cvt_f32_i32_e32 v9, v9
	v_cvt_f32_i32_e32 v8, v8
	v_cvt_f32_i32_e32 v6, v6
	v_add_u32_e32 v19, 0xb0, v176
	v_pk_mul_f32 v[14:15], v[106:107], v[14:15]
	v_pk_mul_f32 v[16:17], v[108:109], v[16:17]
	s_waitcnt lgkmcnt(0)
	v_pk_mul_f32 v[14:15], v[14:15], v[18:19] op_sel_hi:[1,0]
	v_pk_mul_f32 v[12:13], v[100:101], v[12:13]
	v_pk_mul_f32 v[10:11], v[98:99], v[10:11]
	v_pk_mul_f32 v[8:9], v[96:97], v[8:9]
	v_pk_mul_f32 v[6:7], v[94:95], v[6:7]
	v_mad_i64_i32 v[20:21], s[54:55], v19, s29, v[166:167]
	v_pk_mul_f32 v[16:17], v[16:17], v[18:19] op_sel_hi:[1,0]
	v_pk_mul_f32 v[12:13], v[12:13], v[18:19] op_sel_hi:[1,0]
	v_pk_mul_f32 v[10:11], v[10:11], v[18:19] op_sel_hi:[1,0]
	v_cvt_f32_i32_e32 v5, v5
	v_cvt_f32_i32_e32 v4, v4
	v_pk_mul_f32 v[8:9], v[8:9], v[18:19] op_sel_hi:[1,0]
	v_pk_mul_f32 v[6:7], v[6:7], v[18:19] op_sel_hi:[1,0]
	v_mul_f32_e32 v19, 0xbfb8aa3b, v14
	v_exp_f32_e32 v19, v19
	v_pk_mul_f32 v[4:5], v[92:93], v[4:5]
	v_mul_f32_e32 v22, 0xbfb8aa3b, v15
	v_cvt_f32_i32_e32 v3, v3
	v_cvt_f32_i32_e32 v2, v2
	v_exp_f32_e32 v24, v22
	v_pk_mul_f32 v[22:23], v[4:5], v[18:19] op_sel_hi:[1,0]
	v_add_f32_e32 v4, 1.0, v19
	v_rcp_f32_e32 v19, v4
	v_pk_mul_f32 v[2:3], v[90:91], v[2:3]
	v_add_f32_e32 v4, 1.0, v24
	v_rcp_f32_e32 v24, v4
	v_pk_mul_f32 v[4:5], v[2:3], v[18:19] op_sel_hi:[1,0]
	v_mul_f32_e32 v2, v14, v19
	v_mul_f32_e32 v2, v6, v2
	v_mul_f32_e32 v6, 0xbfb8aa3b, v16
	v_mul_f32_e32 v14, 0xbfb8aa3b, v17
	v_exp_f32_e32 v6, v6
	v_exp_f32_e32 v14, v14
	v_mul_f32_e32 v3, v15, v24
	v_mul_f32_e32 v3, v7, v3
	v_add_f32_e32 v6, 1.0, v6
	v_add_f32_e32 v7, 1.0, v14
	v_rcp_f32_e32 v6, v6
	v_rcp_f32_e32 v7, v7
	v_cvt_pk_bf16_f32 v2, v2, v3
	v_lshl_add_u64 v[20:21], v[20:21], 0, v[142:143]
	v_mul_f32_e32 v3, v16, v6
	v_mul_f32_e32 v6, v17, v7
	v_mul_f32_e32 v7, 0xbfb8aa3b, v10
	v_mul_f32_e32 v3, v8, v3
	v_exp_f32_e32 v7, v7
	v_mul_f32_e32 v8, 0xbfb8aa3b, v11
	v_exp_f32_e32 v8, v8
	v_mul_f32_e32 v6, v9, v6
	v_add_f32_e32 v7, 1.0, v7
	v_rcp_f32_e32 v7, v7
	v_add_f32_e32 v8, 1.0, v8
	v_rcp_f32_e32 v8, v8
	v_cvt_pk_bf16_f32 v3, v3, v6
	v_mul_f32_e32 v6, v10, v7
	v_mul_f32_e32 v7, 0xbfb8aa3b, v12
	v_mul_f32_e32 v4, v4, v6
	v_mul_f32_e32 v6, v11, v8
	v_exp_f32_e32 v7, v7
	v_mul_f32_e32 v8, 0xbfb8aa3b, v13
	v_exp_f32_e32 v8, v8
	v_mul_f32_e32 v5, v5, v6
	v_add_f32_e32 v6, 1.0, v7
	v_rcp_f32_e32 v6, v6
	v_add_f32_e32 v7, 1.0, v8
	v_rcp_f32_e32 v7, v7
	v_cvt_pk_bf16_f32 v4, v4, v5
	v_mul_f32_e32 v5, v12, v6
	v_mul_f32_e32 v5, v22, v5
	v_mul_f32_e32 v6, v13, v7
	s_andn2_b64 vcc, exec, s[4:5]
	s_mov_b64 s[4:5], -1
	v_mul_f32_e32 v6, v23, v6
	v_cvt_pk_bf16_f32 v5, v5, v6
	global_store_dwordx4 v[20:21], v[2:5], off sc1
	s_cbranch_vccnz .LBB0_837
	s_lshl_b32 s4, s33, 11
	s_lshl_b64 s[54:55], s[48:49], 10
	s_and_b32 s35, s4, 0x800
	s_lshl_b64 s[4:5], s[46:47], 10
	v_lshl_add_u64 v[4:5], v[156:157], 0, s[54:55]
	v_lshl_add_u64 v[2:3], v[154:155], 0, s[4:5]
	v_lshl_add_u64 v[4:5], v[4:5], 0, s[0:1]
	v_cndmask_b32_e64 v3, v5, v3, s[2:3]
	v_cndmask_b32_e64 v2, v4, v2, s[2:3]
	s_add_i32 m0, s11, s35
	s_andn2_b64 vcc, exec, s[18:19]
	global_load_lds_dword v[2:3], off
	s_cbranch_vccnz .LBB0_836
	s_barrier
	s_branch .LBB0_836

; #define PG8_LAS __attribute__((address_space(3)))
; __device__ __forceinline__ unsigned cvt_pk_bf16(float lo, float hi) { unsigned r; asm volatile("v_cvt_pk_bf16_f32 %0, %1, %2" : "=v"(r) : "v"(lo), "v"(hi)); return r; }
;     __device__ __forceinline__ void operator()(const i32x4 (&acc)[2][2][4][2], const Unit& u, int wr, int wc, int fr, int fq, const PG8_LAS float* sb) const {
;         const int row0 = u.pm * BM + wr * 64 + fr, col0 = u.pn * BM + wc * 32 + 8 * fq;
;         f32x4 sv[2][2];
; #pragma unroll
;         for (int bj = 0; bj < 2; ++bj)
; #pragma unroll
;             for (int n = 0; n < 2; ++n) sv[bj][n] = *(const PG8_LAS f32x4*)(sb + wc * 32 + 8 * fq + bj * HALF + 4 * n);
; #pragma unroll
;         for (int ai = 0; ai < 2; ++ai)
; #pragma unroll
;             for (int m = 0; m < 4; ++m) { const int row = row0 + ai * HALF + m * 16; const float r = sb[256 + wr * 64 + fr + ai * HALF + m * 16]; bf16_t* rowp = O + (size_t)row * ldc + col0;
; #pragma unroll
;                 for (int bj = 0; bj < 2; ++bj) { const f32x4 v0 = __builtin_convertvector(acc[ai][bj][m][0], f32x4) * sv[bj][0] * r, v1 = __builtin_convertvector(acc[ai][bj][m][1], f32x4) * sv[bj][1] * r;
;                     u32x4 w; w.x = cvt_pk_bf16(v0[0], v0[1]); w.y = cvt_pk_bf16(v0[2], v0[3]); w.z = cvt_pk_bf16(v1[0], v1[1]); w.w = cvt_pk_bf16(v1[2], v1[3]);
;                     *(u32x4*)(rowp + bj * HALF) = w; } }
.LBB0_1040:
	s_lshl_b32 s45, s28, 11
	s_and_b32 s45, s45, 0x800
	s_add_i32 s45, s45, 0
	s_add_i32 s45, s45, 0x20400
	s_lshl_b32 s50, s21, 2
	s_add_i32 s50, s45, s50
	v_lshl_add_u32 v118, v1, 2, s50
	s_lshl_b32 s50, s20, 2
	s_add_i32 s45, s45, s50
	v_lshl_add_u32 v172, v164, 2, s45
	v_lshl_add_u32 v162, s44, 8, v165
	ds_read_b128 v[134:137], v118
	ds_read_b128 v[130:133], v118 offset:16
	ds_read_b128 v[126:129], v118 offset:512
	ds_read_b128 v[118:121], v118 offset:528
	ds_read_b32 v176, v172 offset:1024
	v_cvt_f32_i32_e32 v185, v143
	v_cvt_f32_i32_e32 v187, v145
	v_cvt_f32_i32_e32 v186, v144
	v_cvt_f32_i32_e32 v184, v142
	v_cvt_f32_i32_e32 v139, v139
	v_cvt_f32_i32_e32 v141, v141
	v_cvt_f32_i32_e32 v140, v140
	v_cvt_f32_i32_e32 v138, v138
	v_lshl_or_b32 v174, s42, 8, v166
	v_ashrrev_i32_e32 v163, 31, v162
	v_cvt_f32_i32_e32 v115, v115
	v_cvt_f32_i32_e32 v117, v117
	v_cvt_f32_i32_e32 v116, v116
	v_cvt_f32_i32_e32 v114, v114
	v_ashrrev_i32_e32 v175, 31, v174
	v_lshlrev_b64 v[182:183], 13, v[162:163]
	v_cvt_f32_i32_e32 v123, v123
	v_cvt_f32_i32_e32 v125, v125
	v_cvt_f32_i32_e32 v124, v124
	v_cvt_f32_i32_e32 v122, v122
	v_lshl_add_u64 v[182:183], s[38:39], 0, v[182:183]
	v_lshlrev_b64 v[144:145], 1, v[174:175]
	v_lshl_add_u64 v[142:143], v[182:183], 0, v[144:145]
	s_waitcnt lgkmcnt(0)
	v_pk_mul_f32 v[174:175], v[136:137], v[186:187]
	v_pk_mul_f32 v[182:183], v[134:135], v[184:185]
	v_pk_mul_f32 v[140:141], v[132:133], v[140:141]
	v_pk_mul_f32 v[138:139], v[130:131], v[138:139]
	v_pk_mul_f32 v[174:175], v[174:175], v[176:177] op_sel_hi:[1,0]
	v_pk_mul_f32 v[182:183], v[182:183], v[176:177] op_sel_hi:[1,0]
	v_pk_mul_f32 v[184:185], v[140:141], v[176:177] op_sel_hi:[1,0]
	v_pk_mul_f32 v[140:141], v[138:139], v[176:177] op_sel_hi:[1,0]
	v_cvt_pk_bf16_f32 v138, v182, v183
	v_cvt_pk_bf16_f32 v139, v174, v175
	v_pk_mul_f32 v[116:117], v[120:121], v[116:117]
	v_pk_mul_f32 v[114:115], v[118:119], v[114:115]
	v_cvt_pk_bf16_f32 v140, v140, v141
	v_cvt_pk_bf16_f32 v141, v184, v185
	global_store_dwordx4 v[142:143], v[138:141], off sc1
	v_pk_mul_f32 v[124:125], v[128:129], v[124:125]
	v_pk_mul_f32 v[122:123], v[126:127], v[122:123]
	v_pk_mul_f32 v[138:139], v[116:117], v[176:177] op_sel_hi:[1,0]
	v_pk_mul_f32 v[116:117], v[114:115], v[176:177] op_sel_hi:[1,0]
	v_pk_mul_f32 v[124:125], v[124:125], v[176:177] op_sel_hi:[1,0]
	v_pk_mul_f32 v[122:123], v[122:123], v[176:177] op_sel_hi:[1,0]
	v_cvt_f32_i32_e32 v111, v111
	v_cvt_pk_bf16_f32 v114, v122, v123
	v_cvt_pk_bf16_f32 v115, v124, v125
	v_cvt_pk_bf16_f32 v116, v116, v117
	v_cvt_pk_bf16_f32 v117, v138, v139
	global_store_dwordx4 v[142:143], v[114:117], off offset:256 sc1
	ds_read_b32 v116, v172 offset:1088
	v_cvt_f32_i32_e32 v113, v113
	v_cvt_f32_i32_e32 v112, v112
	v_cvt_f32_i32_e32 v110, v110
	v_cvt_f32_i32_e32 v107, v107
	v_cvt_f32_i32_e32 v109, v109
	v_cvt_f32_i32_e32 v108, v108
	v_cvt_f32_i32_e32 v106, v106
	v_or_b32_e32 v114, 16, v162
	v_cvt_f32_i32_e32 v99, v99
	v_cvt_f32_i32_e32 v101, v101
	v_cvt_f32_i32_e32 v100, v100
	v_cvt_f32_i32_e32 v98, v98
	v_ashrrev_i32_e32 v115, 31, v114
	v_cvt_f32_i32_e32 v103, v103
	v_cvt_f32_i32_e32 v105, v105
	v_cvt_f32_i32_e32 v104, v104
	v_cvt_f32_i32_e32 v102, v102
	v_lshlrev_b64 v[114:115], 13, v[114:115]
	v_lshl_add_u64 v[114:115], s[38:39], 0, v[114:115]
	v_pk_mul_f32 v[112:113], v[136:137], v[112:113]
	v_pk_mul_f32 v[110:111], v[134:135], v[110:111]
	v_pk_mul_f32 v[108:109], v[132:133], v[108:109]
	v_pk_mul_f32 v[106:107], v[130:131], v[106:107]
	v_lshl_add_u64 v[114:115], v[114:115], 0, v[144:145]
	s_waitcnt lgkmcnt(0)
	v_pk_mul_f32 v[112:113], v[112:113], v[116:117] op_sel_hi:[1,0]
	v_pk_mul_f32 v[110:111], v[110:111], v[116:117] op_sel_hi:[1,0]
	v_pk_mul_f32 v[122:123], v[108:109], v[116:117] op_sel_hi:[1,0]
	v_pk_mul_f32 v[108:109], v[106:107], v[116:117] op_sel_hi:[1,0]
	v_cvt_pk_bf16_f32 v106, v110, v111
	v_cvt_pk_bf16_f32 v107, v112, v113
	v_pk_mul_f32 v[100:101], v[120:121], v[100:101]
	v_pk_mul_f32 v[98:99], v[118:119], v[98:99]
	v_cvt_pk_bf16_f32 v108, v108, v109
	v_cvt_pk_bf16_f32 v109, v122, v123
	global_store_dwordx4 v[114:115], v[106:109], off sc1
	v_pk_mul_f32 v[104:105], v[128:129], v[104:105]
	v_pk_mul_f32 v[102:103], v[126:127], v[102:103]
	v_pk_mul_f32 v[106:107], v[100:101], v[116:117] op_sel_hi:[1,0]
	v_pk_mul_f32 v[100:101], v[98:99], v[116:117] op_sel_hi:[1,0]
	v_pk_mul_f32 v[104:105], v[104:105], v[116:117] op_sel_hi:[1,0]
	v_pk_mul_f32 v[102:103], v[102:103], v[116:117] op_sel_hi:[1,0]
	v_cvt_f32_i32_e32 v95, v95
	v_cvt_pk_bf16_f32 v98, v102, v103
	v_cvt_pk_bf16_f32 v99, v104, v105
	v_cvt_pk_bf16_f32 v100, v100, v101
	v_cvt_pk_bf16_f32 v101, v106, v107
	global_store_dwordx4 v[114:115], v[98:101], off offset:256 sc1
	ds_read_b32 v100, v172 offset:1152
	v_cvt_f32_i32_e32 v97, v97
	v_cvt_f32_i32_e32 v96, v96
	v_cvt_f32_i32_e32 v94, v94
	v_cvt_f32_i32_e32 v91, v91
	v_cvt_f32_i32_e32 v93, v93
	v_cvt_f32_i32_e32 v92, v92
	v_cvt_f32_i32_e32 v90, v90
	v_or_b32_e32 v98, 32, v162
	v_cvt_f32_i32_e32 v83, v83
	v_cvt_f32_i32_e32 v85, v85
	v_cvt_f32_i32_e32 v84, v84
	v_cvt_f32_i32_e32 v82, v82
	v_ashrrev_i32_e32 v99, 31, v98
	v_cvt_f32_i32_e32 v87, v87
	v_cvt_f32_i32_e32 v89, v89
	v_cvt_f32_i32_e32 v88, v88
	v_cvt_f32_i32_e32 v86, v86
	v_lshlrev_b64 v[98:99], 13, v[98:99]
	v_lshl_add_u64 v[98:99], s[38:39], 0, v[98:99]
	v_pk_mul_f32 v[96:97], v[136:137], v[96:97]
	v_pk_mul_f32 v[94:95], v[134:135], v[94:95]
	v_pk_mul_f32 v[92:93], v[132:133], v[92:93]
	v_pk_mul_f32 v[90:91], v[130:131], v[90:91]
	v_lshl_add_u64 v[98:99], v[98:99], 0, v[144:145]
	s_waitcnt lgkmcnt(0)
; __device__ __forceinline__ unsigned cvt_pk_bf16(float lo, float hi) { unsigned r; asm volatile("v_cvt_pk_bf16_f32 %0, %1, %2" : "=v"(r) : "v"(lo), "v"(hi)); return r; }
;     __device__ __forceinline__ void operator()(const i32x4 (&acc)[2][2][4][2], const Unit& u, int wr, int wc, int fr, int fq, const PG8_LAS float* sb) const {
;     ...
;             for (int m = 0; m < 4; ++m) { const int row = row0 + ai * HALF + m * 16; const float r = sb[256 + wr * 64 + fr + ai * HALF + m * 16]; bf16_t* rowp = O + (size_t)row * ldc + col0;
; #pragma unroll
;                 for (int bj = 0; bj < 2; ++bj) { const f32x4 v0 = __builtin_convertvector(acc[ai][bj][m][0], f32x4) * sv[bj][0] * r, v1 = __builtin_convertvector(acc[ai][bj][m][1], f32x4) * sv[bj][1] * r;
;                     u32x4 w; w.x = cvt_pk_bf16(v0[0], v0[1]); w.y = cvt_pk_bf16(v0[2], v0[3]); w.z = cvt_pk_bf16(v1[0], v1[1]); w.w = cvt_pk_bf16(v1[2], v1[3]);
;                     *(u32x4*)(rowp + bj * HALF) = w; } }
	v_pk_mul_f32 v[96:97], v[96:97], v[100:101] op_sel_hi:[1,0]
	v_pk_mul_f32 v[94:95], v[94:95], v[100:101] op_sel_hi:[1,0]
	v_pk_mul_f32 v[102:103], v[92:93], v[100:101] op_sel_hi:[1,0]
	v_pk_mul_f32 v[92:93], v[90:91], v[100:101] op_sel_hi:[1,0]
	v_cvt_pk_bf16_f32 v90, v94, v95
	v_cvt_pk_bf16_f32 v91, v96, v97
	v_pk_mul_f32 v[84:85], v[120:121], v[84:85]
	v_pk_mul_f32 v[82:83], v[118:119], v[82:83]
	v_cvt_pk_bf16_f32 v92, v92, v93
	v_cvt_pk_bf16_f32 v93, v102, v103
	global_store_dwordx4 v[98:99], v[90:93], off sc1
	v_pk_mul_f32 v[88:89], v[128:129], v[88:89]
	v_pk_mul_f32 v[86:87], v[126:127], v[86:87]
	v_pk_mul_f32 v[90:91], v[84:85], v[100:101] op_sel_hi:[1,0]
	v_pk_mul_f32 v[84:85], v[82:83], v[100:101] op_sel_hi:[1,0]
	v_pk_mul_f32 v[88:89], v[88:89], v[100:101] op_sel_hi:[1,0]
	v_pk_mul_f32 v[86:87], v[86:87], v[100:101] op_sel_hi:[1,0]
	v_cvt_f32_i32_e32 v79, v79
	v_cvt_pk_bf16_f32 v82, v86, v87
	v_cvt_pk_bf16_f32 v83, v88, v89
	v_cvt_pk_bf16_f32 v84, v84, v85
	v_cvt_pk_bf16_f32 v85, v90, v91
	global_store_dwordx4 v[98:99], v[82:85], off offset:256 sc1
	ds_read_b32 v84, v172 offset:1216
	v_cvt_f32_i32_e32 v81, v81
	v_cvt_f32_i32_e32 v80, v80
	v_cvt_f32_i32_e32 v78, v78
	v_cvt_f32_i32_e32 v75, v75
	v_cvt_f32_i32_e32 v77, v77
	v_cvt_f32_i32_e32 v76, v76
	v_cvt_f32_i32_e32 v74, v74
	v_or_b32_e32 v82, 48, v162
	v_cvt_f32_i32_e32 v71, v71
	v_cvt_f32_i32_e32 v70, v70
	v_cvt_f32_i32_e32 v67, v67
	v_cvt_f32_i32_e32 v69, v69
	v_cvt_f32_i32_e32 v68, v68
	v_cvt_f32_i32_e32 v66, v66
	v_ashrrev_i32_e32 v83, 31, v82
	v_cvt_f32_i32_e32 v73, v73
	v_cvt_f32_i32_e32 v72, v72
	v_lshlrev_b64 v[82:83], 13, v[82:83]
	v_lshl_add_u64 v[82:83], s[38:39], 0, v[82:83]
	v_pk_mul_f32 v[80:81], v[136:137], v[80:81]
	v_pk_mul_f32 v[78:79], v[134:135], v[78:79]
	v_pk_mul_f32 v[76:77], v[132:133], v[76:77]
	v_pk_mul_f32 v[74:75], v[130:131], v[74:75]
	v_lshl_add_u64 v[82:83], v[82:83], 0, v[144:145]
	s_waitcnt lgkmcnt(0)
	v_pk_mul_f32 v[80:81], v[80:81], v[84:85] op_sel_hi:[1,0]
	v_pk_mul_f32 v[78:79], v[78:79], v[84:85] op_sel_hi:[1,0]
	v_pk_mul_f32 v[86:87], v[76:77], v[84:85] op_sel_hi:[1,0]
	v_pk_mul_f32 v[76:77], v[74:75], v[84:85] op_sel_hi:[1,0]
	v_cvt_pk_bf16_f32 v74, v78, v79
	v_cvt_pk_bf16_f32 v75, v80, v81
	v_pk_mul_f32 v[70:71], v[126:127], v[70:71]
	v_pk_mul_f32 v[68:69], v[120:121], v[68:69]
	v_pk_mul_f32 v[66:67], v[118:119], v[66:67]
	v_cvt_pk_bf16_f32 v76, v76, v77
	v_cvt_pk_bf16_f32 v77, v86, v87
	global_store_dwordx4 v[82:83], v[74:77], off sc1
	v_pk_mul_f32 v[72:73], v[128:129], v[72:73]
	v_pk_mul_f32 v[70:71], v[70:71], v[84:85] op_sel_hi:[1,0]
	v_pk_mul_f32 v[74:75], v[68:69], v[84:85] op_sel_hi:[1,0]
	v_pk_mul_f32 v[68:69], v[66:67], v[84:85] op_sel_hi:[1,0]
	v_cvt_pk_bf16_f32 v66, v70, v71
	v_pk_mul_f32 v[72:73], v[72:73], v[84:85] op_sel_hi:[1,0]
	v_cvt_f32_i32_e32 v63, v63
	v_cvt_pk_bf16_f32 v67, v72, v73
	v_cvt_pk_bf16_f32 v68, v68, v69
	v_cvt_pk_bf16_f32 v69, v74, v75
	global_store_dwordx4 v[82:83], v[66:69], off offset:256 sc1
	v_cvt_f32_i32_e32 v62, v62
	ds_read_b32 v66, v172 offset:1536
	v_cvt_f32_i32_e32 v59, v59
	v_cvt_f32_i32_e32 v61, v61
	v_cvt_f32_i32_e32 v60, v60
	v_cvt_f32_i32_e32 v58, v58
	v_cvt_f32_i32_e32 v65, v65
	v_cvt_f32_i32_e32 v64, v64
	v_cvt_f32_i32_e32 v55, v55
	v_cvt_f32_i32_e32 v54, v54
	v_cvt_f32_i32_e32 v51, v51
	v_cvt_f32_i32_e32 v53, v53
	v_cvt_f32_i32_e32 v52, v52
	v_cvt_f32_i32_e32 v50, v50
	v_pk_mul_f32 v[62:63], v[134:135], v[62:63]
	v_cvt_f32_i32_e32 v57, v57
	v_cvt_f32_i32_e32 v56, v56
	s_waitcnt lgkmcnt(0)
	v_pk_mul_f32 v[62:63], v[62:63], v[66:67] op_sel_hi:[1,0]
	v_pk_mul_f32 v[60:61], v[132:133], v[60:61]
	v_pk_mul_f32 v[58:59], v[130:131], v[58:59]
	v_pk_mul_f32 v[64:65], v[136:137], v[64:65]
	v_pk_mul_f32 v[70:71], v[60:61], v[66:67] op_sel_hi:[1,0]
	v_pk_mul_f32 v[60:61], v[58:59], v[66:67] op_sel_hi:[1,0]
	v_cvt_pk_bf16_f32 v58, v62, v63
	v_add_co_u32_e32 v62, vcc, s59, v142
	v_pk_mul_f32 v[64:65], v[64:65], v[66:67] op_sel_hi:[1,0]
	s_nop 0
	v_addc_co_u32_e32 v63, vcc, 0, v143, vcc
	v_cvt_pk_bf16_f32 v59, v64, v65
	v_pk_mul_f32 v[54:55], v[126:127], v[54:55]
	v_pk_mul_f32 v[52:53], v[120:121], v[52:53]
	v_pk_mul_f32 v[50:51], v[118:119], v[50:51]
	v_lshl_add_u64 v[68:69], v[142:143], 0, s[12:13]
	v_cvt_pk_bf16_f32 v60, v60, v61
	v_cvt_pk_bf16_f32 v61, v70, v71
	global_store_dwordx4 v[62:63], v[58:61], off sc1
	v_pk_mul_f32 v[56:57], v[128:129], v[56:57]
	v_pk_mul_f32 v[54:55], v[54:55], v[66:67] op_sel_hi:[1,0]
	v_pk_mul_f32 v[58:59], v[52:53], v[66:67] op_sel_hi:[1,0]
	v_pk_mul_f32 v[52:53], v[50:51], v[66:67] op_sel_hi:[1,0]
	v_cvt_pk_bf16_f32 v50, v54, v55
	v_pk_mul_f32 v[56:57], v[56:57], v[66:67] op_sel_hi:[1,0]
	v_cvt_f32_i32_e32 v47, v47
	v_cvt_pk_bf16_f32 v51, v56, v57
	v_cvt_pk_bf16_f32 v52, v52, v53
	v_cvt_pk_bf16_f32 v53, v58, v59
	global_store_dwordx4 v[68:69], v[50:53], off offset:256 sc1
	v_cvt_f32_i32_e32 v46, v46
	ds_read_b32 v50, v172 offset:1600
	v_cvt_f32_i32_e32 v43, v43
	v_cvt_f32_i32_e32 v45, v45
	v_cvt_f32_i32_e32 v44, v44
	v_cvt_f32_i32_e32 v42, v42
	v_cvt_f32_i32_e32 v49, v49
	v_cvt_f32_i32_e32 v48, v48
	v_cvt_f32_i32_e32 v39, v39
	v_cvt_f32_i32_e32 v38, v38
	v_cvt_f32_i32_e32 v35, v35
	v_cvt_f32_i32_e32 v37, v37
	v_cvt_f32_i32_e32 v36, v36
	v_cvt_f32_i32_e32 v34, v34
	v_pk_mul_f32 v[46:47], v[134:135], v[46:47]
	v_cvt_f32_i32_e32 v41, v41
	v_cvt_f32_i32_e32 v40, v40
	s_waitcnt lgkmcnt(0)
; #define PG8_LAS __attribute__((address_space(3)))
; __device__ __forceinline__ unsigned cvt_pk_bf16(float lo, float hi) { unsigned r; asm volatile("v_cvt_pk_bf16_f32 %0, %1, %2" : "=v"(r) : "v"(lo), "v"(hi)); return r; }
;     __device__ __forceinline__ void operator()(const i32x4 (&acc)[2][2][4][2], const Unit& u, int wr, int wc, int fr, int fq, const PG8_LAS float* sb) const {
;     ...
;             for (int m = 0; m < 4; ++m) { const int row = row0 + ai * HALF + m * 16; const float r = sb[256 + wr * 64 + fr + ai * HALF + m * 16]; bf16_t* rowp = O + (size_t)row * ldc + col0;
; #pragma unroll
;                 for (int bj = 0; bj < 2; ++bj) { const f32x4 v0 = __builtin_convertvector(acc[ai][bj][m][0], f32x4) * sv[bj][0] * r, v1 = __builtin_convertvector(acc[ai][bj][m][1], f32x4) * sv[bj][1] * r;
;                     u32x4 w; w.x = cvt_pk_bf16(v0[0], v0[1]); w.y = cvt_pk_bf16(v0[2], v0[3]); w.z = cvt_pk_bf16(v1[0], v1[1]); w.w = cvt_pk_bf16(v1[2], v1[3]);
;                     *(u32x4*)(rowp + bj * HALF) = w; } }
; __device__ __forceinline__ void stage_scales(PG8_LAS unsigned char* sb, const float* cs_tile, const float* rs_tile, int tid, int wid) {
;     const float* src = (tid < 256) ? cs_tile + tid : rs_tile + (tid - 256);
;     __builtin_amdgcn_global_load_lds((const unsigned*)src, (PG8_LAS unsigned*)(sb + wid * 256), 4, 0, 0);
; }
	v_pk_mul_f32 v[46:47], v[46:47], v[50:51] op_sel_hi:[1,0]
	v_pk_mul_f32 v[44:45], v[132:133], v[44:45]
	v_pk_mul_f32 v[42:43], v[130:131], v[42:43]
	v_pk_mul_f32 v[48:49], v[136:137], v[48:49]
	v_pk_mul_f32 v[54:55], v[44:45], v[50:51] op_sel_hi:[1,0]
	v_pk_mul_f32 v[44:45], v[42:43], v[50:51] op_sel_hi:[1,0]
	v_cvt_pk_bf16_f32 v42, v46, v47
	v_add_co_u32_e32 v46, vcc, s60, v142
	v_pk_mul_f32 v[48:49], v[48:49], v[50:51] op_sel_hi:[1,0]
	s_nop 0
	v_addc_co_u32_e32 v47, vcc, 0, v143, vcc
	v_cvt_pk_bf16_f32 v43, v48, v49
	v_pk_mul_f32 v[38:39], v[126:127], v[38:39]
	v_pk_mul_f32 v[36:37], v[120:121], v[36:37]
	v_pk_mul_f32 v[34:35], v[118:119], v[34:35]
	v_lshl_add_u64 v[52:53], v[142:143], 0, s[16:17]
	v_cvt_pk_bf16_f32 v44, v44, v45
	v_cvt_pk_bf16_f32 v45, v54, v55
	global_store_dwordx4 v[46:47], v[42:45], off sc1
	v_pk_mul_f32 v[40:41], v[128:129], v[40:41]
	v_pk_mul_f32 v[38:39], v[38:39], v[50:51] op_sel_hi:[1,0]
	v_pk_mul_f32 v[42:43], v[36:37], v[50:51] op_sel_hi:[1,0]
	v_pk_mul_f32 v[36:37], v[34:35], v[50:51] op_sel_hi:[1,0]
	v_cvt_pk_bf16_f32 v34, v38, v39
	v_pk_mul_f32 v[40:41], v[40:41], v[50:51] op_sel_hi:[1,0]
	v_cvt_f32_i32_e32 v31, v31
	v_cvt_pk_bf16_f32 v35, v40, v41
	v_cvt_pk_bf16_f32 v36, v36, v37
	v_cvt_pk_bf16_f32 v37, v42, v43
	global_store_dwordx4 v[52:53], v[34:37], off offset:256 sc1
	v_cvt_f32_i32_e32 v30, v30
	ds_read_b32 v34, v172 offset:1664
	v_cvt_f32_i32_e32 v27, v27
	v_cvt_f32_i32_e32 v29, v29
	v_cvt_f32_i32_e32 v28, v28
	v_cvt_f32_i32_e32 v26, v26
	v_cvt_f32_i32_e32 v33, v33
	v_cvt_f32_i32_e32 v32, v32
	v_cvt_f32_i32_e32 v23, v23
	v_cvt_f32_i32_e32 v22, v22
	v_cvt_f32_i32_e32 v19, v19
	v_cvt_f32_i32_e32 v21, v21
	v_cvt_f32_i32_e32 v20, v20
	v_cvt_f32_i32_e32 v18, v18
	v_pk_mul_f32 v[30:31], v[134:135], v[30:31]
	v_cvt_f32_i32_e32 v25, v25
	v_cvt_f32_i32_e32 v24, v24
	s_waitcnt lgkmcnt(0)
	v_pk_mul_f32 v[30:31], v[30:31], v[34:35] op_sel_hi:[1,0]
	v_pk_mul_f32 v[28:29], v[132:133], v[28:29]
	v_pk_mul_f32 v[26:27], v[130:131], v[26:27]
	v_pk_mul_f32 v[32:33], v[136:137], v[32:33]
	v_pk_mul_f32 v[38:39], v[28:29], v[34:35] op_sel_hi:[1,0]
	v_pk_mul_f32 v[28:29], v[26:27], v[34:35] op_sel_hi:[1,0]
	v_cvt_pk_bf16_f32 v26, v30, v31
	v_add_co_u32_e32 v30, vcc, s61, v142
	v_pk_mul_f32 v[32:33], v[32:33], v[34:35] op_sel_hi:[1,0]
	s_nop 0
	v_addc_co_u32_e32 v31, vcc, 0, v143, vcc
	v_cvt_pk_bf16_f32 v27, v32, v33
	v_pk_mul_f32 v[22:23], v[126:127], v[22:23]
	v_pk_mul_f32 v[20:21], v[120:121], v[20:21]
	v_pk_mul_f32 v[18:19], v[118:119], v[18:19]
	v_lshl_add_u64 v[36:37], v[142:143], 0, s[36:37]
	v_cvt_pk_bf16_f32 v28, v28, v29
	v_cvt_pk_bf16_f32 v29, v38, v39
	global_store_dwordx4 v[30:31], v[26:29], off sc1
	v_pk_mul_f32 v[24:25], v[128:129], v[24:25]
	v_pk_mul_f32 v[22:23], v[22:23], v[34:35] op_sel_hi:[1,0]
	v_pk_mul_f32 v[26:27], v[20:21], v[34:35] op_sel_hi:[1,0]
	v_pk_mul_f32 v[20:21], v[18:19], v[34:35] op_sel_hi:[1,0]
	v_cvt_pk_bf16_f32 v18, v22, v23
	v_pk_mul_f32 v[24:25], v[24:25], v[34:35] op_sel_hi:[1,0]
	v_cvt_f32_i32_e32 v15, v15
	v_cvt_pk_bf16_f32 v19, v24, v25
	v_cvt_pk_bf16_f32 v20, v20, v21
	v_cvt_pk_bf16_f32 v21, v26, v27
	global_store_dwordx4 v[36:37], v[18:21], off offset:256 sc1
	v_cvt_f32_i32_e32 v14, v14
	ds_read_b32 v18, v172 offset:1728
	v_cvt_f32_i32_e32 v11, v11
	v_cvt_f32_i32_e32 v13, v13
	v_cvt_f32_i32_e32 v12, v12
	v_cvt_f32_i32_e32 v10, v10
	v_cvt_f32_i32_e32 v17, v17
	v_cvt_f32_i32_e32 v16, v16
	v_cvt_f32_i32_e32 v3, v3
	v_cvt_f32_i32_e32 v5, v5
	v_cvt_f32_i32_e32 v4, v4
	v_cvt_f32_i32_e32 v2, v2
	v_pk_mul_f32 v[14:15], v[134:135], v[14:15]
	v_cvt_f32_i32_e32 v7, v7
	v_cvt_f32_i32_e32 v6, v6
	v_cvt_f32_i32_e32 v9, v9
	v_cvt_f32_i32_e32 v8, v8
	s_waitcnt lgkmcnt(0)
	v_pk_mul_f32 v[14:15], v[14:15], v[18:19] op_sel_hi:[1,0]
	v_pk_mul_f32 v[12:13], v[132:133], v[12:13]
	v_pk_mul_f32 v[10:11], v[130:131], v[10:11]
	v_pk_mul_f32 v[16:17], v[136:137], v[16:17]
	v_pk_mul_f32 v[22:23], v[12:13], v[18:19] op_sel_hi:[1,0]
	v_pk_mul_f32 v[12:13], v[10:11], v[18:19] op_sel_hi:[1,0]
	v_cvt_pk_bf16_f32 v10, v14, v15
	v_add_co_u32_e32 v14, vcc, s62, v142
	v_pk_mul_f32 v[16:17], v[16:17], v[18:19] op_sel_hi:[1,0]
	s_nop 0
	v_addc_co_u32_e32 v15, vcc, 0, v143, vcc
	v_cvt_pk_bf16_f32 v11, v16, v17
	v_pk_mul_f32 v[4:5], v[120:121], v[4:5]
	v_pk_mul_f32 v[2:3], v[118:119], v[2:3]
	v_lshl_add_u64 v[20:21], v[142:143], 0, s[40:41]
	v_cvt_pk_bf16_f32 v12, v12, v13
	v_cvt_pk_bf16_f32 v13, v22, v23
	global_store_dwordx4 v[14:15], v[10:13], off sc1
	v_pk_mul_f32 v[8:9], v[128:129], v[8:9]
	v_pk_mul_f32 v[6:7], v[126:127], v[6:7]
	v_pk_mul_f32 v[10:11], v[4:5], v[18:19] op_sel_hi:[1,0]
	v_pk_mul_f32 v[4:5], v[2:3], v[18:19] op_sel_hi:[1,0]
	s_cmp_eq_u32 s28, 3
	s_mov_b64 s[50:51], -1
	v_pk_mul_f32 v[8:9], v[8:9], v[18:19] op_sel_hi:[1,0]
	v_pk_mul_f32 v[6:7], v[6:7], v[18:19] op_sel_hi:[1,0]
	s_nop 0
	v_cvt_pk_bf16_f32 v2, v6, v7
	v_cvt_pk_bf16_f32 v3, v8, v9
	v_cvt_pk_bf16_f32 v4, v4, v5
	v_cvt_pk_bf16_f32 v5, v10, v11
	global_store_dwordx4 v[20:21], v[2:5], off offset:256 sc1
	s_cbranch_scc1 .LBB0_1033
	s_and_b64 s[48:49], s[48:49], exec
	s_cselect_b32 s44, s43, s44
	s_cselect_b32 s42, s4, s42
	s_ashr_i32 s45, s44, 31
	s_ashr_i32 s43, s42, 31
	s_lshl_b64 s[50:51], s[44:45], 10
	s_lshl_b32 s28, s69, 11
	s_lshl_b64 s[48:49], s[42:43], 10
	v_lshl_add_u64 v[4:5], v[156:157], 0, s[50:51]
	s_and_b32 s28, s28, 0x800
	v_lshl_add_u64 v[2:3], v[154:155], 0, s[48:49]
	v_lshl_add_u64 v[4:5], v[4:5], 0, s[14:15]
	v_cndmask_b32_e64 v3, v5, v3, s[2:3]
	v_cndmask_b32_e64 v2, v4, v2, s[2:3]
	s_add_i32 m0, s1, s28
	s_andn2_b64 vcc, exec, s[18:19]
	global_load_lds_dword v[2:3], off
	s_cbranch_vccnz .LBB0_1032
	s_barrier
	s_branch .LBB0_1032
